# all gemm K-loops on the 5-chunk LDS-DMA ring with pieces between MFMAs; hand-written prompt delta chain (LDS-DMA 3-slot ring, counted waits); phase-1 epilogue r1 preloaded
# speedup vs baseline: 1.1159x; 1.0095x over previous
.LBB0_114:
	s_waitcnt vmcnt(5)
	v_add_u32_e32 v54, s4, v110
	v_ashrrev_i32_e32 v55, 31, v54
	v_lshl_add_u64 v[38:39], v[54:55], 2, s[0:1]
	v_or_b32_e32 v40, s2, v114
	v_mov_b64_e32 v[56:57], s[74:75]
	v_ashrrev_i32_e32 v41, 31, v40
	v_mad_i64_i32 v[42:43], s[2:3], v54, s17, v[56:57]
	s_waitcnt vmcnt(5)
	v_lshlrev_b64 v[64:65], 1, v[40:41]
	v_or_b32_e32 v62, 16, v54
	s_waitcnt vmcnt(4)
	v_lshl_add_u64 v[66:67], v[42:43], 0, v[64:65]
	v_ashrrev_i32_e32 v63, 31, v62
	v_lshl_add_u64 v[68:69], v[62:63], 2, s[0:1]
	s_add_i32 s18, s18, s48
	s_cmp_lt_i32 s18, s12
	v_pk_mul_f32 v[40:41], v[94:95], v[142:143] op_sel_hi:[1,0]
	v_pk_mul_f32 v[42:43], v[96:97], v[142:143] op_sel_hi:[1,0]
	v_pk_mul_f32 v[44:45], v[90:91], v[142:143] op_sel_hi:[1,0]
	v_pk_mul_f32 v[70:71], v[92:93], v[142:143] op_sel_hi:[1,0]
	v_pk_mul_f32 v[72:73], v[86:87], v[142:143] op_sel_hi:[1,0]
	v_pk_mul_f32 v[74:75], v[88:89], v[142:143] op_sel_hi:[1,0]
	v_pk_mul_f32 v[76:77], v[82:83], v[142:143] op_sel_hi:[1,0]
	v_pk_mul_f32 v[78:79], v[84:85], v[142:143] op_sel_hi:[1,0]
	v_cvt_pk_bf16_f32 v38, v40, v41
	v_cvt_pk_bf16_f32 v39, v42, v43
	v_cvt_pk_bf16_f32 v40, v44, v45
	v_cvt_pk_bf16_f32 v41, v70, v71
	v_cvt_pk_bf16_f32 v42, v72, v73
	v_cvt_pk_bf16_f32 v43, v74, v75
	v_cvt_pk_bf16_f32 v44, v76, v77
	v_cvt_pk_bf16_f32 v45, v78, v79
	global_store_dwordx4 v[66:67], v[38:41], off
	global_store_dwordx4 v[66:67], v[42:45], off offset:64
	s_nop 1
	v_mad_i64_i32 v[40:41], s[2:3], v62, s17, v[56:57]
	v_or_b32_e32 v42, 32, v54
	v_lshl_add_u64 v[44:45], v[40:41], 0, v[64:65]
	v_ashrrev_i32_e32 v43, 31, v42
	v_lshl_add_u64 v[62:63], v[42:43], 2, s[0:1]
	v_pk_mul_f32 v[40:41], v[58:59], v[144:145] op_sel_hi:[1,0]
	v_pk_mul_f32 v[58:59], v[60:61], v[144:145] op_sel_hi:[1,0]
	v_pk_mul_f32 v[50:51], v[50:51], v[144:145] op_sel_hi:[1,0]
	v_pk_mul_f32 v[52:53], v[52:53], v[144:145] op_sel_hi:[1,0]
	v_pk_mul_f32 v[46:47], v[46:47], v[144:145] op_sel_hi:[1,0]
	v_pk_mul_f32 v[48:49], v[48:49], v[144:145] op_sel_hi:[1,0]
	v_pk_mul_f32 v[60:61], v[34:35], v[144:145] op_sel_hi:[1,0]
	v_pk_mul_f32 v[66:67], v[36:37], v[144:145] op_sel_hi:[1,0]
	v_cvt_pk_bf16_f32 v34, v40, v41
	v_cvt_pk_bf16_f32 v35, v58, v59
	v_cvt_pk_bf16_f32 v36, v50, v51
	v_cvt_pk_bf16_f32 v37, v52, v53
	v_cvt_pk_bf16_f32 v38, v46, v47
	v_cvt_pk_bf16_f32 v39, v48, v49
	v_cvt_pk_bf16_f32 v40, v60, v61
	v_cvt_pk_bf16_f32 v41, v66, v67
	global_store_dwordx4 v[44:45], v[34:37], off
	global_store_dwordx4 v[44:45], v[38:41], off offset:64
	s_nop 1
	v_or_b32_e32 v36, 48, v54
	v_mad_i64_i32 v[38:39], s[2:3], v42, s17, v[56:57]
	v_ashrrev_i32_e32 v37, 31, v36
	v_lshl_add_u64 v[38:39], v[38:39], 0, v[64:65]
	v_lshl_add_u64 v[40:41], v[36:37], 2, s[0:1]
	v_pk_mul_f32 v[30:31], v[30:31], v[146:147] op_sel_hi:[1,0]
	v_pk_mul_f32 v[32:33], v[32:33], v[146:147] op_sel_hi:[1,0]
	v_pk_mul_f32 v[26:27], v[26:27], v[146:147] op_sel_hi:[1,0]
	v_pk_mul_f32 v[28:29], v[28:29], v[146:147] op_sel_hi:[1,0]
	v_pk_mul_f32 v[22:23], v[22:23], v[146:147] op_sel_hi:[1,0]
	v_pk_mul_f32 v[24:25], v[24:25], v[146:147] op_sel_hi:[1,0]
	v_pk_mul_f32 v[42:43], v[18:19], v[146:147] op_sel_hi:[1,0]
	v_pk_mul_f32 v[34:35], v[20:21], v[146:147] op_sel_hi:[1,0]
	v_cvt_pk_bf16_f32 v18, v30, v31
	v_cvt_pk_bf16_f32 v19, v32, v33
	v_cvt_pk_bf16_f32 v20, v26, v27
	v_cvt_pk_bf16_f32 v21, v28, v29
	v_cvt_pk_bf16_f32 v22, v22, v23
	v_cvt_pk_bf16_f32 v23, v24, v25
	v_cvt_pk_bf16_f32 v24, v42, v43
	v_cvt_pk_bf16_f32 v25, v34, v35
	global_store_dwordx4 v[38:39], v[18:21], off
	global_store_dwordx4 v[38:39], v[22:25], off offset:64
	s_nop 1
	v_mad_i64_i32 v[20:21], s[2:3], v36, s17, v[56:57]
	v_lshl_add_u64 v[20:21], v[20:21], 0, v[64:65]
	v_pk_mul_f32 v[14:15], v[14:15], v[148:149] op_sel_hi:[1,0]
	v_pk_mul_f32 v[16:17], v[16:17], v[148:149] op_sel_hi:[1,0]
	v_pk_mul_f32 v[10:11], v[10:11], v[148:149] op_sel_hi:[1,0]
	v_pk_mul_f32 v[12:13], v[12:13], v[148:149] op_sel_hi:[1,0]
	v_pk_mul_f32 v[6:7], v[6:7], v[148:149] op_sel_hi:[1,0]
	v_pk_mul_f32 v[8:9], v[8:9], v[148:149] op_sel_hi:[1,0]
	v_pk_mul_f32 v[22:23], v[2:3], v[148:149] op_sel_hi:[1,0]
	v_pk_mul_f32 v[18:19], v[4:5], v[148:149] op_sel_hi:[1,0]
	v_cvt_pk_bf16_f32 v2, v14, v15
	v_cvt_pk_bf16_f32 v3, v16, v17
	v_cvt_pk_bf16_f32 v4, v10, v11
	v_cvt_pk_bf16_f32 v5, v12, v13
	v_cvt_pk_bf16_f32 v6, v6, v7
	v_cvt_pk_bf16_f32 v7, v8, v9
	v_cvt_pk_bf16_f32 v8, v22, v23
	v_cvt_pk_bf16_f32 v9, v18, v19
	global_store_dwordx4 v[20:21], v[2:5], off
	global_store_dwordx4 v[20:21], v[6:9], off offset:64
	s_nop 1
	s_cbranch_scc0 .LBB0_130

.LBB0_122:
	s_lshl_b32 s4, s4, 7
	v_add_u32_e32 v150, s4, v110
	v_ashrrev_i32_e32 v151, 31, v150
	v_lshl_add_u64 v[150:151], v[150:151], 2, s[0:1]
	global_load_dword v142, v[150:151], off
	global_load_dword v144, v[150:151], off offset:64
	global_load_dword v146, v[150:151], off offset:128
	global_load_dword v148, v[150:151], off offset:192
	s_lshl_b32 s2, s5, 7
	s_lshl_b32 s24, s4, 11
	s_add_u32 s26, s54, s24
	s_addc_u32 s27, s55, 0
	s_lshl_b32 s24, s2, 11
	s_add_u32 s28, s54, s24
	s_addc_u32 s29, s55, 0
	s_add_u32 s28, s28, 0xe680000
	s_addc_u32 s29, s29, 0
	s_barrier
	s_mov_b32 m0, s30
	s_nop 0
	global_load_lds_dwordx4 v104, s[26:27]
	s_add_u32 m0, s30, 0x1000
	s_nop 0
	global_load_lds_dwordx4 v105, s[26:27]
	s_add_u32 m0, s30, 0x2000
	s_nop 0
	global_load_lds_dwordx4 v106, s[26:27]
	s_add_u32 m0, s30, 0x3000
	s_nop 0
	global_load_lds_dwordx4 v107, s[26:27]
	s_add_u32 s31, s30, 0x4000
	s_mov_b32 m0, s31
	s_nop 0
	global_load_lds_dwordx4 v104, s[28:29]
	s_add_u32 m0, s31, 0x1000
	s_nop 0
	global_load_lds_dwordx4 v105, s[28:29]
	s_add_u32 m0, s31, 0x2000
	s_nop 0
	global_load_lds_dwordx4 v106, s[28:29]
	s_add_u32 m0, s31, 0x3000
	s_nop 0
	global_load_lds_dwordx4 v107, s[28:29]
	s_add_u32 s26, s26, 0x80
	s_addc_u32 s27, s27, 0
	s_add_u32 s31, s30, 0x8000
	s_mov_b32 m0, s31
	s_nop 0
	global_load_lds_dwordx4 v104, s[26:27]
	s_add_u32 m0, s31, 0x1000
	s_nop 0
	global_load_lds_dwordx4 v105, s[26:27]
	s_add_u32 m0, s31, 0x2000
	s_nop 0
	global_load_lds_dwordx4 v106, s[26:27]
	s_add_u32 m0, s31, 0x3000
	s_nop 0
	global_load_lds_dwordx4 v107, s[26:27]
	v_mov_b32_e32 v2, 0
	v_mov_b32_e32 v3, v2
	v_mov_b32_e32 v4, v2
	v_mov_b32_e32 v5, v2
	v_mov_b32_e32 v6, v2
	v_mov_b32_e32 v7, v2
	v_mov_b32_e32 v8, v2
	v_mov_b32_e32 v9, v2
	v_mov_b32_e32 v10, v2
	v_mov_b32_e32 v11, v2
	v_mov_b32_e32 v12, v2
	v_mov_b32_e32 v13, v2
	v_mov_b32_e32 v14, v2
	v_mov_b32_e32 v15, v2
	v_mov_b32_e32 v16, v2
	v_mov_b32_e32 v17, v2
	v_mov_b32_e32 v18, v2
	v_mov_b32_e32 v19, v2
	v_mov_b32_e32 v20, v2
	v_mov_b32_e32 v21, v2
	v_mov_b32_e32 v22, v2
	v_mov_b32_e32 v23, v2
	v_mov_b32_e32 v24, v2
	v_mov_b32_e32 v25, v2
	v_mov_b32_e32 v26, v2
	v_mov_b32_e32 v27, v2
	v_mov_b32_e32 v28, v2
	v_mov_b32_e32 v29, v2
	v_mov_b32_e32 v30, v2
	v_mov_b32_e32 v31, v2
	v_mov_b32_e32 v32, v2
	v_mov_b32_e32 v33, v2
	v_mov_b32_e32 v34, v2
	v_mov_b32_e32 v35, v2
	v_mov_b32_e32 v36, v2
	v_mov_b32_e32 v37, v2
	v_mov_b32_e32 v46, v2
	v_mov_b32_e32 v47, v2
	v_mov_b32_e32 v48, v2
	v_mov_b32_e32 v49, v2
	v_mov_b32_e32 v50, v2
	v_mov_b32_e32 v51, v2
	v_mov_b32_e32 v52, v2
	v_mov_b32_e32 v53, v2
	v_mov_b32_e32 v58, v2
	v_mov_b32_e32 v59, v2
	v_mov_b32_e32 v60, v2
	v_mov_b32_e32 v61, v2
	v_mov_b32_e32 v82, v2
	v_mov_b32_e32 v83, v2
	v_mov_b32_e32 v84, v2
	v_mov_b32_e32 v85, v2
	v_mov_b32_e32 v86, v2
	v_mov_b32_e32 v87, v2
	v_mov_b32_e32 v88, v2
	v_mov_b32_e32 v89, v2
	v_mov_b32_e32 v90, v2
	v_mov_b32_e32 v91, v2
	v_mov_b32_e32 v92, v2
	v_mov_b32_e32 v93, v2
	v_mov_b32_e32 v94, v2
	v_mov_b32_e32 v95, v2
	v_mov_b32_e32 v96, v2
	v_mov_b32_e32 v97, v2
	s_mov_b32 s3, 0
	s_mov_b32 s10, 0
	s_mov_b32 s11, 0x4000
	s_waitcnt vmcnt(4)
	s_barrier

.LBB0_586:
	v_readlane_b32 s0, v235, 4
	v_readlane_b32 s1, v235, 5
	v_readlane_b32 s54, v237, 63
	v_readlane_b32 s56, v236, 1
	v_readlane_b32 s46, v237, 54
	v_readlane_b32 s64, v236, 7
	s_and_b64 vcc, exec, s[0:1]
	v_readlane_b32 s55, v236, 0
	v_readlane_b32 s57, v236, 2
	v_readlane_b32 s58, v235, 3
	v_readlane_b32 s59, v236, 6
	s_mul_i32 s62, s46, 17
	v_readlane_b32 s65, v236, 8
	s_cbranch_vccz .LBB0_674
	s_ashr_i32 s0, s96, 1
	s_and_b32 s1, s96, 1
	v_readlane_b32 s30, v237, 49
	v_readlane_b32 s31, v237, 50
	s_lshr_b32 s2, s98, 10
	s_barrier
	s_mul_i32 s4, s0, 0x1a0000
	s_add_u32 s4, s54, s4
	s_addc_u32 s5, s55, 0
	s_add_u32 s4, s4, 0x9900000
	s_addc_u32 s5, s5, 0
	s_mul_i32 s3, s2, 7
	s_min_u32 s3, s3, 19
	s_lshl_b32 s3, s3, 10
	s_add_u32 s4, s4, s3
	s_addc_u32 s5, s5, 0
	s_lshl_b32 s6, s0, 20
	s_add_u32 s6, s30, s6
	s_addc_u32 s7, s31, 0
	s_lshl_b32 s8, s1, 2
	s_add_u32 s8, s8, s2
	s_lshl_b32 s9, s8, 12
	s_add_u32 s6, s6, s9
	s_addc_u32 s7, s7, 0
	s_lshr_b32 s10, s0, 2
	s_lshl_b32 s10, s10, 21
	s_add_u32 s10, s54, s10
	s_addc_u32 s11, s55, 0
	s_and_b32 s12, s0, 3
	s_lshl_b32 s12, s12, 8
	s_lshl_b32 s13, s8, 5
	s_add_u32 s12, s12, s13
	v_and_b32_e32 v220, 63, v0
	v_lshlrev_b32_e32 v204, 4, v220
	v_lshrrev_b32_e32 v221, 4, v220
	v_and_b32_e32 v222, 15, v220
	v_lshlrev_b32_e32 v223, 12, v221
	v_lshl_add_u32 v223, v222, 1, v223
	v_add_u32_e32 v223, s12, v223
	v_add_u32_e32 v206, 0x0, v223
	v_add_u32_e32 v207, 0x400, v223
	v_add_u32_e32 v208, 0x800, v223
	v_add_u32_e32 v209, 0xc00, v223
	v_add_u32_e32 v210, 0x4000, v223
	v_add_u32_e32 v211, 0x4400, v223
	v_add_u32_e32 v212, 0x4800, v223
	v_add_u32_e32 v213, 0x4c00, v223
	s_lshl_b32 s13, s8, 6
	v_lshlrev_b32_e32 v218, 11, v221
	v_lshl_add_u32 v218, v222, 2, v218
	v_add_u32_e32 v218, s13, v218
	s_lshl_b32 s14, s0, 8
	s_add_u32 s14, s54, s14
	s_addc_u32 s15, s55, 0
	s_add_u32 s14, s14, 0xf33b000
	s_addc_u32 s15, s15, 0
	v_lshlrev_b32_e32 v220, 2, v220
	global_load_dword v221, v220, s[14:15]
	s_add_u32 s14, s4, 0x1000
	s_addc_u32 s15, s5, 0
	s_add_u32 s16, s3, 0x0
	s_mov_b32 m0, s16
	s_nop 0
	global_load_lds_dwordx4 v204, s[4:5]
	global_load_lds_dwordx4 v204, s[4:5] offset:1024
	global_load_lds_dwordx4 v204, s[4:5] offset:2048
	global_load_lds_dwordx4 v204, s[4:5] offset:3072
	s_add_u32 m0, s16, 0x1000
	s_nop 0
	global_load_lds_dwordx4 v204, s[14:15]
	global_load_lds_dwordx4 v204, s[14:15] offset:1024
	global_load_lds_dwordx4 v204, s[14:15] offset:2048
	global_load_dwordx4 v[188:191], v204, s[6:7]
	global_load_dwordx4 v[192:195], v204, s[6:7] offset:1024
	s_add_u32 s4, s4, 0x6800
	s_addc_u32 s5, s5, 0
	s_add_u32 s14, s4, 0x1000
	s_addc_u32 s15, s5, 0
	s_add_u32 s16, s3, 0x6800
	s_mov_b32 m0, s16
	s_nop 0
	global_load_lds_dwordx4 v204, s[4:5]
	global_load_lds_dwordx4 v204, s[4:5] offset:1024
	global_load_lds_dwordx4 v204, s[4:5] offset:2048
	global_load_lds_dwordx4 v204, s[4:5] offset:3072
	s_add_u32 m0, s16, 0x1000
	s_nop 0
	global_load_lds_dwordx4 v204, s[14:15]
	global_load_lds_dwordx4 v204, s[14:15] offset:1024
	global_load_lds_dwordx4 v204, s[14:15] offset:2048
	global_load_dwordx4 v[196:199], v204, s[6:7] offset:2048
	global_load_dwordx4 v[200:203], v204, s[6:7] offset:3072
	v_mov_b32_e32 v4, 0
	v_mov_b32_e32 v5, v4
	v_mov_b32_e32 v6, v4
	v_mov_b32_e32 v7, v4
	v_mov_b32_e32 v8, v4
	v_mov_b32_e32 v9, v4
	v_mov_b32_e32 v10, v4
	v_mov_b32_e32 v11, v4
	v_mov_b32_e32 v12, v4
	v_mov_b32_e32 v13, v4
	v_mov_b32_e32 v14, v4
	v_mov_b32_e32 v15, v4
	v_mov_b32_e32 v16, v4
	v_mov_b32_e32 v17, v4
	v_mov_b32_e32 v18, v4
	v_mov_b32_e32 v19, v4
	v_mov_b32_e32 v20, v4
	v_mov_b32_e32 v21, v4
	v_mov_b32_e32 v22, v4
	v_mov_b32_e32 v23, v4
	v_mov_b32_e32 v24, v4
	v_mov_b32_e32 v25, v4
	v_mov_b32_e32 v26, v4
	v_mov_b32_e32 v27, v4
	v_mov_b32_e32 v28, v4
	v_mov_b32_e32 v29, v4
	v_mov_b32_e32 v30, v4
	v_mov_b32_e32 v31, v4
	v_mov_b32_e32 v32, v4
	v_mov_b32_e32 v33, v4
	v_mov_b32_e32 v34, v4
	v_mov_b32_e32 v35, v4
	s_waitcnt vmcnt(18)
	v_add_u32_e32 v220, 0x13800, v220
	s_cmp_lg_u32 s2, 0
	s_cbranch_scc1 .Lch_nogl
	ds_write_b32 v220, v221
	s_waitcnt lgkmcnt(0)
.Lch_nogl:
	s_mov_b32 s20, 0
	s_mov_b32 s21, 0
	s_mov_b32 s22, 0x13800
.Lch_loop:
	s_cmp_lt_u32 s20, 2
	s_cbranch_scc1 .Lch_w_early_a
	s_cmp_eq_u32 s20, 63
	s_cbranch_scc1 .Lch_w_last_a
	s_waitcnt vmcnt(25)
	s_branch .Lch_w_done_a
.Lch_w_last_a:
	s_waitcnt vmcnt(16)
	s_branch .Lch_w_done_a
.Lch_w_early_a:
	s_waitcnt vmcnt(9)
.Lch_w_done_a:
	s_barrier
	s_cmp_gt_u32 s20, 61
	s_cbranch_scc1 .Lch_nodma_a
	s_add_u32 s4, s4, 0x6800
	s_addc_u32 s5, s5, 0
	s_add_u32 s14, s4, 0x1000
	s_addc_u32 s15, s5, 0
	s_add_u32 s16, s21, 0xd000
	s_sub_u32 s17, s16, 0x13800
	s_cmp_ge_u32 s16, 0x13800
	s_cselect_b32 s16, s17, s16
	s_add_u32 s16, s16, s3
	s_mov_b32 m0, s16
	s_nop 0
	global_load_lds_dwordx4 v204, s[4:5]
	global_load_lds_dwordx4 v204, s[4:5] offset:1024
	global_load_lds_dwordx4 v204, s[4:5] offset:2048
	global_load_lds_dwordx4 v204, s[4:5] offset:3072
	s_add_u32 m0, s16, 0x1000
	s_nop 0
	global_load_lds_dwordx4 v204, s[14:15]
	global_load_lds_dwordx4 v204, s[14:15] offset:1024
	global_load_lds_dwordx4 v204, s[14:15] offset:2048
.Lch_nodma_a:
	v_add_u32_e32 v205, s21, v204
	v_mov_b32_e32 v214, s22
	ds_read_b32 v216, v214
	ds_read_b128 v[72:75], v205
	ds_read_b128 v[76:79], v205 offset:4096
	ds_read_b128 v[80:83], v205 offset:8192
	ds_read_b128 v[84:87], v205 offset:12288
	ds_read_b128 v[88:91], v205 offset:1024
	ds_read_b128 v[92:95], v205 offset:5120
	ds_read_b128 v[96:99], v205 offset:9216
	ds_read_b128 v[100:103], v205 offset:13312
	ds_read_b128 v[104:107], v205 offset:2048
	ds_read_b128 v[108:111], v205 offset:6144
	ds_read_b128 v[112:115], v205 offset:10240
	ds_read_b128 v[116:119], v205 offset:14336
	v_cvt_pk_bf16_f32 v36, v4, v5
	v_cvt_pk_bf16_f32 v37, v6, v7
	v_cvt_pk_bf16_f32 v38, v8, v9
	v_cvt_pk_bf16_f32 v39, v10, v11
	v_cvt_pk_bf16_f32 v40, v12, v13
	v_cvt_pk_bf16_f32 v41, v14, v15
	v_cvt_pk_bf16_f32 v42, v16, v17
	v_cvt_pk_bf16_f32 v43, v18, v19
	v_cvt_pk_bf16_f32 v44, v20, v21
	v_cvt_pk_bf16_f32 v45, v22, v23
	v_cvt_pk_bf16_f32 v46, v24, v25
	v_cvt_pk_bf16_f32 v47, v26, v27
	v_cvt_pk_bf16_f32 v48, v28, v29
	v_cvt_pk_bf16_f32 v49, v30, v31
	v_cvt_pk_bf16_f32 v50, v32, v33
	v_cvt_pk_bf16_f32 v51, v34, v35
	s_waitcnt lgkmcnt(11)
	v_mfma_f32_16x16x32_bf16 v[52:55], v[72:75], v[36:39], v[188:191]
	ds_read_b128 v[120:123], v205 offset:3072
	s_waitcnt lgkmcnt(11)
	v_mfma_f32_16x16x32_bf16 v[56:59], v[76:79], v[36:39], v[192:195]
	ds_read_b128 v[124:127], v205 offset:7168
	s_waitcnt lgkmcnt(11)
	v_mfma_f32_16x16x32_bf16 v[60:63], v[80:83], v[36:39], 0
	ds_read_b128 v[128:131], v205 offset:11264
	s_waitcnt lgkmcnt(11)
	v_mfma_f32_16x16x32_bf16 v[64:67], v[84:87], v[36:39], 0
	ds_read_b128 v[132:135], v205 offset:15360
	s_cmp_gt_u32 s20, 61
	s_cbranch_scc1 .Lch_nou_a
	s_add_u32 s16, s20, 2
	s_lshr_b32 s16, s16, 1
	s_lshl_b32 s16, s16, 15
	s_add_u32 s14, s6, s16
	s_addc_u32 s15, s7, 0
	global_load_dwordx4 v[188:191], v204, s[14:15]
	global_load_dwordx4 v[192:195], v204, s[14:15] offset:1024
.Lch_nou_a:
	s_waitcnt lgkmcnt(11)
	v_mfma_f32_16x16x32_bf16 v[52:55], v[88:91], v[40:43], v[52:55]
	ds_read_b128 v[136:139], v205 offset:16384
	s_waitcnt lgkmcnt(11)
	v_mfma_f32_16x16x32_bf16 v[56:59], v[92:95], v[40:43], v[56:59]
	ds_read_b128 v[140:143], v205 offset:17408
	s_waitcnt lgkmcnt(11)
	v_mfma_f32_16x16x32_bf16 v[60:63], v[96:99], v[40:43], v[60:63]
	ds_read_b128 v[144:147], v205 offset:18432
	s_waitcnt lgkmcnt(11)
	v_mfma_f32_16x16x32_bf16 v[64:67], v[100:103], v[40:43], v[64:67]
	ds_read_b128 v[148:151], v205 offset:19456
	s_waitcnt lgkmcnt(11)
	v_mfma_f32_16x16x32_bf16 v[52:55], v[104:107], v[44:47], v[52:55]
	ds_read_b128 v[152:155], v205 offset:20480
	s_waitcnt lgkmcnt(11)
	v_mfma_f32_16x16x32_bf16 v[56:59], v[108:111], v[44:47], v[56:59]
	ds_read_b128 v[156:159], v205 offset:21504
	s_waitcnt lgkmcnt(11)
	v_mfma_f32_16x16x32_bf16 v[60:63], v[112:115], v[44:47], v[60:63]
	ds_read_b128 v[160:163], v205 offset:22528
	s_waitcnt lgkmcnt(11)
	v_mfma_f32_16x16x32_bf16 v[64:67], v[116:119], v[44:47], v[64:67]
	ds_read_b128 v[164:167], v205 offset:23552
	s_waitcnt lgkmcnt(11)
	v_mfma_f32_16x16x32_bf16 v[52:55], v[120:123], v[48:51], v[52:55]
	ds_read_b128 v[180:183], v205 offset:24576
	s_waitcnt lgkmcnt(11)
	v_mfma_f32_16x16x32_bf16 v[56:59], v[124:127], v[48:51], v[56:59]
	ds_read_b128 v[184:187], v205 offset:25600
	s_waitcnt lgkmcnt(11)
	v_mfma_f32_16x16x32_bf16 v[60:63], v[128:131], v[48:51], v[60:63]
	s_waitcnt lgkmcnt(10)
	v_mfma_f32_16x16x32_bf16 v[64:67], v[132:135], v[48:51], v[64:67]
	v_pk_mul_f32 v[4:5], v[4:5], v[216:217] op_sel_hi:[1,0]
	v_pk_mul_f32 v[6:7], v[6:7], v[216:217] op_sel_hi:[1,0]
	v_pk_mul_f32 v[8:9], v[8:9], v[216:217] op_sel_hi:[1,0]
	v_pk_mul_f32 v[10:11], v[10:11], v[216:217] op_sel_hi:[1,0]
	v_pk_mul_f32 v[12:13], v[12:13], v[216:217] op_sel_hi:[1,0]
	v_pk_mul_f32 v[14:15], v[14:15], v[216:217] op_sel_hi:[1,0]
	v_pk_mul_f32 v[16:17], v[16:17], v[216:217] op_sel_hi:[1,0]
	v_pk_mul_f32 v[18:19], v[18:19], v[216:217] op_sel_hi:[1,0]
	v_pk_mul_f32 v[20:21], v[20:21], v[216:217] op_sel_hi:[1,0]
	v_pk_mul_f32 v[22:23], v[22:23], v[216:217] op_sel_hi:[1,0]
	v_pk_mul_f32 v[24:25], v[24:25], v[216:217] op_sel_hi:[1,0]
	v_pk_mul_f32 v[26:27], v[26:27], v[216:217] op_sel_hi:[1,0]
	v_pk_mul_f32 v[28:29], v[28:29], v[216:217] op_sel_hi:[1,0]
	v_pk_mul_f32 v[30:31], v[30:31], v[216:217] op_sel_hi:[1,0]
	v_pk_mul_f32 v[32:33], v[32:33], v[216:217] op_sel_hi:[1,0]
	v_pk_mul_f32 v[34:35], v[34:35], v[216:217] op_sel_hi:[1,0]
	v_cvt_pk_bf16_f32 v68, v52, v53
	v_cvt_pk_bf16_f32 v69, v54, v55
	v_cvt_pk_bf16_f32 v70, v56, v57
	v_cvt_pk_bf16_f32 v71, v58, v59
	s_nop 1
	s_waitcnt lgkmcnt(9)
	v_mfma_f32_16x16x32_bf16 v[60:63], v[136:139], v[68:71], v[60:63]
	s_waitcnt lgkmcnt(8)
	v_mfma_f32_16x16x32_bf16 v[64:67], v[140:143], v[68:71], v[64:67]
	s_waitcnt lgkmcnt(7)
	v_mfma_f32_16x16x32_bf16 v[4:7], v[144:147], v[68:71], v[4:7]
	s_waitcnt lgkmcnt(6)
	v_mfma_f32_16x16x32_bf16 v[8:11], v[148:151], v[68:71], v[8:11]
	s_waitcnt lgkmcnt(5)
	v_mfma_f32_16x16x32_bf16 v[12:15], v[152:155], v[68:71], v[12:15]
	s_waitcnt lgkmcnt(4)
	v_mfma_f32_16x16x32_bf16 v[16:19], v[156:159], v[68:71], v[16:19]
	s_waitcnt lgkmcnt(3)
	v_mfma_f32_16x16x32_bf16 v[20:23], v[160:163], v[68:71], v[20:23]
	s_waitcnt lgkmcnt(2)
	v_mfma_f32_16x16x32_bf16 v[24:27], v[164:167], v[68:71], v[24:27]
	s_waitcnt lgkmcnt(1)
	v_mfma_f32_16x16x32_bf16 v[28:31], v[180:183], v[68:71], v[28:31]
	s_waitcnt lgkmcnt(0)
	v_mfma_f32_16x16x32_bf16 v[32:35], v[184:187], v[68:71], v[32:35]
	v_cvt_pk_bf16_f32 v220, v60, v60
	global_store_short v206, v220, s[10:11]
	v_cvt_pk_bf16_f32 v221, v61, v61
	global_store_short v207, v221, s[10:11]
	v_cvt_pk_bf16_f32 v222, v62, v62
	global_store_short v208, v222, s[10:11]
	v_cvt_pk_bf16_f32 v223, v63, v63
	global_store_short v209, v223, s[10:11]
	v_cvt_pk_bf16_f32 v224, v64, v64
	global_store_short v210, v224, s[10:11]
	v_cvt_pk_bf16_f32 v225, v65, v65
	global_store_short v211, v225, s[10:11]
	v_cvt_pk_bf16_f32 v226, v66, v66
	global_store_short v212, v226, s[10:11]
	v_cvt_pk_bf16_f32 v227, v67, v67
	global_store_short v213, v227, s[10:11]
	s_add_u32 s10, s10, 0x8000
	s_addc_u32 s11, s11, 0
	s_add_u32 s21, s21, 0x6800
	s_sub_u32 s17, s21, 0x13800
	s_cmp_ge_u32 s21, 0x13800
	s_cselect_b32 s21, s17, s21
	s_add_u32 s22, s22, 4
	s_add_u32 s20, s20, 1
	s_cmp_lt_u32 s20, 2
	s_cbranch_scc1 .Lch_w_early_b
	s_cmp_eq_u32 s20, 63
	s_cbranch_scc1 .Lch_w_last_b
	s_waitcnt vmcnt(25)
	s_branch .Lch_w_done_b

.Lch_w_early_b:
	s_waitcnt vmcnt(17)

.Lch_nodma_b:
	v_add_u32_e32 v205, s21, v204
	v_mov_b32_e32 v214, s22
	ds_read_b32 v216, v214
	ds_read_b128 v[72:75], v205
	ds_read_b128 v[76:79], v205 offset:4096
	ds_read_b128 v[80:83], v205 offset:8192
	ds_read_b128 v[84:87], v205 offset:12288
	ds_read_b128 v[88:91], v205 offset:1024
	ds_read_b128 v[92:95], v205 offset:5120
	ds_read_b128 v[96:99], v205 offset:9216
	ds_read_b128 v[100:103], v205 offset:13312
	ds_read_b128 v[104:107], v205 offset:2048
	ds_read_b128 v[108:111], v205 offset:6144
	ds_read_b128 v[112:115], v205 offset:10240
	ds_read_b128 v[116:119], v205 offset:14336
	v_cvt_pk_bf16_f32 v36, v4, v5
	v_cvt_pk_bf16_f32 v37, v6, v7
	v_cvt_pk_bf16_f32 v38, v8, v9
	v_cvt_pk_bf16_f32 v39, v10, v11
	v_cvt_pk_bf16_f32 v40, v12, v13
	v_cvt_pk_bf16_f32 v41, v14, v15
	v_cvt_pk_bf16_f32 v42, v16, v17
	v_cvt_pk_bf16_f32 v43, v18, v19
	v_cvt_pk_bf16_f32 v44, v20, v21
	v_cvt_pk_bf16_f32 v45, v22, v23
	v_cvt_pk_bf16_f32 v46, v24, v25
	v_cvt_pk_bf16_f32 v47, v26, v27
	v_cvt_pk_bf16_f32 v48, v28, v29
	v_cvt_pk_bf16_f32 v49, v30, v31
	v_cvt_pk_bf16_f32 v50, v32, v33
	v_cvt_pk_bf16_f32 v51, v34, v35
	s_waitcnt lgkmcnt(11)
	v_mfma_f32_16x16x32_bf16 v[52:55], v[72:75], v[36:39], v[196:199]
	ds_read_b128 v[120:123], v205 offset:3072
	s_waitcnt lgkmcnt(11)
	v_mfma_f32_16x16x32_bf16 v[56:59], v[76:79], v[36:39], v[200:203]
	ds_read_b128 v[124:127], v205 offset:7168
	s_waitcnt lgkmcnt(11)
	v_mfma_f32_16x16x32_bf16 v[60:63], v[80:83], v[36:39], 0
	ds_read_b128 v[128:131], v205 offset:11264
	s_waitcnt lgkmcnt(11)
	v_mfma_f32_16x16x32_bf16 v[64:67], v[84:87], v[36:39], 0
	ds_read_b128 v[132:135], v205 offset:15360
	s_cmp_gt_u32 s20, 61
	s_cbranch_scc1 .Lch_nou_b
	s_add_u32 s16, s20, 2
	s_lshr_b32 s16, s16, 1
	s_lshl_b32 s16, s16, 15
	s_add_u32 s16, s16, 0x800
	s_add_u32 s14, s6, s16
	s_addc_u32 s15, s7, 0
	global_load_dwordx4 v[196:199], v204, s[14:15]
	global_load_dwordx4 v[200:203], v204, s[14:15] offset:1024
.Lch_nou_b:
	s_waitcnt lgkmcnt(11)
	v_mfma_f32_16x16x32_bf16 v[52:55], v[88:91], v[40:43], v[52:55]
	ds_read_b128 v[136:139], v205 offset:16384
	s_waitcnt lgkmcnt(11)
	v_mfma_f32_16x16x32_bf16 v[56:59], v[92:95], v[40:43], v[56:59]
	ds_read_b128 v[140:143], v205 offset:17408
	s_waitcnt lgkmcnt(11)
	v_mfma_f32_16x16x32_bf16 v[60:63], v[96:99], v[40:43], v[60:63]
	ds_read_b128 v[144:147], v205 offset:18432
	s_waitcnt lgkmcnt(11)
	v_mfma_f32_16x16x32_bf16 v[64:67], v[100:103], v[40:43], v[64:67]
	ds_read_b128 v[148:151], v205 offset:19456
	s_waitcnt lgkmcnt(11)
	v_mfma_f32_16x16x32_bf16 v[52:55], v[104:107], v[44:47], v[52:55]
	ds_read_b128 v[152:155], v205 offset:20480
	s_waitcnt lgkmcnt(11)
	v_mfma_f32_16x16x32_bf16 v[56:59], v[108:111], v[44:47], v[56:59]
	ds_read_b128 v[156:159], v205 offset:21504
	s_waitcnt lgkmcnt(11)
	v_mfma_f32_16x16x32_bf16 v[60:63], v[112:115], v[44:47], v[60:63]
	ds_read_b128 v[160:163], v205 offset:22528
	s_waitcnt lgkmcnt(11)
	v_mfma_f32_16x16x32_bf16 v[64:67], v[116:119], v[44:47], v[64:67]
	ds_read_b128 v[164:167], v205 offset:23552
	s_waitcnt lgkmcnt(11)
	v_mfma_f32_16x16x32_bf16 v[52:55], v[120:123], v[48:51], v[52:55]
	ds_read_b128 v[180:183], v205 offset:24576
	s_waitcnt lgkmcnt(11)
	v_mfma_f32_16x16x32_bf16 v[56:59], v[124:127], v[48:51], v[56:59]
	ds_read_b128 v[184:187], v205 offset:25600
	s_waitcnt lgkmcnt(11)
	v_mfma_f32_16x16x32_bf16 v[60:63], v[128:131], v[48:51], v[60:63]
	s_waitcnt lgkmcnt(10)
	v_mfma_f32_16x16x32_bf16 v[64:67], v[132:135], v[48:51], v[64:67]
	v_pk_mul_f32 v[4:5], v[4:5], v[216:217] op_sel_hi:[1,0]
	v_pk_mul_f32 v[6:7], v[6:7], v[216:217] op_sel_hi:[1,0]
	v_pk_mul_f32 v[8:9], v[8:9], v[216:217] op_sel_hi:[1,0]
	v_pk_mul_f32 v[10:11], v[10:11], v[216:217] op_sel_hi:[1,0]
	v_pk_mul_f32 v[12:13], v[12:13], v[216:217] op_sel_hi:[1,0]
	v_pk_mul_f32 v[14:15], v[14:15], v[216:217] op_sel_hi:[1,0]
	v_pk_mul_f32 v[16:17], v[16:17], v[216:217] op_sel_hi:[1,0]
	v_pk_mul_f32 v[18:19], v[18:19], v[216:217] op_sel_hi:[1,0]
	v_pk_mul_f32 v[20:21], v[20:21], v[216:217] op_sel_hi:[1,0]
	v_pk_mul_f32 v[22:23], v[22:23], v[216:217] op_sel_hi:[1,0]
	v_pk_mul_f32 v[24:25], v[24:25], v[216:217] op_sel_hi:[1,0]
	v_pk_mul_f32 v[26:27], v[26:27], v[216:217] op_sel_hi:[1,0]
	v_pk_mul_f32 v[28:29], v[28:29], v[216:217] op_sel_hi:[1,0]
	v_pk_mul_f32 v[30:31], v[30:31], v[216:217] op_sel_hi:[1,0]
	v_pk_mul_f32 v[32:33], v[32:33], v[216:217] op_sel_hi:[1,0]
	v_pk_mul_f32 v[34:35], v[34:35], v[216:217] op_sel_hi:[1,0]
	v_cvt_pk_bf16_f32 v68, v52, v53
	v_cvt_pk_bf16_f32 v69, v54, v55
	v_cvt_pk_bf16_f32 v70, v56, v57
	v_cvt_pk_bf16_f32 v71, v58, v59
	s_nop 1
	s_waitcnt lgkmcnt(9)
	v_mfma_f32_16x16x32_bf16 v[60:63], v[136:139], v[68:71], v[60:63]
	s_waitcnt lgkmcnt(8)
	v_mfma_f32_16x16x32_bf16 v[64:67], v[140:143], v[68:71], v[64:67]
	s_waitcnt lgkmcnt(7)
	v_mfma_f32_16x16x32_bf16 v[4:7], v[144:147], v[68:71], v[4:7]
	s_waitcnt lgkmcnt(6)
	v_mfma_f32_16x16x32_bf16 v[8:11], v[148:151], v[68:71], v[8:11]
	s_waitcnt lgkmcnt(5)
	v_mfma_f32_16x16x32_bf16 v[12:15], v[152:155], v[68:71], v[12:15]
	s_waitcnt lgkmcnt(4)
	v_mfma_f32_16x16x32_bf16 v[16:19], v[156:159], v[68:71], v[16:19]
	s_waitcnt lgkmcnt(3)
	v_mfma_f32_16x16x32_bf16 v[20:23], v[160:163], v[68:71], v[20:23]
	s_waitcnt lgkmcnt(2)
	v_mfma_f32_16x16x32_bf16 v[24:27], v[164:167], v[68:71], v[24:27]
	s_waitcnt lgkmcnt(1)
	v_mfma_f32_16x16x32_bf16 v[28:31], v[180:183], v[68:71], v[28:31]
	s_waitcnt lgkmcnt(0)
	v_mfma_f32_16x16x32_bf16 v[32:35], v[184:187], v[68:71], v[32:35]
	v_cvt_pk_bf16_f32 v220, v60, v60
	global_store_short v206, v220, s[10:11]
	v_cvt_pk_bf16_f32 v221, v61, v61
	global_store_short v207, v221, s[10:11]
	v_cvt_pk_bf16_f32 v222, v62, v62
	global_store_short v208, v222, s[10:11]
	v_cvt_pk_bf16_f32 v223, v63, v63
	global_store_short v209, v223, s[10:11]
	v_cvt_pk_bf16_f32 v224, v64, v64
	global_store_short v210, v224, s[10:11]
	v_cvt_pk_bf16_f32 v225, v65, v65
	global_store_short v211, v225, s[10:11]
	v_cvt_pk_bf16_f32 v226, v66, v66
	global_store_short v212, v226, s[10:11]
	v_cvt_pk_bf16_f32 v227, v67, v67
	global_store_short v213, v227, s[10:11]
	s_add_u32 s10, s10, 0x8000
	s_addc_u32 s11, s11, 0
	s_add_u32 s21, s21, 0x6800
	s_sub_u32 s17, s21, 0x13800
	s_cmp_ge_u32 s21, 0x13800
	s_cselect_b32 s21, s17, s21
	s_add_u32 s22, s22, 4
	s_add_u32 s20, s20, 1
	s_cmp_lt_u32 s20, 64
	s_cbranch_scc1 .Lch_loop
	s_lshl_b32 s14, s0, 16
	s_add_u32 s14, s30, s14
	s_addc_u32 s15, s31, 0
	s_add_u32 s14, s14, 0x449c000
	s_addc_u32 s15, s15, 0
	global_store_dword v218, v4, s[14:15]
	global_store_dword v218, v5, s[14:15] offset:512
	global_store_dword v218, v6, s[14:15] offset:1024
	global_store_dword v218, v7, s[14:15] offset:1536
	s_add_u32 s14, s14, 0x2000
	s_addc_u32 s15, s15, 0
	global_store_dword v218, v8, s[14:15]
	global_store_dword v218, v9, s[14:15] offset:512
	global_store_dword v218, v10, s[14:15] offset:1024
	global_store_dword v218, v11, s[14:15] offset:1536
	s_add_u32 s14, s14, 0x2000
	s_addc_u32 s15, s15, 0
	global_store_dword v218, v12, s[14:15]
	global_store_dword v218, v13, s[14:15] offset:512
	global_store_dword v218, v14, s[14:15] offset:1024
	global_store_dword v218, v15, s[14:15] offset:1536
	s_add_u32 s14, s14, 0x2000
	s_addc_u32 s15, s15, 0
	global_store_dword v218, v16, s[14:15]
	global_store_dword v218, v17, s[14:15] offset:512
	global_store_dword v218, v18, s[14:15] offset:1024
	global_store_dword v218, v19, s[14:15] offset:1536
	s_add_u32 s14, s14, 0x2000
	s_addc_u32 s15, s15, 0
	global_store_dword v218, v20, s[14:15]
	global_store_dword v218, v21, s[14:15] offset:512
	global_store_dword v218, v22, s[14:15] offset:1024
	global_store_dword v218, v23, s[14:15] offset:1536
	s_add_u32 s14, s14, 0x2000
	s_addc_u32 s15, s15, 0
	global_store_dword v218, v24, s[14:15]
	global_store_dword v218, v25, s[14:15] offset:512
	global_store_dword v218, v26, s[14:15] offset:1024
	global_store_dword v218, v27, s[14:15] offset:1536
	s_add_u32 s14, s14, 0x2000
	s_addc_u32 s15, s15, 0
	global_store_dword v218, v28, s[14:15]
	global_store_dword v218, v29, s[14:15] offset:512
	global_store_dword v218, v30, s[14:15] offset:1024
	global_store_dword v218, v31, s[14:15] offset:1536
	s_add_u32 s14, s14, 0x2000
	s_addc_u32 s15, s15, 0
	global_store_dword v218, v32, s[14:15]
	global_store_dword v218, v33, s[14:15] offset:512
	global_store_dword v218, v34, s[14:15] offset:1024
	global_store_dword v218, v35, s[14:15] offset:1536
	v_readlane_b32 s5, v237, 36
	v_readlane_b32 s6, v237, 37
	v_readlane_b32 s7, v237, 38
	v_readlane_b32 s8, v237, 39
	v_readlane_b32 s9, v237, 40
	v_readlane_b32 s10, v237, 41
	v_readlane_b32 s11, v237, 42
	s_barrier

.LBB0_733:
	s_lshl_b32 s2, s23, 10
	s_and_b32 s2, s2, 0x60000
	v_lshl_add_u64 v[108:109], v[106:107], 0, s[2:3]
	s_lshl_b32 s2, s29, 5
	s_and_b32 s8, s2, 0xffffff80
	s_ashr_i32 s9, s8, 31
	s_lshl_b64 s[10:11], s[8:9], 10
	v_lshl_add_u64 v[2:3], v[100:101], 0, s[10:11]
	v_add_co_u32_e32 v6, vcc, s25, v2
	s_lshl_b32 s2, s29, 7
	s_nop 0
	v_addc_co_u32_e32 v7, vcc, 0, v3, vcc
	v_add_co_u32_e32 v8, vcc, s26, v2
	s_and_b32 s30, s2, 0x180
	s_nop 0
	v_addc_co_u32_e32 v9, vcc, 0, v3, vcc
	s_lshl_b32 s2, s30, 10
	s_barrier
	s_mov_b32 m0, s98
	v_lshl_add_u64 v[66:67], v[2:3], 0, v[238:239]
	global_load_lds_dwordx4 v[66:67], off
	v_add_co_u32_e32 v2, vcc, s27, v2
	v_lshl_add_u64 v[4:5], v[102:103], 0, s[2:3]
	s_nop 0
	v_addc_co_u32_e32 v3, vcc, 0, v3, vcc
	s_add_u32 m0, s98, 0x1000
	v_lshl_add_u64 v[70:71], v[6:7], 0, v[238:239]
	global_load_lds_dwordx4 v[70:71], off
	s_add_u32 m0, s98, 0x2000
	v_lshl_add_u64 v[74:75], v[8:9], 0, v[238:239]
	global_load_lds_dwordx4 v[74:75], off
	s_add_u32 m0, s98, 0x3000
	v_lshl_add_u64 v[78:79], v[2:3], 0, v[238:239]
	global_load_lds_dwordx4 v[78:79], off
	s_add_u32 m0, s98, 0x4000
	v_lshl_add_u64 v[82:83], v[4:5], 0, v[238:239]
	global_load_lds_dwordx4 v[82:83], off
	v_add_co_u32_e32 v2, vcc, s25, v4
	s_and_b32 s12, s21, 0xffffff80
	s_nop 0
	v_addc_co_u32_e32 v3, vcc, 0, v5, vcc
	v_add_co_u32_e32 v6, vcc, s26, v4
	s_ashr_i32 s13, s12, 31
	s_nop 0
	v_addc_co_u32_e32 v7, vcc, 0, v5, vcc
	s_add_u32 m0, s98, 0x5000
	v_lshl_add_u64 v[86:87], v[2:3], 0, v[238:239]
	global_load_lds_dwordx4 v[86:87], off
	s_add_u32 m0, s98, 0x6000
	v_lshl_add_u64 v[90:91], v[6:7], 0, v[238:239]
	global_load_lds_dwordx4 v[90:91], off
	v_add_co_u32_e32 v2, vcc, s27, v4
	s_lshl_b64 s[12:13], s[12:13], 10
	s_nop 0
	v_addc_co_u32_e32 v3, vcc, 0, v5, vcc
	s_add_u32 m0, s98, 0x7000
	v_lshl_add_u64 v[94:95], v[2:3], 0, v[238:239]
	global_load_lds_dwordx4 v[94:95], off
	s_mov_b32 s9, 0
	s_mov_b64 s[10:11], 0
	s_mov_b32 s2, 0
	v_mov_b32_e32 v62, 0
	v_mov_b32_e32 v63, v99
	v_mov_b32_e32 v64, v99
	v_mov_b32_e32 v65, v99
	v_mov_b32_e32 v58, 0
	v_mov_b32_e32 v59, v99
	v_mov_b32_e32 v60, v99
	v_mov_b32_e32 v61, v99
	v_mov_b32_e32 v54, 0
	v_mov_b32_e32 v55, v99
	v_mov_b32_e32 v56, v99
	v_mov_b32_e32 v57, v99
	v_mov_b32_e32 v50, 0
	v_mov_b32_e32 v51, v99
	v_mov_b32_e32 v52, v99
	v_mov_b32_e32 v53, v99
	v_mov_b32_e32 v46, 0
	v_mov_b32_e32 v47, v99
	v_mov_b32_e32 v48, v99
	v_mov_b32_e32 v49, v99
	v_mov_b32_e32 v42, 0
	v_lshl_add_u64 v[110:111], v[104:105], 0, s[12:13]
	v_mov_b32_e32 v43, v99
	v_mov_b32_e32 v44, v99
	v_mov_b32_e32 v45, v99
	v_mov_b32_e32 v38, 0
	v_mov_b32_e32 v39, v99
	v_mov_b32_e32 v40, v99
	v_mov_b32_e32 v41, v99
	v_mov_b32_e32 v34, 0
	v_mov_b32_e32 v35, v99
	v_mov_b32_e32 v36, v99
	v_mov_b32_e32 v37, v99
	v_mov_b32_e32 v30, 0
	v_mov_b32_e32 v31, v99
	v_mov_b32_e32 v32, v99
	v_mov_b32_e32 v33, v99
	v_mov_b32_e32 v26, 0
	v_mov_b32_e32 v27, v99
	v_mov_b32_e32 v28, v99
	v_mov_b32_e32 v29, v99
	v_mov_b32_e32 v22, 0
	v_mov_b32_e32 v23, v99
	v_mov_b32_e32 v24, v99
	v_mov_b32_e32 v25, v99
	v_mov_b32_e32 v18, 0
	v_mov_b32_e32 v19, v99
	v_mov_b32_e32 v20, v99
	v_mov_b32_e32 v21, v99
	v_mov_b32_e32 v14, 0
	v_mov_b32_e32 v15, v99
	v_mov_b32_e32 v16, v99
	v_mov_b32_e32 v17, v99
	v_mov_b32_e32 v10, 0
	v_mov_b32_e32 v11, v99
	v_mov_b32_e32 v12, v99
	v_mov_b32_e32 v13, v99
	v_mov_b32_e32 v6, 0
	v_mov_b32_e32 v7, v99
	v_mov_b32_e32 v8, v99
	v_mov_b32_e32 v9, v99
	v_mov_b32_e32 v2, 0
	v_mov_b32_e32 v3, v99
	v_mov_b32_e32 v4, v99
	v_mov_b32_e32 v5, v99
	s_waitcnt lgkmcnt(0)
	s_add_u32 m0, s98, 0x8000
	v_lshl_add_u64 v[66:67], v[66:67], 0, v[242:243]
	global_load_lds_dwordx4 v[66:67], off
	s_add_u32 m0, s98, 0x9000
	v_lshl_add_u64 v[70:71], v[70:71], 0, v[242:243]
	global_load_lds_dwordx4 v[70:71], off
	s_add_u32 m0, s98, 0xa000
	v_lshl_add_u64 v[74:75], v[74:75], 0, v[242:243]
	global_load_lds_dwordx4 v[74:75], off
	s_add_u32 m0, s98, 0xb000
	v_lshl_add_u64 v[78:79], v[78:79], 0, v[242:243]
	global_load_lds_dwordx4 v[78:79], off
	s_mov_b32 s100, 0
	s_mov_b32 s101, 0x4000
	s_waitcnt vmcnt(4)
	s_barrier
	s_branch .LBB0_735
.LBB0_734:
	s_add_u32 s10, s10, 0x80
	s_addc_u32 s11, s11, 0
	s_add_i32 s2, s2, 1
	s_add_u32 s100, s100, 0x8000
	s_cmp_lt_u32 s100, 0x14000
	s_cbranch_scc1 .Ldqr_0
	s_sub_u32 s100, s100, 0x14000
.Ldqr_0:
	s_mov_b32 s101, 0x4000
	s_cmp_lg_u32 s100, 0x10000
	s_cbranch_scc1 .Ldqs_0
	s_mov_b32 s101, 0xffff0000
.Ldqs_0:
	s_cmp_gt_u32 s2, 6
	s_cbranch_scc1 .Ldqv_0
	s_waitcnt vmcnt(4)
	s_branch .Ldqx_0

.Ldqx_0:
	s_cmpk_lg_i32 s10, 0x400
	s_mov_b32 s9, s12
	s_waitcnt lgkmcnt(0)
	s_barrier
	s_cbranch_scc0 .LBB0_732

.LBB0_737:
	v_add_u32_e32 v98, s100, v113
	v_add3_u32 v119, v98, v116, s101
	ds_read_b128 v[120:123], v119
	v_add_u32_e32 v98, v98, v115
	ds_read_b128 v[124:127], v119 offset:2048
	ds_read_b128 v[128:131], v98
	ds_read_b128 v[132:135], v98 offset:2048
	ds_read_b128 v[136:139], v119 offset:4096
	ds_read_b128 v[140:143], v119 offset:6144
	s_waitcnt lgkmcnt(3)
	v_mfma_f32_16x16x32_bf16 v[58:61], v[124:127], v[128:131], v[58:61]
	s_andn2_b64 vcc, exec, s[12:13]
	v_mfma_f32_16x16x32_bf16 v[62:65], v[120:123], v[128:131], v[62:65]
	s_waitcnt lgkmcnt(1)
	v_mfma_f32_16x16x32_bf16 v[54:57], v[136:139], v[128:131], v[54:57]
	s_cbranch_vccz .Ldq_0_0
	s_add_u32 s99, s100, 0xc000
	s_cmp_lt_u32 s99, 0x14000
	s_cbranch_scc1 .Ldqw_0_0
	s_sub_u32 s99, s99, 0x14000
.Ldqw_0_0:
	s_add_u32 s99, s99, s98
	s_mov_b32 m0, s99
	v_lshl_add_u64 v[82:83], v[82:83], 0, v[242:243]
	global_load_lds_dwordx4 v[82:83], off
.Ldq_0_0:
	s_waitcnt lgkmcnt(0)
	v_mfma_f32_16x16x32_bf16 v[50:53], v[140:143], v[128:131], v[50:53]
	v_mfma_f32_16x16x32_bf16 v[46:49], v[120:123], v[132:135], v[46:49]
	s_cbranch_vccz .Ldq_0_1
	s_add_u32 m0, s99, 0x1000
	v_lshl_add_u64 v[86:87], v[86:87], 0, v[242:243]
	global_load_lds_dwordx4 v[86:87], off
.Ldq_0_1:
	v_mfma_f32_16x16x32_bf16 v[42:45], v[124:127], v[132:135], v[42:45]
	v_mfma_f32_16x16x32_bf16 v[38:41], v[136:139], v[132:135], v[38:41]
	s_cbranch_vccz .Ldq_0_2
	s_add_u32 m0, s99, 0x2000
	v_lshl_add_u64 v[90:91], v[90:91], 0, v[242:243]
	global_load_lds_dwordx4 v[90:91], off
.Ldq_0_2:
	v_mfma_f32_16x16x32_bf16 v[34:37], v[140:143], v[132:135], v[34:37]
	ds_read_b128 v[128:131], v98 offset:4096
	ds_read_b128 v[132:135], v98 offset:6144
	v_add_u32_e32 v98, s100, v117
	v_add3_u32 v119, v98, v116, s101
	s_waitcnt lgkmcnt(1)
	v_mfma_f32_16x16x32_bf16 v[30:33], v[120:123], v[128:131], v[30:33]
	s_cbranch_vccz .Ldq_0_3
	s_add_u32 m0, s99, 0x3000
	v_lshl_add_u64 v[94:95], v[94:95], 0, v[242:243]
	global_load_lds_dwordx4 v[94:95], off
.Ldq_0_3:
	v_add_u32_e32 v98, v98, v115
	s_mov_b64 s[14:15], -1
	v_mfma_f32_16x16x32_bf16 v[26:29], v[124:127], v[128:131], v[26:29]
	v_mfma_f32_16x16x32_bf16 v[22:25], v[136:139], v[128:131], v[22:25]
	s_cmp_gt_u32 s2, 5
	s_cbranch_scc1 .Ldq_0_4
	s_add_u32 s99, s100, 0x10000
	s_cmp_lt_u32 s99, 0x14000
	s_cbranch_scc1 .Ldqw_0_4
	s_sub_u32 s99, s99, 0x14000
.Ldqw_0_4:
	s_add_u32 s99, s99, s98
	s_mov_b32 m0, s99
	v_lshl_add_u64 v[66:67], v[66:67], 0, v[242:243]
	global_load_lds_dwordx4 v[66:67], off
.Ldq_0_4:
	v_mfma_f32_16x16x32_bf16 v[18:21], v[140:143], v[128:131], v[18:21]
	s_waitcnt lgkmcnt(0)
	v_mfma_f32_16x16x32_bf16 v[14:17], v[120:123], v[132:135], v[14:17]
	s_cmp_gt_u32 s2, 5
	s_cbranch_scc1 .Ldq_0_5
	s_add_u32 m0, s99, 0x1000
	v_lshl_add_u64 v[70:71], v[70:71], 0, v[242:243]
	global_load_lds_dwordx4 v[70:71], off
.Ldq_0_5:
	ds_read_b128 v[120:123], v119
	v_mfma_f32_16x16x32_bf16 v[10:13], v[124:127], v[132:135], v[10:13]
	v_mfma_f32_16x16x32_bf16 v[6:9], v[136:139], v[132:135], v[6:9]
	s_cmp_gt_u32 s2, 5
	s_cbranch_scc1 .Ldq_0_6
	s_add_u32 m0, s99, 0x2000
	v_lshl_add_u64 v[74:75], v[74:75], 0, v[242:243]
	global_load_lds_dwordx4 v[74:75], off
.Ldq_0_6:
	v_mfma_f32_16x16x32_bf16 v[2:5], v[140:143], v[132:135], v[2:5]
	ds_read_b128 v[124:127], v119 offset:2048
	ds_read_b128 v[128:131], v98
	ds_read_b128 v[132:135], v98 offset:2048
	ds_read_b128 v[136:139], v119 offset:4096
	ds_read_b128 v[140:143], v119 offset:6144
	s_waitcnt lgkmcnt(3)
	v_mfma_f32_16x16x32_bf16 v[62:65], v[120:123], v[128:131], v[62:65]
	s_cmp_gt_u32 s2, 5
	s_cbranch_scc1 .Ldq_0_7
	s_add_u32 m0, s99, 0x3000
	v_lshl_add_u64 v[78:79], v[78:79], 0, v[242:243]
	global_load_lds_dwordx4 v[78:79], off
.Ldq_0_7:
	v_mfma_f32_16x16x32_bf16 v[58:61], v[124:127], v[128:131], v[58:61]
	s_waitcnt lgkmcnt(1)
	v_mfma_f32_16x16x32_bf16 v[54:57], v[136:139], v[128:131], v[54:57]
	s_waitcnt lgkmcnt(0)
	v_mfma_f32_16x16x32_bf16 v[50:53], v[140:143], v[128:131], v[50:53]
	v_mfma_f32_16x16x32_bf16 v[46:49], v[120:123], v[132:135], v[46:49]
	v_mfma_f32_16x16x32_bf16 v[42:45], v[124:127], v[132:135], v[42:45]
	v_mfma_f32_16x16x32_bf16 v[38:41], v[136:139], v[132:135], v[38:41]
	v_mfma_f32_16x16x32_bf16 v[34:37], v[140:143], v[132:135], v[34:37]
	ds_read_b128 v[128:131], v98 offset:4096
	ds_read_b128 v[132:135], v98 offset:6144
	s_waitcnt lgkmcnt(1)
	v_mfma_f32_16x16x32_bf16 v[30:33], v[120:123], v[128:131], v[30:33]
	v_mfma_f32_16x16x32_bf16 v[26:29], v[124:127], v[128:131], v[26:29]
	v_mfma_f32_16x16x32_bf16 v[22:25], v[136:139], v[128:131], v[22:25]
	v_mfma_f32_16x16x32_bf16 v[18:21], v[140:143], v[128:131], v[18:21]
	s_waitcnt lgkmcnt(0)
	v_mfma_f32_16x16x32_bf16 v[14:17], v[120:123], v[132:135], v[14:17]
	v_mfma_f32_16x16x32_bf16 v[10:13], v[124:127], v[132:135], v[10:13]
	v_mfma_f32_16x16x32_bf16 v[6:9], v[136:139], v[132:135], v[6:9]
	v_mfma_f32_16x16x32_bf16 v[2:5], v[140:143], v[132:135], v[2:5]
	s_cbranch_vccnz .LBB0_739
	s_add_i32 s12, s9, 0x8000
	s_mov_b64 s[14:15], 0

.LBB0_741:
	s_cmp_lt_i32 s96, s19
	s_cbranch_scc0 .LBB0_751
	s_ashr_i32 s11, s96, 1
	s_add_i32 s18, s18, s11
	s_lshl_b32 s2, s18, 5
	s_lshl_b32 s3, s96, 6
	s_and_b32 s2, s2, 0xffffff80
	s_and_b32 s3, s3, 64
	v_readlane_b32 s68, v237, 35
	s_or_b32 s2, s2, s3
	s_lshl_b32 s3, s18, 7
	v_readlane_b32 s80, v237, 47
	v_readlane_b32 s81, v237, 48
	s_and_b32 s10, s3, 0x180
	s_ashr_i32 s3, s2, 31
	v_readlane_b32 s82, v237, 49
	v_readlane_b32 s83, v237, 50
	s_mov_b64 s[24:25], s[80:81]
	s_lshl_b64 s[4:5], s[2:3], 10
	s_mov_b64 s[26:27], s[82:83]
	s_add_u32 s6, s26, s4
	s_addc_u32 s7, s27, s5
	s_lshl_b32 s3, s10, 10
	v_lshrrev_b32_e32 v8, 3, v0
	s_add_u32 s8, s54, s3
	v_lshlrev_b32_e32 v14, 10, v8
	v_mov_b32_e32 v15, 0
	v_lshlrev_b32_e32 v4, 4, v0
	s_addc_u32 s9, s55, 0
	v_lshl_add_u64 v[2:3], s[6:7], 0, v[14:15]
	v_and_b32_e32 v4, 0x70, v4
	v_mov_b32_e32 v5, v15
	v_lshl_add_u64 v[2:3], v[2:3], 0, v[4:5]
	v_lshl_add_u64 v[6:7], s[8:9], 0, v[14:15]
	s_mov_b32 s3, 0x2400000
	v_lshl_add_u64 v[4:5], v[6:7], 0, v[4:5]
	v_add_co_u32_e32 v6, vcc, s3, v2
	s_mov_b32 s3, 0x2408000
	s_nop 0
	v_addc_co_u32_e32 v7, vcc, 0, v3, vcc
	v_add_co_u32_e32 v2, vcc, s3, v2
	s_mov_b32 s3, 0xed80000
	s_nop 0
	v_addc_co_u32_e32 v3, vcc, 0, v3, vcc
	s_barrier
	s_mov_b32 m0, s98
	v_lshl_add_u64 v[34:35], v[6:7], 0, v[238:239]
	global_load_lds_dwordx4 v[34:35], off
	s_add_u32 m0, s98, 0x1000
	v_lshl_add_u64 v[38:39], v[2:3], 0, v[238:239]
	global_load_lds_dwordx4 v[38:39], off
	v_add_co_u32_e32 v2, vcc, s3, v4
	s_mov_b32 s3, 0xed88000
	s_nop 0
	v_addc_co_u32_e32 v3, vcc, 0, v5, vcc
	v_add_co_u32_e32 v6, vcc, s3, v4
	s_mov_b32 s3, 0xed90000
	s_nop 0
	v_addc_co_u32_e32 v7, vcc, 0, v5, vcc
	s_add_u32 m0, s98, 0x4000
	v_lshl_add_u64 v[42:43], v[2:3], 0, v[238:239]
	global_load_lds_dwordx4 v[42:43], off
	s_add_u32 m0, s98, 0x5000
	v_lshl_add_u64 v[46:47], v[6:7], 0, v[238:239]
	global_load_lds_dwordx4 v[46:47], off
	v_add_co_u32_e32 v2, vcc, s3, v4
	s_mov_b32 s3, 0xed98000
	s_nop 0
	v_addc_co_u32_e32 v3, vcc, 0, v5, vcc
	v_add_co_u32_e32 v4, vcc, s3, v4
	v_lshlrev_b32_e32 v6, 7, v0
	s_nop 0
	v_addc_co_u32_e32 v5, vcc, 0, v5, vcc
	s_add_u32 m0, s98, 0x6000
	v_lshl_add_u64 v[50:51], v[2:3], 0, v[238:239]
	global_load_lds_dwordx4 v[50:51], off
	s_add_u32 m0, s98, 0x7000
	v_lshl_add_u64 v[54:55], v[4:5], 0, v[238:239]
	global_load_lds_dwordx4 v[54:55], off
	v_lshrrev_b32_e32 v2, 4, v0
	v_bfe_u32 v3, v0, 4, 2
	v_and_b32_e32 v4, 7, v0
	v_lshrrev_b32_e32 v5, 2, v0
	v_and_or_b32 v62, v5, 32, v174
	v_bitop3_b32 v2, v2, v4, 3 bitop3:0x6c
	v_bitop3_b32 v3, v3, v4, 4 bitop3:0x36
	v_and_b32_e32 v5, 0x7c00, v6
	v_lshlrev_b32_e32 v4, 4, v4
	v_lshlrev_b32_e32 v64, 4, v2
	v_or3_b32 v2, s4, v5, v4
	s_sub_i32 s4, s11, s17
	s_and_b32 s4, s4, 3
	v_lshlrev_b32_e32 v7, 7, v8
	v_xor_b32_e32 v8, v8, v0
	s_lshl_b32 s4, s4, 17
	s_movk_i32 s6, 0x70
	v_and_b32_e32 v63, 0x2780, v6
	v_lshlrev_b32_e32 v6, 4, v8
	v_lshlrev_b32_e32 v66, 4, v3
	v_mov_b32_e32 v3, s5
	v_or3_b32 v14, s4, v5, v4
	s_mov_b32 s3, 0
	v_lshlrev_b32_e32 v65, 7, v62
	v_and_or_b32 v67, v6, s6, v7
	v_lshl_add_u64 v[58:59], s[26:27], 0, v[2:3]
	v_lshl_add_u64 v[60:61], s[54:55], 0, v[14:15]
	s_mov_b64 s[4:5], 0
	s_mov_b32 s11, 0
	v_mov_b32_e32 v14, v15
	v_mov_b32_e32 v16, v15
	v_mov_b32_e32 v17, v15
	v_mov_b32_e32 v30, v15
	v_mov_b32_e32 v31, v15
	v_mov_b32_e32 v32, v15
	v_mov_b32_e32 v33, v15
	v_mov_b32_e32 v26, v15
	v_mov_b32_e32 v27, v15
	v_mov_b32_e32 v28, v15
	v_mov_b32_e32 v29, v15
	v_mov_b32_e32 v22, v15
	v_mov_b32_e32 v23, v15
	v_mov_b32_e32 v24, v15
	v_mov_b32_e32 v25, v15
	v_mov_b32_e32 v18, v15
	v_mov_b32_e32 v19, v15
	v_mov_b32_e32 v20, v15
	v_mov_b32_e32 v21, v15
	v_mov_b32_e32 v10, v15
	v_mov_b32_e32 v11, v15
	v_mov_b32_e32 v12, v15
	v_mov_b32_e32 v13, v15
	v_mov_b32_e32 v6, v15
	v_mov_b32_e32 v7, v15
	v_mov_b32_e32 v8, v15
	v_mov_b32_e32 v9, v15
	v_mov_b32_e32 v2, v15
	v_mov_b32_e32 v3, v15
	v_mov_b32_e32 v4, v15
	v_mov_b32_e32 v5, v15
	v_readlane_b32 s69, v237, 36
	v_readlane_b32 s70, v237, 37
	v_readlane_b32 s71, v237, 38
	v_readlane_b32 s72, v237, 39
	v_readlane_b32 s73, v237, 40
	v_readlane_b32 s74, v237, 41
	v_readlane_b32 s75, v237, 42
	v_readlane_b32 s76, v237, 43
	v_readlane_b32 s77, v237, 44
	v_readlane_b32 s78, v237, 45
	v_readlane_b32 s79, v237, 46
	s_waitcnt lgkmcnt(0)
	s_add_u32 m0, s98, 0x8000
	v_lshl_add_u64 v[34:35], v[34:35], 0, v[242:243]
	global_load_lds_dwordx4 v[34:35], off
	s_add_u32 m0, s98, 0x9000
	v_lshl_add_u64 v[38:39], v[38:39], 0, v[242:243]
	global_load_lds_dwordx4 v[38:39], off
	s_mov_b32 s100, 0
	s_mov_b32 s101, 0x4000
	s_waitcnt vmcnt(2)
	s_barrier
	s_branch .LBB0_744
.LBB0_743:
	s_add_u32 s4, s4, 0x80
	s_addc_u32 s5, s5, 0
	s_add_i32 s11, s11, 1
	s_add_u32 s100, s100, 0x8000
	s_cmp_lt_u32 s100, 0x14000
	s_cbranch_scc1 .Ldqr_1
	s_sub_u32 s100, s100, 0x14000

.Ldqs_1:
	s_cmp_gt_u32 s11, 6
	s_cbranch_scc1 .Ldqv_1
	s_waitcnt vmcnt(2)
	s_branch .Ldqx_1

.Ldqx_1:
	s_cmpk_lg_i32 s4, 0x400
	s_mov_b32 s3, s6
	s_waitcnt lgkmcnt(0)
	s_barrier
	s_cbranch_scc0 .LBB0_750

.LBB0_746:
	v_add_u32_e32 v72, s100, v64
	v_add3_u32 v88, v72, v63, s101
	ds_read_b128 v[68:71], v88
	v_add_u32_e32 v80, v72, v65
	ds_read_b128 v[72:75], v88 offset:2048
	ds_read_b128 v[76:79], v80
	ds_read_b128 v[80:83], v80 offset:2048
	ds_read_b128 v[84:87], v88 offset:4096
	s_waitcnt lgkmcnt(2)
	v_mfma_f32_16x16x32_bf16 v[30:33], v[72:75], v[76:79], v[30:33]
	s_andn2_b64 vcc, exec, s[6:7]
	s_waitcnt lgkmcnt(1)
	v_mfma_f32_16x16x32_bf16 v[10:13], v[72:75], v[80:83], v[10:13]
	v_add_u32_e32 v72, s100, v66
	v_add3_u32 v92, v72, v63, s101
	s_mov_b64 s[8:9], -1
	v_mfma_f32_16x16x32_bf16 v[14:17], v[68:71], v[76:79], v[14:17]
	s_cbranch_vccz .Ldq_1_0
	s_add_u32 s99, s100, 0xc000
	s_cmp_lt_u32 s99, 0x14000
	s_cbranch_scc1 .Ldqw_1_0
	s_sub_u32 s99, s99, 0x14000
.Ldqw_1_0:
	s_add_u32 s99, s99, s98
	s_mov_b32 m0, s99
	v_lshl_add_u64 v[42:43], v[42:43], 0, v[242:243]
	global_load_lds_dwordx4 v[42:43], off
.Ldq_1_0:
	v_mfma_f32_16x16x32_bf16 v[18:21], v[68:71], v[80:83], v[18:21]
	ds_read_b128 v[68:71], v92
	ds_read_b128 v[88:91], v88 offset:6144
	s_waitcnt lgkmcnt(2)
	v_mfma_f32_16x16x32_bf16 v[6:9], v[84:87], v[80:83], v[6:9]
	s_cbranch_vccz .Ldq_1_1
	s_add_u32 m0, s99, 0x1000
	v_lshl_add_u64 v[46:47], v[46:47], 0, v[242:243]
	global_load_lds_dwordx4 v[46:47], off
.Ldq_1_1:
	s_waitcnt lgkmcnt(0)
	v_mfma_f32_16x16x32_bf16 v[2:5], v[88:91], v[80:83], v[2:5]
	v_add_u32_e32 v80, v72, v65
	v_mfma_f32_16x16x32_bf16 v[26:29], v[84:87], v[76:79], v[26:29]
	s_cbranch_vccz .Ldq_1_2
	s_add_u32 m0, s99, 0x2000
	v_lshl_add_u64 v[50:51], v[50:51], 0, v[242:243]
	global_load_lds_dwordx4 v[50:51], off
.Ldq_1_2:
	v_mfma_f32_16x16x32_bf16 v[22:25], v[88:91], v[76:79], v[22:25]
	ds_read_b128 v[72:75], v92 offset:2048
	ds_read_b128 v[76:79], v80
	ds_read_b128 v[80:83], v80 offset:2048
	ds_read_b128 v[84:87], v92 offset:4096
	ds_read_b128 v[88:91], v92 offset:6144
	s_waitcnt lgkmcnt(3)
	v_mfma_f32_16x16x32_bf16 v[14:17], v[68:71], v[76:79], v[14:17]
	s_cbranch_vccz .Ldq_1_3
	s_add_u32 m0, s99, 0x3000
	v_lshl_add_u64 v[54:55], v[54:55], 0, v[242:243]
	global_load_lds_dwordx4 v[54:55], off
.Ldq_1_3:
	v_mfma_f32_16x16x32_bf16 v[30:33], v[72:75], v[76:79], v[30:33]
	s_waitcnt lgkmcnt(1)
	v_mfma_f32_16x16x32_bf16 v[26:29], v[84:87], v[76:79], v[26:29]
	s_cmp_gt_u32 s11, 5
	s_cbranch_scc1 .Ldq_1_4
	s_add_u32 s99, s100, 0x10000
	s_cmp_lt_u32 s99, 0x14000
	s_cbranch_scc1 .Ldqw_1_4
	s_sub_u32 s99, s99, 0x14000
.Ldqw_1_4:
	s_add_u32 s99, s99, s98
	s_mov_b32 m0, s99
	v_lshl_add_u64 v[34:35], v[34:35], 0, v[242:243]
	global_load_lds_dwordx4 v[34:35], off
.Ldq_1_4:
	s_waitcnt lgkmcnt(0)
	v_mfma_f32_16x16x32_bf16 v[22:25], v[88:91], v[76:79], v[22:25]
	v_mfma_f32_16x16x32_bf16 v[18:21], v[68:71], v[80:83], v[18:21]
	s_cmp_gt_u32 s11, 5
	s_cbranch_scc1 .Ldq_1_5
	s_add_u32 m0, s99, 0x1000
	v_lshl_add_u64 v[38:39], v[38:39], 0, v[242:243]
	global_load_lds_dwordx4 v[38:39], off
.Ldq_1_5:
	v_mfma_f32_16x16x32_bf16 v[10:13], v[72:75], v[80:83], v[10:13]
	v_mfma_f32_16x16x32_bf16 v[6:9], v[84:87], v[80:83], v[6:9]
	v_mfma_f32_16x16x32_bf16 v[2:5], v[88:91], v[80:83], v[2:5]
	s_cbranch_vccnz .LBB0_748
	s_add_i32 s6, s3, 0x8000
	s_mov_b64 s[8:9], 0

.LBB0_820:
	s_lshl_b32 s10, s13, 7
	s_ashr_i32 s11, s10, 31
	s_lshl_b64 s[20:21], s[10:11], 10
	s_waitcnt lgkmcnt(0)
	v_lshl_add_u64 v[2:3], v[98:99], 0, s[20:21]
	v_add_co_u32_e32 v4, vcc, s23, v2
	s_lshl_b32 s12, s12, 7
	s_nop 0
	v_addc_co_u32_e32 v5, vcc, 0, v3, vcc
	v_add_co_u32_e32 v6, vcc, s24, v2
	s_ashr_i32 s13, s12, 31
	s_nop 0
	v_addc_co_u32_e32 v7, vcc, 0, v3, vcc
	s_lshl_b64 s[18:19], s[12:13], 11
	s_barrier
	s_add_u32 m0, s98, 0x1000
	v_lshl_add_u64 v[66:67], v[4:5], 0, v[238:239]
	global_load_lds_dwordx4 v[66:67], off
	s_add_u32 m0, s98, 0x2000
	v_lshl_add_u64 v[74:75], v[6:7], 0, v[238:239]
	global_load_lds_dwordx4 v[74:75], off
	v_add_co_u32_e32 v4, vcc, s25, v2
	v_lshl_add_u64 v[112:113], v[102:103], 0, s[18:19]
	s_nop 0
	v_addc_co_u32_e32 v5, vcc, 0, v3, vcc
	s_mov_b32 m0, s98
	v_lshl_add_u64 v[70:71], v[2:3], 0, v[238:239]
	global_load_lds_dwordx4 v[70:71], off
	s_add_u32 m0, s98, 0x4000
	v_lshl_add_u64 v[82:83], v[112:113], 0, v[238:239]
	global_load_lds_dwordx4 v[82:83], off
	v_add_co_u32_e32 v2, vcc, s24, v112
	v_mov_b32_e32 v46, 0
	s_nop 0
	v_addc_co_u32_e32 v3, vcc, 0, v113, vcc
	s_add_u32 m0, s98, 0x3000
	v_lshl_add_u64 v[78:79], v[4:5], 0, v[238:239]
	global_load_lds_dwordx4 v[78:79], off
	s_add_u32 m0, s98, 0x5000
	v_lshl_add_u64 v[86:87], v[2:3], 0, v[238:239]
	global_load_lds_dwordx4 v[86:87], off
	v_add_co_u32_e32 v2, vcc, s26, v112
	s_mov_b32 s31, 0
	s_nop 0
	v_addc_co_u32_e32 v3, vcc, 0, v113, vcc
	v_add_co_u32_e32 v4, vcc, s27, v112
	s_mov_b64 s[14:15], 0
	s_nop 0
	v_addc_co_u32_e32 v5, vcc, 0, v113, vcc
	s_add_u32 m0, s98, 0x6000
	v_lshl_add_u64 v[90:91], v[2:3], 0, v[238:239]
	global_load_lds_dwordx4 v[90:91], off
	s_add_u32 m0, s98, 0x7000
	v_lshl_add_u64 v[94:95], v[4:5], 0, v[238:239]
	global_load_lds_dwordx4 v[94:95], off
	s_mov_b32 s13, 0
	v_mov_b32_e32 v47, v46
	v_mov_b32_e32 v48, v46
	v_mov_b32_e32 v49, v46
	v_mov_b32_e32 v58, v46
	v_mov_b32_e32 v59, v46
	v_mov_b32_e32 v60, v46
	v_mov_b32_e32 v61, v46
	v_mov_b32_e32 v62, v46
	v_mov_b32_e32 v63, v46
	v_mov_b32_e32 v64, v46
	v_mov_b32_e32 v65, v46
	v_mov_b32_e32 v54, v46
	v_mov_b32_e32 v55, v46
	v_mov_b32_e32 v56, v46
	v_mov_b32_e32 v57, v46
	v_mov_b32_e32 v14, v46
	v_mov_b32_e32 v15, v46
	v_mov_b32_e32 v16, v46
	v_mov_b32_e32 v17, v46
	v_mov_b32_e32 v6, v46
	v_mov_b32_e32 v7, v46
	v_mov_b32_e32 v8, v46
	v_mov_b32_e32 v9, v46
	v_mov_b32_e32 v10, v46
	v_mov_b32_e32 v11, v46
	s_lshl_b64 s[16:17], s[10:11], 9
	v_lshl_add_u64 v[108:109], v[104:105], 0, s[20:21]
	v_lshl_add_u64 v[110:111], v[106:107], 0, s[18:19]
	v_mov_b32_e32 v12, v46
	v_mov_b32_e32 v13, v46
	v_mov_b32_e32 v50, v46
	v_mov_b32_e32 v51, v46
	v_mov_b32_e32 v52, v46
	v_mov_b32_e32 v53, v46
	v_mov_b32_e32 v42, v46
	v_mov_b32_e32 v43, v46
	v_mov_b32_e32 v44, v46
	v_mov_b32_e32 v45, v46
	v_mov_b32_e32 v30, v46
	v_mov_b32_e32 v31, v46
	v_mov_b32_e32 v32, v46
	v_mov_b32_e32 v33, v46
	v_mov_b32_e32 v34, v46
	v_mov_b32_e32 v35, v46
	v_mov_b32_e32 v36, v46
	v_mov_b32_e32 v37, v46
	v_mov_b32_e32 v38, v46
	v_mov_b32_e32 v39, v46
	v_mov_b32_e32 v40, v46
	v_mov_b32_e32 v41, v46
	v_mov_b32_e32 v26, v46
	v_mov_b32_e32 v27, v46
	v_mov_b32_e32 v28, v46
	v_mov_b32_e32 v29, v46
	v_mov_b32_e32 v22, v46
	v_mov_b32_e32 v23, v46
	v_mov_b32_e32 v24, v46
	v_mov_b32_e32 v25, v46
	v_mov_b32_e32 v18, v46
	v_mov_b32_e32 v19, v46
	v_mov_b32_e32 v20, v46
	v_mov_b32_e32 v21, v46
	v_mov_b32_e32 v2, v46
	v_mov_b32_e32 v3, v46
	v_mov_b32_e32 v4, v46
	v_mov_b32_e32 v5, v46
	s_waitcnt lgkmcnt(0)
	s_add_u32 m0, s98, 0x8000
	v_lshl_add_u64 v[70:71], v[70:71], 0, v[242:243]
	global_load_lds_dwordx4 v[70:71], off
	s_add_u32 m0, s98, 0x9000
	v_lshl_add_u64 v[66:67], v[66:67], 0, v[242:243]
	global_load_lds_dwordx4 v[66:67], off
	s_add_u32 m0, s98, 0xa000
	v_lshl_add_u64 v[74:75], v[74:75], 0, v[242:243]
	global_load_lds_dwordx4 v[74:75], off
	s_add_u32 m0, s98, 0xb000
	v_lshl_add_u64 v[78:79], v[78:79], 0, v[242:243]
	global_load_lds_dwordx4 v[78:79], off
	s_mov_b32 s100, 0
	s_mov_b32 s101, 0x4000
	s_waitcnt vmcnt(4)
	s_barrier
	s_branch .LBB0_822
.LBB0_821:
	s_add_u32 s14, s14, 0x80
	s_addc_u32 s15, s15, 0
	s_add_i32 s13, s13, 1
	s_add_u32 s100, s100, 0x8000
	s_cmp_lt_u32 s100, 0x14000
	s_cbranch_scc1 .Ldqr_2
	s_sub_u32 s100, s100, 0x14000

.Ldqs_2:
	s_cmp_gt_u32 s13, 6
	s_cbranch_scc1 .Ldqv_2
	s_waitcnt vmcnt(4)
	s_branch .Ldqx_2

.Ldqx_2:
	s_cmpk_lg_i32 s14, 0x400
	s_mov_b32 s31, s11
	s_waitcnt lgkmcnt(0)
	s_barrier
	s_cbranch_scc0 .LBB0_828

.LBB0_824:
	v_add_u32_e32 v128, s100, v115
	v_add3_u32 v144, v128, v118, s101
	ds_read_b128 v[124:127], v144
	v_add_u32_e32 v148, v128, v117
	ds_read_b128 v[128:131], v144 offset:2048
	ds_read_b128 v[132:135], v148
	ds_read_b128 v[136:139], v148 offset:2048
	ds_read_b128 v[140:143], v144 offset:4096
	ds_read_b128 v[144:147], v144 offset:6144
	s_waitcnt lgkmcnt(3)
	v_mfma_f32_16x16x32_bf16 v[58:61], v[128:131], v[132:135], v[58:61]
	s_mov_b64 s[20:21], -1
	s_andn2_b64 vcc, exec, s[18:19]
	v_mfma_f32_16x16x32_bf16 v[46:49], v[124:127], v[132:135], v[46:49]
	s_waitcnt lgkmcnt(1)
	v_mfma_f32_16x16x32_bf16 v[62:65], v[140:143], v[132:135], v[62:65]
	s_cbranch_vccz .Ldq_2_0
	s_add_u32 s99, s100, 0xc000
	s_cmp_lt_u32 s99, 0x14000
	s_cbranch_scc1 .Ldqw_2_0
	s_sub_u32 s99, s99, 0x14000

.Ldq_2_0:
	s_waitcnt lgkmcnt(0)
	v_mfma_f32_16x16x32_bf16 v[54:57], v[144:147], v[132:135], v[54:57]
	v_mfma_f32_16x16x32_bf16 v[14:17], v[124:127], v[136:139], v[14:17]
	s_cbranch_vccz .Ldq_2_1
	s_add_u32 m0, s99, 0x1000
	v_lshl_add_u64 v[86:87], v[86:87], 0, v[242:243]
	global_load_lds_dwordx4 v[86:87], off
.Ldq_2_1:
	v_mfma_f32_16x16x32_bf16 v[6:9], v[128:131], v[136:139], v[6:9]
	v_mfma_f32_16x16x32_bf16 v[10:13], v[140:143], v[136:139], v[10:13]
	s_cbranch_vccz .Ldq_2_2
	s_add_u32 m0, s99, 0x2000
	v_lshl_add_u64 v[90:91], v[90:91], 0, v[242:243]
	global_load_lds_dwordx4 v[90:91], off
.Ldq_2_2:
	v_mfma_f32_16x16x32_bf16 v[50:53], v[144:147], v[136:139], v[50:53]
	ds_read_b128 v[132:135], v148 offset:4096
	ds_read_b128 v[136:139], v148 offset:6144
	s_waitcnt lgkmcnt(1)
	v_mfma_f32_16x16x32_bf16 v[30:33], v[128:131], v[132:135], v[30:33]
	s_cbranch_vccz .Ldq_2_3
	s_add_u32 m0, s99, 0x3000
	v_lshl_add_u64 v[94:95], v[94:95], 0, v[242:243]
	global_load_lds_dwordx4 v[94:95], off
.Ldq_2_3:
	s_waitcnt lgkmcnt(0)
	v_mfma_f32_16x16x32_bf16 v[22:25], v[128:131], v[136:139], v[22:25]
	v_add_u32_e32 v128, s100, v119
	v_add3_u32 v148, v128, v118, s101
	v_add_u32_e32 v149, v128, v117
	v_mfma_f32_16x16x32_bf16 v[42:45], v[124:127], v[132:135], v[42:45]
	s_cmp_gt_u32 s13, 5
	s_cbranch_scc1 .Ldq_2_4
	s_add_u32 s99, s100, 0x10000
	s_cmp_lt_u32 s99, 0x14000
	s_cbranch_scc1 .Ldqw_2_4
	s_sub_u32 s99, s99, 0x14000
.Ldqw_2_4:
	s_add_u32 s99, s99, s98
	s_mov_b32 m0, s99
	v_lshl_add_u64 v[70:71], v[70:71], 0, v[242:243]
	global_load_lds_dwordx4 v[70:71], off
.Ldq_2_4:
	v_mfma_f32_16x16x32_bf16 v[34:37], v[140:143], v[132:135], v[34:37]
	v_mfma_f32_16x16x32_bf16 v[38:41], v[144:147], v[132:135], v[38:41]
	s_cmp_gt_u32 s13, 5
	s_cbranch_scc1 .Ldq_2_5
	s_add_u32 m0, s99, 0x1000
	v_lshl_add_u64 v[66:67], v[66:67], 0, v[242:243]
	global_load_lds_dwordx4 v[66:67], off
.Ldq_2_5:
	v_mfma_f32_16x16x32_bf16 v[26:29], v[124:127], v[136:139], v[26:29]
	ds_read_b128 v[124:127], v148
	v_mfma_f32_16x16x32_bf16 v[18:21], v[140:143], v[136:139], v[18:21]
	s_cmp_gt_u32 s13, 5
	s_cbranch_scc1 .Ldq_2_6
	s_add_u32 m0, s99, 0x2000
	v_lshl_add_u64 v[74:75], v[74:75], 0, v[242:243]
	global_load_lds_dwordx4 v[74:75], off
.Ldq_2_6:
	v_mfma_f32_16x16x32_bf16 v[2:5], v[144:147], v[136:139], v[2:5]
	ds_read_b128 v[128:131], v148 offset:2048
	ds_read_b128 v[132:135], v149
	ds_read_b128 v[136:139], v149 offset:2048
	ds_read_b128 v[140:143], v148 offset:4096
	ds_read_b128 v[144:147], v148 offset:6144
	s_waitcnt lgkmcnt(3)
	v_mfma_f32_16x16x32_bf16 v[46:49], v[124:127], v[132:135], v[46:49]
	s_cmp_gt_u32 s13, 5
	s_cbranch_scc1 .Ldq_2_7
	s_add_u32 m0, s99, 0x3000
	v_lshl_add_u64 v[78:79], v[78:79], 0, v[242:243]
	global_load_lds_dwordx4 v[78:79], off
.Ldq_2_7:
	v_mfma_f32_16x16x32_bf16 v[58:61], v[128:131], v[132:135], v[58:61]
	s_waitcnt lgkmcnt(1)
	v_mfma_f32_16x16x32_bf16 v[62:65], v[140:143], v[132:135], v[62:65]
	s_waitcnt lgkmcnt(0)
	v_mfma_f32_16x16x32_bf16 v[54:57], v[144:147], v[132:135], v[54:57]
	v_mfma_f32_16x16x32_bf16 v[14:17], v[124:127], v[136:139], v[14:17]
	v_mfma_f32_16x16x32_bf16 v[6:9], v[128:131], v[136:139], v[6:9]
	v_mfma_f32_16x16x32_bf16 v[10:13], v[140:143], v[136:139], v[10:13]
	v_mfma_f32_16x16x32_bf16 v[50:53], v[144:147], v[136:139], v[50:53]
	ds_read_b128 v[132:135], v149 offset:4096
	ds_read_b128 v[136:139], v149 offset:6144
	s_waitcnt lgkmcnt(1)
	v_mfma_f32_16x16x32_bf16 v[42:45], v[124:127], v[132:135], v[42:45]
	v_mfma_f32_16x16x32_bf16 v[30:33], v[128:131], v[132:135], v[30:33]
	v_mfma_f32_16x16x32_bf16 v[34:37], v[140:143], v[132:135], v[34:37]
	v_mfma_f32_16x16x32_bf16 v[38:41], v[144:147], v[132:135], v[38:41]
	s_waitcnt lgkmcnt(0)
	v_mfma_f32_16x16x32_bf16 v[26:29], v[124:127], v[136:139], v[26:29]
	v_mfma_f32_16x16x32_bf16 v[22:25], v[128:131], v[136:139], v[22:25]
	v_mfma_f32_16x16x32_bf16 v[18:21], v[140:143], v[136:139], v[18:21]
	v_mfma_f32_16x16x32_bf16 v[2:5], v[144:147], v[136:139], v[2:5]
	s_cbranch_vccnz .LBB0_826
	s_add_i32 s11, s31, 0x8000
	s_mov_b64 s[20:21], 0

.LBB0_828:
	s_waitcnt vmcnt(7)
	v_lshl_add_u64 v[70:71], s[16:17], 1, v[100:101]
	s_waitcnt vmcnt(6)
	v_add_co_u32_e32 v66, vcc, 0x8000, v70
	s_nop 1
	v_addc_co_u32_e32 v67, vcc, 0, v71, vcc
	v_add_co_u32_e32 v72, vcc, 0x10000, v70
	s_barrier
	s_nop 0
	v_addc_co_u32_e32 v73, vcc, 0, v71, vcc
	s_waitcnt vmcnt(4)
	v_add_co_u32_e32 v78, vcc, 0x18000, v70
	s_nop 1
	v_addc_co_u32_e32 v79, vcc, 0, v71, vcc
	s_waitcnt vmcnt(2)
	v_add_co_u32_e32 v86, vcc, 0x10000, v112
	s_add_u32 m0, s98, 0x1000
	v_lshl_add_u64 v[66:67], v[66:67], 0, v[238:239]
	global_load_lds_dwordx4 v[66:67], off
	s_nop 0
	s_add_u32 m0, s98, 0x2000
	v_lshl_add_u64 v[74:75], v[72:73], 0, v[238:239]
	global_load_lds_dwordx4 v[74:75], off
	v_addc_co_u32_e32 v87, vcc, 0, v113, vcc
	v_add_co_u32_e32 v90, vcc, 0x20000, v112
	s_mov_b32 m0, s98
	v_lshl_add_u64 v[70:71], v[70:71], 0, v[238:239]
	global_load_lds_dwordx4 v[70:71], off
	s_nop 0
	s_add_u32 m0, s98, 0x4000
	v_lshl_add_u64 v[82:83], v[112:113], 0, v[240:241]
	global_load_lds_dwordx4 v[82:83], off
	v_addc_co_u32_e32 v91, vcc, 0, v113, vcc
	v_add_co_u32_e32 v94, vcc, 0x30000, v112
	s_add_u32 m0, s98, 0x3000
	v_lshl_add_u64 v[78:79], v[78:79], 0, v[238:239]
	global_load_lds_dwordx4 v[78:79], off
	s_nop 0
	s_add_u32 m0, s98, 0x5000
	v_lshl_add_u64 v[86:87], v[86:87], 0, v[240:241]
	global_load_lds_dwordx4 v[86:87], off
	v_addc_co_u32_e32 v95, vcc, 0, v113, vcc
	s_add_u32 m0, s98, 0x6000
	v_lshl_add_u64 v[90:91], v[90:91], 0, v[240:241]
	global_load_lds_dwordx4 v[90:91], off
	s_nop 0
	s_add_u32 m0, s98, 0x7000
	v_lshl_add_u64 v[94:95], v[94:95], 0, v[240:241]
	global_load_lds_dwordx4 v[94:95], off
	s_mov_b32 s11, 0
	s_mov_b64 s[14:15], 0
	s_mov_b32 s13, 0
	s_waitcnt lgkmcnt(0)
	s_add_u32 m0, s98, 0x8000
	v_lshl_add_u64 v[70:71], v[70:71], 0, v[242:243]
	global_load_lds_dwordx4 v[70:71], off
	s_add_u32 m0, s98, 0x9000
	v_lshl_add_u64 v[66:67], v[66:67], 0, v[242:243]
	global_load_lds_dwordx4 v[66:67], off
	s_add_u32 m0, s98, 0xa000
	v_lshl_add_u64 v[74:75], v[74:75], 0, v[242:243]
	global_load_lds_dwordx4 v[74:75], off
	s_add_u32 m0, s98, 0xb000
	v_lshl_add_u64 v[78:79], v[78:79], 0, v[242:243]
	global_load_lds_dwordx4 v[78:79], off
	s_mov_b32 s100, 0
	s_mov_b32 s101, 0x4000
	s_waitcnt vmcnt(4)
	s_barrier
	s_branch .LBB0_830

.Ldqx_3:
	s_cmpk_lg_i32 s14, 0x400
	s_mov_b32 s11, s16
	s_waitcnt lgkmcnt(0)
	s_barrier
	s_cbranch_scc0 .LBB0_836

.LBB0_832:
	v_add_u32_e32 v112, s100, v115
	v_add3_u32 v113, v112, v118, s101
	ds_read_b128 v[124:127], v113
	v_add_u32_e32 v112, v112, v117
	ds_read_b128 v[128:131], v113 offset:2048
	ds_read_b128 v[132:135], v112
	ds_read_b128 v[136:139], v112 offset:2048
	ds_read_b128 v[140:143], v113 offset:4096
	ds_read_b128 v[144:147], v113 offset:6144
	s_waitcnt lgkmcnt(3)
	v_mfma_f32_16x16x32_bf16 v[58:61], v[128:131], v[132:135], v[58:61]
	s_andn2_b64 vcc, exec, s[16:17]
	v_mfma_f32_16x16x32_bf16 v[46:49], v[124:127], v[132:135], v[46:49]
	s_waitcnt lgkmcnt(1)
	v_mfma_f32_16x16x32_bf16 v[62:65], v[140:143], v[132:135], v[62:65]
	s_cbranch_vccz .Ldq_3_0
	s_add_u32 s99, s100, 0xc000
	s_cmp_lt_u32 s99, 0x14000
	s_cbranch_scc1 .Ldqw_3_0
	s_sub_u32 s99, s99, 0x14000

.Ldq_3_2:
	v_mfma_f32_16x16x32_bf16 v[50:53], v[144:147], v[136:139], v[50:53]
	ds_read_b128 v[132:135], v112 offset:4096
	ds_read_b128 v[136:139], v112 offset:6144
	v_add_u32_e32 v112, s100, v119
	v_add3_u32 v113, v112, v118, s101
	s_waitcnt lgkmcnt(1)
	v_mfma_f32_16x16x32_bf16 v[42:45], v[124:127], v[132:135], v[42:45]
	s_cbranch_vccz .Ldq_3_3
	s_add_u32 m0, s99, 0x3000
	v_lshl_add_u64 v[94:95], v[94:95], 0, v[242:243]
	global_load_lds_dwordx4 v[94:95], off
.Ldq_3_3:
	v_add_u32_e32 v112, v112, v117
	s_mov_b64 s[18:19], -1
	v_mfma_f32_16x16x32_bf16 v[30:33], v[128:131], v[132:135], v[30:33]
	v_mfma_f32_16x16x32_bf16 v[34:37], v[140:143], v[132:135], v[34:37]
	s_cmp_gt_u32 s13, 5
	s_cbranch_scc1 .Ldq_3_4
	s_add_u32 s99, s100, 0x10000
	s_cmp_lt_u32 s99, 0x14000
	s_cbranch_scc1 .Ldqw_3_4
	s_sub_u32 s99, s99, 0x14000

.Ldq_3_4:
	v_mfma_f32_16x16x32_bf16 v[38:41], v[144:147], v[132:135], v[38:41]
	s_waitcnt lgkmcnt(0)
	v_mfma_f32_16x16x32_bf16 v[26:29], v[124:127], v[136:139], v[26:29]
	s_cmp_gt_u32 s13, 5
	s_cbranch_scc1 .Ldq_3_5
	s_add_u32 m0, s99, 0x1000
	v_lshl_add_u64 v[66:67], v[66:67], 0, v[242:243]
	global_load_lds_dwordx4 v[66:67], off
.Ldq_3_5:
	ds_read_b128 v[124:127], v113
	v_mfma_f32_16x16x32_bf16 v[22:25], v[128:131], v[136:139], v[22:25]
	v_mfma_f32_16x16x32_bf16 v[18:21], v[140:143], v[136:139], v[18:21]
	s_cmp_gt_u32 s13, 5
	s_cbranch_scc1 .Ldq_3_6
	s_add_u32 m0, s99, 0x2000
	v_lshl_add_u64 v[74:75], v[74:75], 0, v[242:243]
	global_load_lds_dwordx4 v[74:75], off
.Ldq_3_6:
	v_mfma_f32_16x16x32_bf16 v[2:5], v[144:147], v[136:139], v[2:5]
	ds_read_b128 v[128:131], v113 offset:2048
	ds_read_b128 v[132:135], v112
	ds_read_b128 v[136:139], v112 offset:2048
	ds_read_b128 v[140:143], v113 offset:4096
	ds_read_b128 v[144:147], v113 offset:6144
	s_waitcnt lgkmcnt(3)
	v_mfma_f32_16x16x32_bf16 v[46:49], v[124:127], v[132:135], v[46:49]
	s_cmp_gt_u32 s13, 5
	s_cbranch_scc1 .Ldq_3_7
	s_add_u32 m0, s99, 0x3000
	v_lshl_add_u64 v[78:79], v[78:79], 0, v[242:243]
	global_load_lds_dwordx4 v[78:79], off
.Ldq_3_7:
	v_mfma_f32_16x16x32_bf16 v[58:61], v[128:131], v[132:135], v[58:61]
	s_waitcnt lgkmcnt(1)
	v_mfma_f32_16x16x32_bf16 v[62:65], v[140:143], v[132:135], v[62:65]
	s_waitcnt lgkmcnt(0)
	v_mfma_f32_16x16x32_bf16 v[54:57], v[144:147], v[132:135], v[54:57]
	v_mfma_f32_16x16x32_bf16 v[14:17], v[124:127], v[136:139], v[14:17]
	v_mfma_f32_16x16x32_bf16 v[6:9], v[128:131], v[136:139], v[6:9]
	v_mfma_f32_16x16x32_bf16 v[10:13], v[140:143], v[136:139], v[10:13]
	v_mfma_f32_16x16x32_bf16 v[50:53], v[144:147], v[136:139], v[50:53]
	ds_read_b128 v[132:135], v112 offset:4096
	ds_read_b128 v[136:139], v112 offset:6144
	s_waitcnt lgkmcnt(1)
	v_mfma_f32_16x16x32_bf16 v[42:45], v[124:127], v[132:135], v[42:45]
	v_mfma_f32_16x16x32_bf16 v[30:33], v[128:131], v[132:135], v[30:33]
	v_mfma_f32_16x16x32_bf16 v[34:37], v[140:143], v[132:135], v[34:37]
	v_mfma_f32_16x16x32_bf16 v[38:41], v[144:147], v[132:135], v[38:41]
	s_waitcnt lgkmcnt(0)
	v_mfma_f32_16x16x32_bf16 v[26:29], v[124:127], v[136:139], v[26:29]
	v_mfma_f32_16x16x32_bf16 v[22:25], v[128:131], v[136:139], v[22:25]
	v_mfma_f32_16x16x32_bf16 v[18:21], v[140:143], v[136:139], v[18:21]
	v_mfma_f32_16x16x32_bf16 v[2:5], v[144:147], v[136:139], v[2:5]
	s_cbranch_vccnz .LBB0_834
	s_add_i32 s16, s11, 0x8000
	s_mov_b64 s[18:19], 0

.LBB0_853:
	s_lshl_b32 s8, s11, 7
	s_ashr_i32 s9, s8, 31
	s_lshl_b64 s[18:19], s[8:9], 10
	s_waitcnt lgkmcnt(0)
	v_lshl_add_u64 v[2:3], v[98:99], 0, s[18:19]
	v_add_co_u32_e32 v4, vcc, s23, v2
	s_lshl_b32 s10, s10, 7
	s_nop 0
	v_addc_co_u32_e32 v5, vcc, 0, v3, vcc
	v_add_co_u32_e32 v6, vcc, s24, v2
	s_ashr_i32 s11, s10, 31
	s_nop 0
	v_addc_co_u32_e32 v7, vcc, 0, v3, vcc
	s_lshl_b64 s[16:17], s[10:11], 11
	s_barrier
	s_add_u32 m0, s98, 0x1000
	v_lshl_add_u64 v[66:67], v[4:5], 0, v[238:239]
	global_load_lds_dwordx4 v[66:67], off
	s_add_u32 m0, s98, 0x2000
	v_lshl_add_u64 v[74:75], v[6:7], 0, v[238:239]
	global_load_lds_dwordx4 v[74:75], off
	v_add_co_u32_e32 v4, vcc, s25, v2
	v_lshl_add_u64 v[112:113], v[102:103], 0, s[16:17]
	s_nop 0
	v_addc_co_u32_e32 v5, vcc, 0, v3, vcc
	s_mov_b32 m0, s98
	v_lshl_add_u64 v[70:71], v[2:3], 0, v[238:239]
	global_load_lds_dwordx4 v[70:71], off
	s_add_u32 m0, s98, 0x4000
	v_lshl_add_u64 v[82:83], v[112:113], 0, v[238:239]
	global_load_lds_dwordx4 v[82:83], off
	v_add_co_u32_e32 v2, vcc, s24, v112
	v_mov_b32_e32 v46, 0
	s_nop 0
	v_addc_co_u32_e32 v3, vcc, 0, v113, vcc
	s_add_u32 m0, s98, 0x3000
	v_lshl_add_u64 v[78:79], v[4:5], 0, v[238:239]
	global_load_lds_dwordx4 v[78:79], off
	s_add_u32 m0, s98, 0x5000
	v_lshl_add_u64 v[86:87], v[2:3], 0, v[238:239]
	global_load_lds_dwordx4 v[86:87], off
	v_add_co_u32_e32 v2, vcc, s26, v112
	s_mov_b32 s31, 0
	s_nop 0
	v_addc_co_u32_e32 v3, vcc, 0, v113, vcc
	v_add_co_u32_e32 v4, vcc, s27, v112
	s_mov_b64 s[12:13], 0
	s_nop 0
	v_addc_co_u32_e32 v5, vcc, 0, v113, vcc
	s_add_u32 m0, s98, 0x6000
	v_lshl_add_u64 v[90:91], v[2:3], 0, v[238:239]
	global_load_lds_dwordx4 v[90:91], off
	s_add_u32 m0, s98, 0x7000
	v_lshl_add_u64 v[94:95], v[4:5], 0, v[238:239]
	global_load_lds_dwordx4 v[94:95], off
	s_mov_b32 s11, 0
	v_mov_b32_e32 v47, v46
	v_mov_b32_e32 v48, v46
	v_mov_b32_e32 v49, v46
	v_mov_b32_e32 v58, v46
	v_mov_b32_e32 v59, v46
	v_mov_b32_e32 v60, v46
	v_mov_b32_e32 v61, v46
	v_mov_b32_e32 v62, v46
	v_mov_b32_e32 v63, v46
	v_mov_b32_e32 v64, v46
	v_mov_b32_e32 v65, v46
	v_mov_b32_e32 v54, v46
	v_mov_b32_e32 v55, v46
	v_mov_b32_e32 v56, v46
	v_mov_b32_e32 v57, v46
	v_mov_b32_e32 v14, v46
	v_mov_b32_e32 v15, v46
	v_mov_b32_e32 v16, v46
	v_mov_b32_e32 v17, v46
	v_mov_b32_e32 v6, v46
	v_mov_b32_e32 v7, v46
	v_mov_b32_e32 v8, v46
	v_mov_b32_e32 v9, v46
	v_mov_b32_e32 v10, v46
	v_mov_b32_e32 v11, v46
	s_lshl_b64 s[14:15], s[8:9], 9
	v_lshl_add_u64 v[108:109], v[104:105], 0, s[18:19]
	v_lshl_add_u64 v[110:111], v[106:107], 0, s[16:17]
	v_mov_b32_e32 v12, v46
	v_mov_b32_e32 v13, v46
	v_mov_b32_e32 v50, v46
	v_mov_b32_e32 v51, v46
	v_mov_b32_e32 v52, v46
	v_mov_b32_e32 v53, v46
	v_mov_b32_e32 v42, v46
	v_mov_b32_e32 v43, v46
	v_mov_b32_e32 v44, v46
	v_mov_b32_e32 v45, v46
	v_mov_b32_e32 v30, v46
	v_mov_b32_e32 v31, v46
	v_mov_b32_e32 v32, v46
	v_mov_b32_e32 v33, v46
	v_mov_b32_e32 v34, v46
	v_mov_b32_e32 v35, v46
	v_mov_b32_e32 v36, v46
	v_mov_b32_e32 v37, v46
	v_mov_b32_e32 v38, v46
	v_mov_b32_e32 v39, v46
	v_mov_b32_e32 v40, v46
	v_mov_b32_e32 v41, v46
	v_mov_b32_e32 v26, v46
	v_mov_b32_e32 v27, v46
	v_mov_b32_e32 v28, v46
	v_mov_b32_e32 v29, v46
	v_mov_b32_e32 v22, v46
	v_mov_b32_e32 v23, v46
	v_mov_b32_e32 v24, v46
	v_mov_b32_e32 v25, v46
	v_mov_b32_e32 v18, v46
	v_mov_b32_e32 v19, v46
	v_mov_b32_e32 v20, v46
	v_mov_b32_e32 v21, v46
	v_mov_b32_e32 v2, v46
	v_mov_b32_e32 v3, v46
	v_mov_b32_e32 v4, v46
	v_mov_b32_e32 v5, v46
	s_waitcnt lgkmcnt(0)
	s_add_u32 m0, s98, 0x8000
	v_lshl_add_u64 v[70:71], v[70:71], 0, v[242:243]
	global_load_lds_dwordx4 v[70:71], off
	s_add_u32 m0, s98, 0x9000
	v_lshl_add_u64 v[66:67], v[66:67], 0, v[242:243]
	global_load_lds_dwordx4 v[66:67], off
	s_add_u32 m0, s98, 0xa000
	v_lshl_add_u64 v[74:75], v[74:75], 0, v[242:243]
	global_load_lds_dwordx4 v[74:75], off
	s_add_u32 m0, s98, 0xb000
	v_lshl_add_u64 v[78:79], v[78:79], 0, v[242:243]
	global_load_lds_dwordx4 v[78:79], off
	s_mov_b32 s100, 0
	s_mov_b32 s101, 0x4000
	s_waitcnt vmcnt(4)
	s_barrier
	s_branch .LBB0_855
.LBB0_854:
	s_add_u32 s12, s12, 0x80
	s_addc_u32 s13, s13, 0
	s_add_i32 s11, s11, 1
	s_add_u32 s100, s100, 0x8000
	s_cmp_lt_u32 s100, 0x14000
	s_cbranch_scc1 .Ldqr_4
	s_sub_u32 s100, s100, 0x14000

.Ldqs_4:
	s_cmp_gt_u32 s11, 6
	s_cbranch_scc1 .Ldqv_4
	s_waitcnt vmcnt(4)
	s_branch .Ldqx_4

.Ldqx_4:
	s_cmpk_lg_i32 s12, 0x400
	s_mov_b32 s31, s9
	s_waitcnt lgkmcnt(0)
	s_barrier
	s_cbranch_scc0 .LBB0_861

.LBB0_857:
	v_add_u32_e32 v128, s100, v115
	v_add3_u32 v144, v128, v118, s101
	ds_read_b128 v[124:127], v144
	v_add_u32_e32 v148, v128, v117
	ds_read_b128 v[128:131], v144 offset:2048
	ds_read_b128 v[132:135], v148
	ds_read_b128 v[136:139], v148 offset:2048
	ds_read_b128 v[140:143], v144 offset:4096
	ds_read_b128 v[144:147], v144 offset:6144
	s_waitcnt lgkmcnt(3)
	v_mfma_f32_16x16x32_bf16 v[58:61], v[128:131], v[132:135], v[58:61]
	s_mov_b64 s[18:19], -1
	s_andn2_b64 vcc, exec, s[16:17]
	v_mfma_f32_16x16x32_bf16 v[46:49], v[124:127], v[132:135], v[46:49]
	s_waitcnt lgkmcnt(1)
	v_mfma_f32_16x16x32_bf16 v[62:65], v[140:143], v[132:135], v[62:65]
	s_cbranch_vccz .Ldq_4_0
	s_add_u32 s99, s100, 0xc000
	s_cmp_lt_u32 s99, 0x14000
	s_cbranch_scc1 .Ldqw_4_0
	s_sub_u32 s99, s99, 0x14000

.Ldq_4_3:
	s_waitcnt lgkmcnt(0)
	v_mfma_f32_16x16x32_bf16 v[22:25], v[128:131], v[136:139], v[22:25]
	v_add_u32_e32 v128, s100, v119
	v_add3_u32 v148, v128, v118, s101
	v_add_u32_e32 v149, v128, v117
	v_mfma_f32_16x16x32_bf16 v[42:45], v[124:127], v[132:135], v[42:45]
	s_cmp_gt_u32 s11, 5
	s_cbranch_scc1 .Ldq_4_4
	s_add_u32 s99, s100, 0x10000
	s_cmp_lt_u32 s99, 0x14000
	s_cbranch_scc1 .Ldqw_4_4
	s_sub_u32 s99, s99, 0x14000

.Ldq_4_4:
	v_mfma_f32_16x16x32_bf16 v[34:37], v[140:143], v[132:135], v[34:37]
	v_mfma_f32_16x16x32_bf16 v[38:41], v[144:147], v[132:135], v[38:41]
	s_cmp_gt_u32 s11, 5
	s_cbranch_scc1 .Ldq_4_5
	s_add_u32 m0, s99, 0x1000
	v_lshl_add_u64 v[66:67], v[66:67], 0, v[242:243]
	global_load_lds_dwordx4 v[66:67], off
.Ldq_4_5:
	v_mfma_f32_16x16x32_bf16 v[26:29], v[124:127], v[136:139], v[26:29]
	ds_read_b128 v[124:127], v148
	v_mfma_f32_16x16x32_bf16 v[18:21], v[140:143], v[136:139], v[18:21]
	s_cmp_gt_u32 s11, 5
	s_cbranch_scc1 .Ldq_4_6
	s_add_u32 m0, s99, 0x2000
	v_lshl_add_u64 v[74:75], v[74:75], 0, v[242:243]
	global_load_lds_dwordx4 v[74:75], off
.Ldq_4_6:
	v_mfma_f32_16x16x32_bf16 v[2:5], v[144:147], v[136:139], v[2:5]
	ds_read_b128 v[128:131], v148 offset:2048
	ds_read_b128 v[132:135], v149
	ds_read_b128 v[136:139], v149 offset:2048
	ds_read_b128 v[140:143], v148 offset:4096
	ds_read_b128 v[144:147], v148 offset:6144
	s_waitcnt lgkmcnt(3)
	v_mfma_f32_16x16x32_bf16 v[46:49], v[124:127], v[132:135], v[46:49]
	s_cmp_gt_u32 s11, 5
	s_cbranch_scc1 .Ldq_4_7
	s_add_u32 m0, s99, 0x3000
	v_lshl_add_u64 v[78:79], v[78:79], 0, v[242:243]
	global_load_lds_dwordx4 v[78:79], off
.Ldq_4_7:
	v_mfma_f32_16x16x32_bf16 v[58:61], v[128:131], v[132:135], v[58:61]
	s_waitcnt lgkmcnt(1)
	v_mfma_f32_16x16x32_bf16 v[62:65], v[140:143], v[132:135], v[62:65]
	s_waitcnt lgkmcnt(0)
	v_mfma_f32_16x16x32_bf16 v[54:57], v[144:147], v[132:135], v[54:57]
	v_mfma_f32_16x16x32_bf16 v[14:17], v[124:127], v[136:139], v[14:17]
	v_mfma_f32_16x16x32_bf16 v[6:9], v[128:131], v[136:139], v[6:9]
	v_mfma_f32_16x16x32_bf16 v[10:13], v[140:143], v[136:139], v[10:13]
	v_mfma_f32_16x16x32_bf16 v[50:53], v[144:147], v[136:139], v[50:53]
	ds_read_b128 v[132:135], v149 offset:4096
	ds_read_b128 v[136:139], v149 offset:6144
	s_waitcnt lgkmcnt(1)
	v_mfma_f32_16x16x32_bf16 v[42:45], v[124:127], v[132:135], v[42:45]
	v_mfma_f32_16x16x32_bf16 v[30:33], v[128:131], v[132:135], v[30:33]
	v_mfma_f32_16x16x32_bf16 v[34:37], v[140:143], v[132:135], v[34:37]
	v_mfma_f32_16x16x32_bf16 v[38:41], v[144:147], v[132:135], v[38:41]
	s_waitcnt lgkmcnt(0)
	v_mfma_f32_16x16x32_bf16 v[26:29], v[124:127], v[136:139], v[26:29]
	v_mfma_f32_16x16x32_bf16 v[22:25], v[128:131], v[136:139], v[22:25]
	v_mfma_f32_16x16x32_bf16 v[18:21], v[140:143], v[136:139], v[18:21]
	v_mfma_f32_16x16x32_bf16 v[2:5], v[144:147], v[136:139], v[2:5]
	s_cbranch_vccnz .LBB0_859
	s_add_i32 s9, s31, 0x8000
	s_mov_b64 s[18:19], 0

.LBB0_861:
	s_waitcnt vmcnt(7)
	v_lshl_add_u64 v[70:71], s[14:15], 1, v[100:101]
	s_waitcnt vmcnt(6)
	v_add_co_u32_e32 v66, vcc, 0x8000, v70
	s_nop 1
	v_addc_co_u32_e32 v67, vcc, 0, v71, vcc
	v_add_co_u32_e32 v72, vcc, 0x10000, v70
	s_barrier
	s_nop 0
	v_addc_co_u32_e32 v73, vcc, 0, v71, vcc
	s_waitcnt vmcnt(4)
	v_add_co_u32_e32 v78, vcc, 0x18000, v70
	s_nop 1
	v_addc_co_u32_e32 v79, vcc, 0, v71, vcc
	s_waitcnt vmcnt(2)
	v_add_co_u32_e32 v86, vcc, 0x10000, v112
	s_add_u32 m0, s98, 0x1000
	v_lshl_add_u64 v[66:67], v[66:67], 0, v[238:239]
	global_load_lds_dwordx4 v[66:67], off
	s_nop 0
	s_add_u32 m0, s98, 0x2000
	v_lshl_add_u64 v[74:75], v[72:73], 0, v[238:239]
	global_load_lds_dwordx4 v[74:75], off
	v_addc_co_u32_e32 v87, vcc, 0, v113, vcc
	v_add_co_u32_e32 v90, vcc, 0x20000, v112
	s_mov_b32 m0, s98
	v_lshl_add_u64 v[70:71], v[70:71], 0, v[238:239]
	global_load_lds_dwordx4 v[70:71], off
	s_nop 0
	s_add_u32 m0, s98, 0x4000
	v_lshl_add_u64 v[82:83], v[112:113], 0, v[240:241]
	global_load_lds_dwordx4 v[82:83], off
	v_addc_co_u32_e32 v91, vcc, 0, v113, vcc
	v_add_co_u32_e32 v94, vcc, 0x30000, v112
	s_add_u32 m0, s98, 0x3000
	v_lshl_add_u64 v[78:79], v[78:79], 0, v[238:239]
	global_load_lds_dwordx4 v[78:79], off
	s_nop 0
	s_add_u32 m0, s98, 0x5000
	v_lshl_add_u64 v[86:87], v[86:87], 0, v[240:241]
	global_load_lds_dwordx4 v[86:87], off
	v_addc_co_u32_e32 v95, vcc, 0, v113, vcc
	s_add_u32 m0, s98, 0x6000
	v_lshl_add_u64 v[90:91], v[90:91], 0, v[240:241]
	global_load_lds_dwordx4 v[90:91], off
	s_nop 0
	s_add_u32 m0, s98, 0x7000
	v_lshl_add_u64 v[94:95], v[94:95], 0, v[240:241]
	global_load_lds_dwordx4 v[94:95], off
	s_mov_b32 s9, 0
	s_mov_b64 s[12:13], 0
	s_mov_b32 s11, 0
	s_waitcnt lgkmcnt(0)
	s_add_u32 m0, s98, 0x8000
	v_lshl_add_u64 v[70:71], v[70:71], 0, v[242:243]
	global_load_lds_dwordx4 v[70:71], off
	s_add_u32 m0, s98, 0x9000
	v_lshl_add_u64 v[66:67], v[66:67], 0, v[242:243]
	global_load_lds_dwordx4 v[66:67], off
	s_add_u32 m0, s98, 0xa000
	v_lshl_add_u64 v[74:75], v[74:75], 0, v[242:243]
	global_load_lds_dwordx4 v[74:75], off
	s_add_u32 m0, s98, 0xb000
	v_lshl_add_u64 v[78:79], v[78:79], 0, v[242:243]
	global_load_lds_dwordx4 v[78:79], off
	s_mov_b32 s100, 0
	s_mov_b32 s101, 0x4000
	s_waitcnt vmcnt(4)
	s_barrier
	s_branch .LBB0_863

.Ldqx_5:
	s_cmpk_lg_i32 s12, 0x400
	s_mov_b32 s9, s14
	s_waitcnt lgkmcnt(0)
	s_barrier
	s_cbranch_scc0 .LBB0_869

.LBB0_865:
	v_add_u32_e32 v112, s100, v115
	v_add3_u32 v113, v112, v118, s101
	ds_read_b128 v[124:127], v113
	v_add_u32_e32 v112, v112, v117
	ds_read_b128 v[128:131], v113 offset:2048
	ds_read_b128 v[132:135], v112
	ds_read_b128 v[136:139], v112 offset:2048
	ds_read_b128 v[140:143], v113 offset:4096
	ds_read_b128 v[144:147], v113 offset:6144
	s_waitcnt lgkmcnt(3)
	v_mfma_f32_16x16x32_bf16 v[58:61], v[128:131], v[132:135], v[58:61]
	s_andn2_b64 vcc, exec, s[14:15]
	v_mfma_f32_16x16x32_bf16 v[46:49], v[124:127], v[132:135], v[46:49]
	s_waitcnt lgkmcnt(1)
	v_mfma_f32_16x16x32_bf16 v[62:65], v[140:143], v[132:135], v[62:65]
	s_cbranch_vccz .Ldq_5_0
	s_add_u32 s99, s100, 0xc000
	s_cmp_lt_u32 s99, 0x14000
	s_cbranch_scc1 .Ldqw_5_0
	s_sub_u32 s99, s99, 0x14000

.Ldq_5_3:
	v_add_u32_e32 v112, v112, v117
	s_mov_b64 s[16:17], -1
	v_mfma_f32_16x16x32_bf16 v[30:33], v[128:131], v[132:135], v[30:33]
	v_mfma_f32_16x16x32_bf16 v[34:37], v[140:143], v[132:135], v[34:37]
	s_cmp_gt_u32 s11, 5
	s_cbranch_scc1 .Ldq_5_4
	s_add_u32 s99, s100, 0x10000
	s_cmp_lt_u32 s99, 0x14000
	s_cbranch_scc1 .Ldqw_5_4
	s_sub_u32 s99, s99, 0x14000

.Ldq_5_4:
	v_mfma_f32_16x16x32_bf16 v[38:41], v[144:147], v[132:135], v[38:41]
	s_waitcnt lgkmcnt(0)
	v_mfma_f32_16x16x32_bf16 v[26:29], v[124:127], v[136:139], v[26:29]
	s_cmp_gt_u32 s11, 5
	s_cbranch_scc1 .Ldq_5_5
	s_add_u32 m0, s99, 0x1000
	v_lshl_add_u64 v[66:67], v[66:67], 0, v[242:243]
	global_load_lds_dwordx4 v[66:67], off
.Ldq_5_5:
	ds_read_b128 v[124:127], v113
	v_mfma_f32_16x16x32_bf16 v[22:25], v[128:131], v[136:139], v[22:25]
	v_mfma_f32_16x16x32_bf16 v[18:21], v[140:143], v[136:139], v[18:21]
	s_cmp_gt_u32 s11, 5
	s_cbranch_scc1 .Ldq_5_6
	s_add_u32 m0, s99, 0x2000
	v_lshl_add_u64 v[74:75], v[74:75], 0, v[242:243]
	global_load_lds_dwordx4 v[74:75], off
.Ldq_5_6:
	v_mfma_f32_16x16x32_bf16 v[2:5], v[144:147], v[136:139], v[2:5]
	ds_read_b128 v[128:131], v113 offset:2048
	ds_read_b128 v[132:135], v112
	ds_read_b128 v[136:139], v112 offset:2048
	ds_read_b128 v[140:143], v113 offset:4096
	ds_read_b128 v[144:147], v113 offset:6144
	s_waitcnt lgkmcnt(3)
	v_mfma_f32_16x16x32_bf16 v[46:49], v[124:127], v[132:135], v[46:49]
	s_cmp_gt_u32 s11, 5
	s_cbranch_scc1 .Ldq_5_7
	s_add_u32 m0, s99, 0x3000
	v_lshl_add_u64 v[78:79], v[78:79], 0, v[242:243]
	global_load_lds_dwordx4 v[78:79], off
.Ldq_5_7:
	v_mfma_f32_16x16x32_bf16 v[58:61], v[128:131], v[132:135], v[58:61]
	s_waitcnt lgkmcnt(1)
	v_mfma_f32_16x16x32_bf16 v[62:65], v[140:143], v[132:135], v[62:65]
	s_waitcnt lgkmcnt(0)
	v_mfma_f32_16x16x32_bf16 v[54:57], v[144:147], v[132:135], v[54:57]
	v_mfma_f32_16x16x32_bf16 v[14:17], v[124:127], v[136:139], v[14:17]
	v_mfma_f32_16x16x32_bf16 v[6:9], v[128:131], v[136:139], v[6:9]
	v_mfma_f32_16x16x32_bf16 v[10:13], v[140:143], v[136:139], v[10:13]
	v_mfma_f32_16x16x32_bf16 v[50:53], v[144:147], v[136:139], v[50:53]
	ds_read_b128 v[132:135], v112 offset:4096
	ds_read_b128 v[136:139], v112 offset:6144
	s_waitcnt lgkmcnt(1)
	v_mfma_f32_16x16x32_bf16 v[42:45], v[124:127], v[132:135], v[42:45]
	v_mfma_f32_16x16x32_bf16 v[30:33], v[128:131], v[132:135], v[30:33]
	v_mfma_f32_16x16x32_bf16 v[34:37], v[140:143], v[132:135], v[34:37]
	v_mfma_f32_16x16x32_bf16 v[38:41], v[144:147], v[132:135], v[38:41]
	s_waitcnt lgkmcnt(0)
	v_mfma_f32_16x16x32_bf16 v[26:29], v[124:127], v[136:139], v[26:29]
	v_mfma_f32_16x16x32_bf16 v[22:25], v[128:131], v[136:139], v[22:25]
	v_mfma_f32_16x16x32_bf16 v[18:21], v[140:143], v[136:139], v[18:21]
	v_mfma_f32_16x16x32_bf16 v[2:5], v[144:147], v[136:139], v[2:5]
	s_cbranch_vccnz .LBB0_867
	s_add_i32 s14, s9, 0x8000
	s_mov_b64 s[16:17], 0

.LBB0_884:
	s_lshl_b32 s5, s59, 6
	s_lshl_b32 s4, s12, 7
	s_and_b32 s5, s5, 64
	s_or_b32 s4, s4, s5
	s_ashr_i32 s5, s4, 31
	s_lshl_b32 s10, s11, 7
	s_lshl_b64 s[12:13], s[4:5], 9
	s_lshl_b64 s[14:15], s[4:5], 10
	s_add_u32 s18, s54, s14
	s_addc_u32 s19, s55, s15
	s_ashr_i32 s11, s10, 31
	s_lshl_b64 s[16:17], s[10:11], 11
	v_lshrrev_b32_e32 v12, 3, v0
	v_lshlrev_b32_e32 v6, 3, v0
	s_add_u32 s24, s54, s16
	s_waitcnt lgkmcnt(0)
	v_mov_b32_e32 v3, 0
	v_lshlrev_b32_e32 v2, 10, v12
	s_waitcnt vmcnt(51)
	v_and_b32_e32 v62, 56, v6
	s_addc_u32 s25, s55, s17
	v_lshl_add_u64 v[4:5], s[18:19], 0, v[2:3]
	v_lshlrev_b32_e32 v6, 1, v62
	v_mov_b32_e32 v7, v3
	v_lshlrev_b32_e32 v8, 11, v12
	v_mov_b32_e32 v9, v3
	v_lshl_add_u64 v[4:5], v[4:5], 0, v[6:7]
	v_lshl_add_u64 v[10:11], s[24:25], 0, v[8:9]
	s_mov_b32 s5, 0xd580000
	v_lshl_add_u64 v[6:7], v[10:11], 0, v[6:7]
	v_add_co_u32_e32 v10, vcc, s5, v4
	s_mov_b32 s5, 0xd588000
	s_nop 0
	v_addc_co_u32_e32 v11, vcc, 0, v5, vcc
	v_add_co_u32_e32 v4, vcc, s5, v4
	s_mov_b32 s5, 0xee00000
	s_nop 0
	v_addc_co_u32_e32 v5, vcc, 0, v5, vcc
	s_barrier
	s_mov_b32 m0, s98
	v_lshl_add_u64 v[34:35], v[10:11], 0, v[238:239]
	global_load_lds_dwordx4 v[34:35], off
	s_add_u32 m0, s98, 0x1000
	v_lshl_add_u64 v[38:39], v[4:5], 0, v[238:239]
	global_load_lds_dwordx4 v[38:39], off
	v_add_co_u32_e32 v4, vcc, s5, v6
	s_mov_b32 s5, 0xee10000
	s_nop 0
	v_addc_co_u32_e32 v5, vcc, 0, v7, vcc
	v_add_co_u32_e32 v10, vcc, s5, v6
	s_mov_b32 s5, 0xee20000
	s_nop 0
	v_addc_co_u32_e32 v11, vcc, 0, v7, vcc
	s_add_u32 m0, s98, 0x4000
	v_lshl_add_u64 v[42:43], v[4:5], 0, v[238:239]
	global_load_lds_dwordx4 v[42:43], off
	s_add_u32 m0, s98, 0x5000
	v_lshl_add_u64 v[46:47], v[10:11], 0, v[238:239]
	global_load_lds_dwordx4 v[46:47], off
	v_add_co_u32_e32 v4, vcc, s5, v6
	s_mov_b32 s5, 0xee30000
	s_nop 0
	v_addc_co_u32_e32 v5, vcc, 0, v7, vcc
	v_add_co_u32_e32 v10, vcc, s5, v6
	v_and_b32_e32 v9, 7, v0
	s_nop 0
	v_addc_co_u32_e32 v11, vcc, 0, v7, vcc
	s_add_u32 m0, s98, 0x6000
	v_lshl_add_u64 v[50:51], v[4:5], 0, v[238:239]
	global_load_lds_dwordx4 v[50:51], off
	s_add_u32 m0, s98, 0x7000
	v_lshl_add_u64 v[54:55], v[10:11], 0, v[238:239]
	global_load_lds_dwordx4 v[54:55], off
	v_lshrrev_b32_e32 v4, 4, v0
	v_bitop3_b32 v4, v4, v9, 3 bitop3:0x6c
	v_bfe_u32 v5, v0, 4, 2
	s_mov_b64 s[18:19], 0xee00000
	v_lshlrev_b32_e32 v68, 4, v4
	v_lshlrev_b32_e32 v4, 7, v0
	v_lshrrev_b32_e32 v10, 2, v0
	v_lshl_add_u64 v[64:65], v[6:7], 0, s[18:19]
	v_and_b32_e32 v71, 0x2780, v4
	v_bitop3_b32 v4, v5, v9, 4 bitop3:0x36
	v_lshlrev_b32_e32 v6, 4, v9
	v_lshlrev_b32_e32 v66, 9, v12
	v_lshlrev_b32_e32 v11, 7, v12
	v_xor_b32_e32 v12, v12, v0
	v_and_b32_e32 v63, 32, v10
	v_lshlrev_b32_e32 v72, 4, v4
	v_or3_b32 v4, s14, v2, v6
	v_mov_b32_e32 v5, s15
	s_movk_i32 s11, 0x70
	v_lshlrev_b32_e32 v10, 4, v12
	v_and_or_b32 v67, v0, 15, v63
	v_lshl_add_u64 v[58:59], s[54:55], 0, v[4:5]
	v_or3_b32 v4, s16, v8, v6
	v_mov_b32_e32 v5, s17
	s_mov_b32 s5, 0
	v_and_or_b32 v69, v10, s11, v11
	v_lshlrev_b32_e32 v70, 7, v67
	v_lshl_add_u64 v[60:61], s[54:55], 0, v[4:5]
	s_mov_b64 s[14:15], 0
	s_mov_b32 s11, 0
	v_mov_b32_e32 v2, v3
	v_mov_b32_e32 v4, v3
	v_mov_b32_e32 v5, v3
	v_mov_b32_e32 v22, v3
	v_mov_b32_e32 v23, v3
	v_mov_b32_e32 v24, v3
	v_mov_b32_e32 v25, v3
	v_mov_b32_e32 v26, v3
	v_mov_b32_e32 v27, v3
	v_mov_b32_e32 v28, v3
	v_mov_b32_e32 v29, v3
	v_mov_b32_e32 v30, v3
	v_mov_b32_e32 v31, v3
	v_mov_b32_e32 v32, v3
	v_mov_b32_e32 v33, v3
	v_mov_b32_e32 v14, v3
	v_mov_b32_e32 v15, v3
	v_mov_b32_e32 v16, v3
	v_mov_b32_e32 v17, v3
	v_mov_b32_e32 v18, v3
	v_mov_b32_e32 v19, v3
	v_mov_b32_e32 v20, v3
	v_mov_b32_e32 v21, v3
	v_mov_b32_e32 v10, v3
	v_mov_b32_e32 v11, v3
	v_mov_b32_e32 v12, v3
	v_mov_b32_e32 v13, v3
	v_mov_b32_e32 v6, v3
	v_mov_b32_e32 v7, v3
	v_mov_b32_e32 v8, v3
	v_mov_b32_e32 v9, v3
	s_waitcnt lgkmcnt(0)
	s_add_u32 m0, s98, 0x8000
	v_lshl_add_u64 v[34:35], v[34:35], 0, v[242:243]
	global_load_lds_dwordx4 v[34:35], off
	s_add_u32 m0, s98, 0x9000
	v_lshl_add_u64 v[38:39], v[38:39], 0, v[242:243]
	global_load_lds_dwordx4 v[38:39], off
	s_mov_b32 s100, 0
	s_mov_b32 s101, 0x4000
	s_waitcnt vmcnt(2)
	s_barrier
	s_branch .LBB0_886
.LBB0_885:
	s_add_u32 s14, s14, 0x80
	s_addc_u32 s15, s15, 0
	s_add_i32 s11, s11, 1
	s_add_u32 s100, s100, 0x8000
	s_cmp_lt_u32 s100, 0x14000
	s_cbranch_scc1 .Ldqr_6
	s_sub_u32 s100, s100, 0x14000

.Ldqx_6:
	s_cmpk_lg_i32 s14, 0x400
	s_mov_b32 s5, s16
	s_waitcnt lgkmcnt(0)
	s_barrier
	s_cbranch_scc0 .LBB0_892

.LBB0_888:
	v_add_u32_e32 v73, s100, v68
	v_add3_u32 v94, v73, v71, s101
	ds_read_b128 v[74:77], v94
	v_add_u32_e32 v73, v73, v70
	ds_read_b128 v[78:81], v94 offset:2048
	ds_read_b128 v[82:85], v73
	ds_read_b128 v[86:89], v73 offset:2048
	v_add_u32_e32 v73, s100, v72
	v_add3_u32 v98, v73, v71, s101
	ds_read_b128 v[90:93], v94 offset:4096
	s_waitcnt lgkmcnt(2)
	v_mfma_f32_16x16x32_bf16 v[22:25], v[78:81], v[82:85], v[22:25]
	v_add_u32_e32 v73, v73, v70
	s_mov_b64 s[18:19], -1
	s_andn2_b64 vcc, exec, s[16:17]
	v_mfma_f32_16x16x32_bf16 v[2:5], v[74:77], v[82:85], v[2:5]
	s_waitcnt lgkmcnt(1)
	v_mfma_f32_16x16x32_bf16 v[14:17], v[74:77], v[86:89], v[14:17]
	s_cbranch_vccz .Ldq_6_0
	s_add_u32 s99, s100, 0xc000
	s_cmp_lt_u32 s99, 0x14000
	s_cbranch_scc1 .Ldqw_6_0
	s_sub_u32 s99, s99, 0x14000

.Ldq_6_0:
	ds_read_b128 v[74:77], v98
	ds_read_b128 v[94:97], v94 offset:6144
	s_waitcnt lgkmcnt(2)
	v_mfma_f32_16x16x32_bf16 v[26:29], v[90:93], v[82:85], v[26:29]
	s_waitcnt lgkmcnt(0)
	v_mfma_f32_16x16x32_bf16 v[30:33], v[94:97], v[82:85], v[30:33]
	s_cbranch_vccz .Ldq_6_1
	s_add_u32 m0, s99, 0x1000
	v_lshl_add_u64 v[46:47], v[46:47], 0, v[242:243]
	global_load_lds_dwordx4 v[46:47], off
.Ldq_6_1:
	v_mfma_f32_16x16x32_bf16 v[18:21], v[78:81], v[86:89], v[18:21]
	v_mfma_f32_16x16x32_bf16 v[10:13], v[90:93], v[86:89], v[10:13]
	s_cbranch_vccz .Ldq_6_2
	s_add_u32 m0, s99, 0x2000
	v_lshl_add_u64 v[50:51], v[50:51], 0, v[242:243]
	global_load_lds_dwordx4 v[50:51], off
.Ldq_6_2:
	v_mfma_f32_16x16x32_bf16 v[6:9], v[94:97], v[86:89], v[6:9]
	ds_read_b128 v[78:81], v98 offset:2048
	ds_read_b128 v[82:85], v73
	ds_read_b128 v[86:89], v73 offset:2048
	ds_read_b128 v[90:93], v98 offset:4096
	ds_read_b128 v[94:97], v98 offset:6144
	s_waitcnt lgkmcnt(3)
	v_mfma_f32_16x16x32_bf16 v[2:5], v[74:77], v[82:85], v[2:5]
	s_cbranch_vccz .Ldq_6_3
	s_add_u32 m0, s99, 0x3000
	v_lshl_add_u64 v[54:55], v[54:55], 0, v[242:243]
	global_load_lds_dwordx4 v[54:55], off
.Ldq_6_3:
	v_mfma_f32_16x16x32_bf16 v[22:25], v[78:81], v[82:85], v[22:25]
	s_waitcnt lgkmcnt(1)
	v_mfma_f32_16x16x32_bf16 v[26:29], v[90:93], v[82:85], v[26:29]
	s_cmp_gt_u32 s11, 5
	s_cbranch_scc1 .Ldq_6_4
	s_add_u32 s99, s100, 0x10000
	s_cmp_lt_u32 s99, 0x14000
	s_cbranch_scc1 .Ldqw_6_4
	s_sub_u32 s99, s99, 0x14000

.Ldq_6_4:
	s_waitcnt lgkmcnt(0)
	v_mfma_f32_16x16x32_bf16 v[30:33], v[94:97], v[82:85], v[30:33]
	v_mfma_f32_16x16x32_bf16 v[14:17], v[74:77], v[86:89], v[14:17]
	s_cmp_gt_u32 s11, 5
	s_cbranch_scc1 .Ldq_6_5
	s_add_u32 m0, s99, 0x1000
	v_lshl_add_u64 v[38:39], v[38:39], 0, v[242:243]
	global_load_lds_dwordx4 v[38:39], off
.Ldq_6_5:
	v_mfma_f32_16x16x32_bf16 v[18:21], v[78:81], v[86:89], v[18:21]
	v_mfma_f32_16x16x32_bf16 v[10:13], v[90:93], v[86:89], v[10:13]
	v_mfma_f32_16x16x32_bf16 v[6:9], v[94:97], v[86:89], v[6:9]
	s_cbranch_vccnz .LBB0_890
	s_add_i32 s16, s5, 0x8000
	s_mov_b64 s[18:19], 0

.LBB0_892:
	s_lshl_b64 s[12:13], s[12:13], 1
	s_add_u32 s12, s6, s12
	s_addc_u32 s13, s7, s13
	s_waitcnt vmcnt(5)
	v_lshlrev_b32_e32 v34, 1, v66
	v_mov_b32_e32 v35, 0
	v_lshl_add_u64 v[36:37], s[12:13], 0, v[34:35]
	v_lshlrev_b32_e32 v34, 1, v62
	s_waitcnt vmcnt(4)
	v_lshl_add_u64 v[38:39], v[36:37], 0, v[34:35]
	s_waitcnt vmcnt(1)
	v_add_co_u32_e32 v50, vcc, 0x8000, v38
	s_nop 1
	v_addc_co_u32_e32 v51, vcc, 0, v39, vcc
	v_add_co_u32_e32 v52, vcc, 0x10000, v64
	s_barrier
	s_nop 0
	v_addc_co_u32_e32 v53, vcc, 0, v65, vcc
	v_add_co_u32_e32 v74, vcc, 0x20000, v64
	s_nop 1
	v_addc_co_u32_e32 v75, vcc, 0, v65, vcc
	s_mov_b32 m0, s98
	v_lshl_add_u64 v[34:35], v[38:39], 0, v[238:239]
	global_load_lds_dwordx4 v[34:35], off
	s_add_u32 m0, s98, 0x4000
	v_lshl_add_u64 v[42:43], v[64:65], 0, v[240:241]
	global_load_lds_dwordx4 v[42:43], off
	v_add_co_u32_e32 v64, vcc, 0x30000, v64
	s_add_u32 m0, s98, 0x1000
	v_lshl_add_u64 v[38:39], v[50:51], 0, v[238:239]
	global_load_lds_dwordx4 v[38:39], off
	s_add_u32 m0, s98, 0x5000
	v_lshl_add_u64 v[46:47], v[52:53], 0, v[240:241]
	global_load_lds_dwordx4 v[46:47], off
	v_addc_co_u32_e32 v65, vcc, 0, v65, vcc
	s_add_u32 m0, s98, 0x6000
	v_lshl_add_u64 v[50:51], v[74:75], 0, v[240:241]
	global_load_lds_dwordx4 v[50:51], off
	s_add_u32 m0, s98, 0x7000
	v_lshl_add_u64 v[54:55], v[64:65], 0, v[240:241]
	global_load_lds_dwordx4 v[54:55], off
	s_mov_b32 s5, 0
	s_mov_b64 s[12:13], 0
	s_mov_b32 s11, 0
	s_waitcnt lgkmcnt(0)
	s_add_u32 m0, s98, 0x8000
	v_lshl_add_u64 v[34:35], v[34:35], 0, v[242:243]
	global_load_lds_dwordx4 v[34:35], off
	s_add_u32 m0, s98, 0x9000
	v_lshl_add_u64 v[38:39], v[38:39], 0, v[242:243]
	global_load_lds_dwordx4 v[38:39], off
	s_mov_b32 s100, 0
	s_mov_b32 s101, 0x4000
	s_waitcnt vmcnt(2)
	s_barrier
	s_branch .LBB0_894

.Ldqx_7:
	s_cmpk_lg_i32 s12, 0x400
	s_mov_b32 s5, s14
	s_waitcnt lgkmcnt(0)
	s_barrier
	s_cbranch_scc0 .LBB0_900

.LBB0_896:
	v_add_u32_e32 v62, s100, v68
	v_add3_u32 v64, v62, v71, s101
	ds_read_b128 v[74:77], v64
	v_add_u32_e32 v62, v62, v70
	ds_read_b128 v[78:81], v64 offset:2048
	ds_read_b128 v[82:85], v62
	ds_read_b128 v[86:89], v62 offset:2048
	ds_read_b128 v[90:93], v64 offset:4096
	ds_read_b128 v[94:97], v64 offset:6144
	v_add_u32_e32 v62, s100, v72
	v_add3_u32 v64, v62, v71, s101
	s_waitcnt lgkmcnt(3)
	v_mfma_f32_16x16x32_bf16 v[22:25], v[78:81], v[82:85], v[22:25]
	v_add_u32_e32 v62, v62, v70
	s_mov_b64 s[16:17], -1
	s_andn2_b64 vcc, exec, s[14:15]
	v_mfma_f32_16x16x32_bf16 v[2:5], v[74:77], v[82:85], v[2:5]
	s_waitcnt lgkmcnt(1)
	v_mfma_f32_16x16x32_bf16 v[26:29], v[90:93], v[82:85], v[26:29]
	s_cbranch_vccz .Ldq_7_0
	s_add_u32 s99, s100, 0xc000
	s_cmp_lt_u32 s99, 0x14000
	s_cbranch_scc1 .Ldqw_7_0
	s_sub_u32 s99, s99, 0x14000

.Ldq_7_0:
	s_waitcnt lgkmcnt(0)
	v_mfma_f32_16x16x32_bf16 v[30:33], v[94:97], v[82:85], v[30:33]
	v_mfma_f32_16x16x32_bf16 v[14:17], v[74:77], v[86:89], v[14:17]
	s_cbranch_vccz .Ldq_7_1
	s_add_u32 m0, s99, 0x1000
	v_lshl_add_u64 v[46:47], v[46:47], 0, v[242:243]
	global_load_lds_dwordx4 v[46:47], off
.Ldq_7_1:
	ds_read_b128 v[74:77], v64
	v_mfma_f32_16x16x32_bf16 v[18:21], v[78:81], v[86:89], v[18:21]
	v_mfma_f32_16x16x32_bf16 v[10:13], v[90:93], v[86:89], v[10:13]
	s_cbranch_vccz .Ldq_7_2
	s_add_u32 m0, s99, 0x2000
	v_lshl_add_u64 v[50:51], v[50:51], 0, v[242:243]
	global_load_lds_dwordx4 v[50:51], off
.Ldq_7_2:
	v_mfma_f32_16x16x32_bf16 v[6:9], v[94:97], v[86:89], v[6:9]
	ds_read_b128 v[78:81], v64 offset:2048
	ds_read_b128 v[82:85], v62
	ds_read_b128 v[86:89], v62 offset:2048
	ds_read_b128 v[90:93], v64 offset:4096
	ds_read_b128 v[94:97], v64 offset:6144
	s_waitcnt lgkmcnt(3)
	v_mfma_f32_16x16x32_bf16 v[2:5], v[74:77], v[82:85], v[2:5]
	s_cbranch_vccz .Ldq_7_3
	s_add_u32 m0, s99, 0x3000
	v_lshl_add_u64 v[54:55], v[54:55], 0, v[242:243]
	global_load_lds_dwordx4 v[54:55], off

.Ldq_7_5:
	v_mfma_f32_16x16x32_bf16 v[18:21], v[78:81], v[86:89], v[18:21]
	v_mfma_f32_16x16x32_bf16 v[10:13], v[90:93], v[86:89], v[10:13]
	v_mfma_f32_16x16x32_bf16 v[6:9], v[94:97], v[86:89], v[6:9]
	s_cbranch_vccnz .LBB0_898
	s_add_i32 s14, s5, 0x8000
	s_mov_b64 s[16:17], 0

.LBB0_913:
	s_lshl_b32 s6, s9, 7
	s_ashr_i32 s7, s6, 31
	s_lshl_b64 s[16:17], s[6:7], 10
	s_waitcnt lgkmcnt(0)
	v_lshl_add_u64 v[2:3], v[98:99], 0, s[16:17]
	v_add_co_u32_e32 v4, vcc, s20, v2
	s_lshl_b32 s8, s8, 7
	s_nop 0
	v_addc_co_u32_e32 v5, vcc, 0, v3, vcc
	v_add_co_u32_e32 v6, vcc, s21, v2
	s_ashr_i32 s9, s8, 31
	s_nop 0
	v_addc_co_u32_e32 v7, vcc, 0, v3, vcc
	s_lshl_b64 s[14:15], s[8:9], 11
	s_barrier
	s_add_u32 m0, s98, 0x1000
	v_lshl_add_u64 v[66:67], v[4:5], 0, v[238:239]
	global_load_lds_dwordx4 v[66:67], off
	s_add_u32 m0, s98, 0x2000
	v_lshl_add_u64 v[74:75], v[6:7], 0, v[238:239]
	global_load_lds_dwordx4 v[74:75], off
	v_add_co_u32_e32 v4, vcc, s22, v2
	v_lshl_add_u64 v[112:113], v[102:103], 0, s[14:15]
	s_nop 0
	v_addc_co_u32_e32 v5, vcc, 0, v3, vcc
	s_mov_b32 m0, s98
	v_lshl_add_u64 v[70:71], v[2:3], 0, v[238:239]
	global_load_lds_dwordx4 v[70:71], off
	s_add_u32 m0, s98, 0x4000
	v_lshl_add_u64 v[82:83], v[112:113], 0, v[238:239]
	global_load_lds_dwordx4 v[82:83], off
	v_add_co_u32_e32 v2, vcc, s21, v112
	v_mov_b32_e32 v46, 0
	s_nop 0
	v_addc_co_u32_e32 v3, vcc, 0, v113, vcc
	s_add_u32 m0, s98, 0x3000
	v_lshl_add_u64 v[78:79], v[4:5], 0, v[238:239]
	global_load_lds_dwordx4 v[78:79], off
	s_add_u32 m0, s98, 0x5000
	v_lshl_add_u64 v[86:87], v[2:3], 0, v[238:239]
	global_load_lds_dwordx4 v[86:87], off
	v_add_co_u32_e32 v2, vcc, s23, v112
	s_mov_b32 s27, 0
	s_nop 0
	v_addc_co_u32_e32 v3, vcc, 0, v113, vcc
	v_add_co_u32_e32 v4, vcc, s24, v112
	s_mov_b64 s[10:11], 0
	s_nop 0
	v_addc_co_u32_e32 v5, vcc, 0, v113, vcc
	s_add_u32 m0, s98, 0x6000
	v_lshl_add_u64 v[90:91], v[2:3], 0, v[238:239]
	global_load_lds_dwordx4 v[90:91], off
	s_add_u32 m0, s98, 0x7000
	v_lshl_add_u64 v[94:95], v[4:5], 0, v[238:239]
	global_load_lds_dwordx4 v[94:95], off
	s_mov_b32 s9, 0
	v_mov_b32_e32 v47, v46
	v_mov_b32_e32 v48, v46
	v_mov_b32_e32 v49, v46
	v_mov_b32_e32 v58, v46
	v_mov_b32_e32 v59, v46
	v_mov_b32_e32 v60, v46
	v_mov_b32_e32 v61, v46
	v_mov_b32_e32 v62, v46
	v_mov_b32_e32 v63, v46
	v_mov_b32_e32 v64, v46
	v_mov_b32_e32 v65, v46
	v_mov_b32_e32 v54, v46
	v_mov_b32_e32 v55, v46
	v_mov_b32_e32 v56, v46
	v_mov_b32_e32 v57, v46
	v_mov_b32_e32 v14, v46
	v_mov_b32_e32 v15, v46
	v_mov_b32_e32 v16, v46
	v_mov_b32_e32 v17, v46
	v_mov_b32_e32 v6, v46
	v_mov_b32_e32 v7, v46
	v_mov_b32_e32 v8, v46
	v_mov_b32_e32 v9, v46
	v_mov_b32_e32 v10, v46
	v_mov_b32_e32 v11, v46
	s_lshl_b64 s[12:13], s[6:7], 9
	v_lshl_add_u64 v[108:109], v[104:105], 0, s[16:17]
	v_lshl_add_u64 v[110:111], v[106:107], 0, s[14:15]
	v_mov_b32_e32 v12, v46
	v_mov_b32_e32 v13, v46
	v_mov_b32_e32 v50, v46
	v_mov_b32_e32 v51, v46
	v_mov_b32_e32 v52, v46
	v_mov_b32_e32 v53, v46
	v_mov_b32_e32 v42, v46
	v_mov_b32_e32 v43, v46
	v_mov_b32_e32 v44, v46
	v_mov_b32_e32 v45, v46
	v_mov_b32_e32 v30, v46
	v_mov_b32_e32 v31, v46
	v_mov_b32_e32 v32, v46
	v_mov_b32_e32 v33, v46
	v_mov_b32_e32 v34, v46
	v_mov_b32_e32 v35, v46
	v_mov_b32_e32 v36, v46
	v_mov_b32_e32 v37, v46
	v_mov_b32_e32 v38, v46
	v_mov_b32_e32 v39, v46
	v_mov_b32_e32 v40, v46
	v_mov_b32_e32 v41, v46
	v_mov_b32_e32 v26, v46
	v_mov_b32_e32 v27, v46
	v_mov_b32_e32 v28, v46
	v_mov_b32_e32 v29, v46
	v_mov_b32_e32 v22, v46
	v_mov_b32_e32 v23, v46
	v_mov_b32_e32 v24, v46
	v_mov_b32_e32 v25, v46
	v_mov_b32_e32 v18, v46
	v_mov_b32_e32 v19, v46
	v_mov_b32_e32 v20, v46
	v_mov_b32_e32 v21, v46
	v_mov_b32_e32 v2, v46
	v_mov_b32_e32 v3, v46
	v_mov_b32_e32 v4, v46
	v_mov_b32_e32 v5, v46
	s_waitcnt lgkmcnt(0)
	s_add_u32 m0, s98, 0x8000
	v_lshl_add_u64 v[70:71], v[70:71], 0, v[242:243]
	global_load_lds_dwordx4 v[70:71], off
	s_add_u32 m0, s98, 0x9000
	v_lshl_add_u64 v[66:67], v[66:67], 0, v[242:243]
	global_load_lds_dwordx4 v[66:67], off
	s_add_u32 m0, s98, 0xa000
	v_lshl_add_u64 v[74:75], v[74:75], 0, v[242:243]
	global_load_lds_dwordx4 v[74:75], off
	s_add_u32 m0, s98, 0xb000
	v_lshl_add_u64 v[78:79], v[78:79], 0, v[242:243]
	global_load_lds_dwordx4 v[78:79], off
	s_mov_b32 s100, 0
	s_mov_b32 s101, 0x4000
	s_waitcnt vmcnt(4)
	s_barrier
	s_branch .LBB0_915
.LBB0_914:
	s_add_u32 s10, s10, 0x80
	s_addc_u32 s11, s11, 0
	s_add_i32 s9, s9, 1
	s_add_u32 s100, s100, 0x8000
	s_cmp_lt_u32 s100, 0x14000
	s_cbranch_scc1 .Ldqr_8
	s_sub_u32 s100, s100, 0x14000

.Ldqs_8:
	s_cmp_gt_u32 s9, 6
	s_cbranch_scc1 .Ldqv_8
	s_waitcnt vmcnt(4)
	s_branch .Ldqx_8

.Ldqx_8:
	s_cmpk_lg_i32 s10, 0x400
	s_mov_b32 s27, s7
	s_waitcnt lgkmcnt(0)
	s_barrier
	s_cbranch_scc0 .LBB0_921

.LBB0_917:
	v_add_u32_e32 v128, s100, v115
	v_add3_u32 v144, v128, v118, s101
	ds_read_b128 v[124:127], v144
	v_add_u32_e32 v148, v128, v117
	ds_read_b128 v[128:131], v144 offset:2048
	ds_read_b128 v[132:135], v148
	ds_read_b128 v[136:139], v148 offset:2048
	ds_read_b128 v[140:143], v144 offset:4096
	ds_read_b128 v[144:147], v144 offset:6144
	s_waitcnt lgkmcnt(3)
	v_mfma_f32_16x16x32_bf16 v[58:61], v[128:131], v[132:135], v[58:61]
	s_mov_b64 s[16:17], -1
	s_andn2_b64 vcc, exec, s[14:15]
	v_mfma_f32_16x16x32_bf16 v[46:49], v[124:127], v[132:135], v[46:49]
	s_waitcnt lgkmcnt(1)
	v_mfma_f32_16x16x32_bf16 v[62:65], v[140:143], v[132:135], v[62:65]
	s_cbranch_vccz .Ldq_8_0
	s_add_u32 s99, s100, 0xc000
	s_cmp_lt_u32 s99, 0x14000
	s_cbranch_scc1 .Ldqw_8_0
	s_sub_u32 s99, s99, 0x14000

.Ldq_8_3:
	s_waitcnt lgkmcnt(0)
	v_mfma_f32_16x16x32_bf16 v[22:25], v[128:131], v[136:139], v[22:25]
	v_add_u32_e32 v128, s100, v119
	v_add3_u32 v148, v128, v118, s101
	v_add_u32_e32 v149, v128, v117
	v_mfma_f32_16x16x32_bf16 v[42:45], v[124:127], v[132:135], v[42:45]
	s_cmp_gt_u32 s9, 5
	s_cbranch_scc1 .Ldq_8_4
	s_add_u32 s99, s100, 0x10000
	s_cmp_lt_u32 s99, 0x14000
	s_cbranch_scc1 .Ldqw_8_4
	s_sub_u32 s99, s99, 0x14000

.Ldq_8_4:
	v_mfma_f32_16x16x32_bf16 v[34:37], v[140:143], v[132:135], v[34:37]
	v_mfma_f32_16x16x32_bf16 v[38:41], v[144:147], v[132:135], v[38:41]
	s_cmp_gt_u32 s9, 5
	s_cbranch_scc1 .Ldq_8_5
	s_add_u32 m0, s99, 0x1000
	v_lshl_add_u64 v[66:67], v[66:67], 0, v[242:243]
	global_load_lds_dwordx4 v[66:67], off
.Ldq_8_5:
	v_mfma_f32_16x16x32_bf16 v[26:29], v[124:127], v[136:139], v[26:29]
	ds_read_b128 v[124:127], v148
	v_mfma_f32_16x16x32_bf16 v[18:21], v[140:143], v[136:139], v[18:21]
	s_cmp_gt_u32 s9, 5
	s_cbranch_scc1 .Ldq_8_6
	s_add_u32 m0, s99, 0x2000
	v_lshl_add_u64 v[74:75], v[74:75], 0, v[242:243]
	global_load_lds_dwordx4 v[74:75], off
.Ldq_8_6:
	v_mfma_f32_16x16x32_bf16 v[2:5], v[144:147], v[136:139], v[2:5]
	ds_read_b128 v[128:131], v148 offset:2048
	ds_read_b128 v[132:135], v149
	ds_read_b128 v[136:139], v149 offset:2048
	ds_read_b128 v[140:143], v148 offset:4096
	ds_read_b128 v[144:147], v148 offset:6144
	s_waitcnt lgkmcnt(3)
	v_mfma_f32_16x16x32_bf16 v[46:49], v[124:127], v[132:135], v[46:49]
	s_cmp_gt_u32 s9, 5
	s_cbranch_scc1 .Ldq_8_7
	s_add_u32 m0, s99, 0x3000
	v_lshl_add_u64 v[78:79], v[78:79], 0, v[242:243]
	global_load_lds_dwordx4 v[78:79], off
.Ldq_8_7:
	v_mfma_f32_16x16x32_bf16 v[58:61], v[128:131], v[132:135], v[58:61]
	s_waitcnt lgkmcnt(1)
	v_mfma_f32_16x16x32_bf16 v[62:65], v[140:143], v[132:135], v[62:65]
	s_waitcnt lgkmcnt(0)
	v_mfma_f32_16x16x32_bf16 v[54:57], v[144:147], v[132:135], v[54:57]
	v_mfma_f32_16x16x32_bf16 v[14:17], v[124:127], v[136:139], v[14:17]
	v_mfma_f32_16x16x32_bf16 v[6:9], v[128:131], v[136:139], v[6:9]
	v_mfma_f32_16x16x32_bf16 v[10:13], v[140:143], v[136:139], v[10:13]
	v_mfma_f32_16x16x32_bf16 v[50:53], v[144:147], v[136:139], v[50:53]
	ds_read_b128 v[132:135], v149 offset:4096
	ds_read_b128 v[136:139], v149 offset:6144
	s_waitcnt lgkmcnt(1)
	v_mfma_f32_16x16x32_bf16 v[42:45], v[124:127], v[132:135], v[42:45]
	v_mfma_f32_16x16x32_bf16 v[30:33], v[128:131], v[132:135], v[30:33]
	v_mfma_f32_16x16x32_bf16 v[34:37], v[140:143], v[132:135], v[34:37]
	v_mfma_f32_16x16x32_bf16 v[38:41], v[144:147], v[132:135], v[38:41]
	s_waitcnt lgkmcnt(0)
	v_mfma_f32_16x16x32_bf16 v[26:29], v[124:127], v[136:139], v[26:29]
	v_mfma_f32_16x16x32_bf16 v[22:25], v[128:131], v[136:139], v[22:25]
	v_mfma_f32_16x16x32_bf16 v[18:21], v[140:143], v[136:139], v[18:21]
	v_mfma_f32_16x16x32_bf16 v[2:5], v[144:147], v[136:139], v[2:5]
	s_cbranch_vccnz .LBB0_919
	s_add_i32 s7, s27, 0x8000
	s_mov_b64 s[16:17], 0

.LBB0_921:
	s_waitcnt vmcnt(7)
	v_lshl_add_u64 v[70:71], s[12:13], 1, v[100:101]
	v_add_co_u32_e32 v72, vcc, 0x8000, v70
	s_nop 1
	v_addc_co_u32_e32 v73, vcc, 0, v71, vcc
	s_waitcnt vmcnt(4)
	v_add_co_u32_e32 v78, vcc, 0x10000, v70
	s_barrier
	s_nop 0
	v_addc_co_u32_e32 v79, vcc, 0, v71, vcc
	s_add_u32 m0, s98, 0x1000
	v_lshl_add_u64 v[66:67], v[72:73], 0, v[238:239]
	global_load_lds_dwordx4 v[66:67], off
	s_add_u32 m0, s98, 0x2000
	v_lshl_add_u64 v[74:75], v[78:79], 0, v[238:239]
	global_load_lds_dwordx4 v[74:75], off
	v_add_co_u32_e32 v78, vcc, 0x18000, v70
	s_mov_b32 s7, 0
	s_nop 0
	v_addc_co_u32_e32 v79, vcc, 0, v71, vcc
	v_add_co_u32_e32 v86, vcc, 0x10000, v112
	s_mov_b32 m0, s98
	v_lshl_add_u64 v[70:71], v[70:71], 0, v[238:239]
	global_load_lds_dwordx4 v[70:71], off
	s_nop 0
	s_add_u32 m0, s98, 0x4000
	v_lshl_add_u64 v[82:83], v[112:113], 0, v[240:241]
	global_load_lds_dwordx4 v[82:83], off
	v_addc_co_u32_e32 v87, vcc, 0, v113, vcc
	v_add_co_u32_e32 v90, vcc, 0x20000, v112
	s_add_u32 m0, s98, 0x3000
	v_lshl_add_u64 v[78:79], v[78:79], 0, v[238:239]
	global_load_lds_dwordx4 v[78:79], off
	s_nop 0
	s_add_u32 m0, s98, 0x5000
	v_lshl_add_u64 v[86:87], v[86:87], 0, v[240:241]
	global_load_lds_dwordx4 v[86:87], off
	v_addc_co_u32_e32 v91, vcc, 0, v113, vcc
	v_add_co_u32_e32 v94, vcc, 0x30000, v112
	s_mov_b64 s[10:11], 0
	s_nop 0
	v_addc_co_u32_e32 v95, vcc, 0, v113, vcc
	s_add_u32 m0, s98, 0x6000
	v_lshl_add_u64 v[90:91], v[90:91], 0, v[240:241]
	global_load_lds_dwordx4 v[90:91], off
	s_nop 0
	s_add_u32 m0, s98, 0x7000
	v_lshl_add_u64 v[94:95], v[94:95], 0, v[240:241]
	global_load_lds_dwordx4 v[94:95], off
	s_mov_b32 s9, 0
	s_waitcnt lgkmcnt(0)
	s_add_u32 m0, s98, 0x8000
	v_lshl_add_u64 v[70:71], v[70:71], 0, v[242:243]
	global_load_lds_dwordx4 v[70:71], off
	s_add_u32 m0, s98, 0x9000
	v_lshl_add_u64 v[66:67], v[66:67], 0, v[242:243]
	global_load_lds_dwordx4 v[66:67], off
	s_add_u32 m0, s98, 0xa000
	v_lshl_add_u64 v[74:75], v[74:75], 0, v[242:243]
	global_load_lds_dwordx4 v[74:75], off
	s_add_u32 m0, s98, 0xb000
	v_lshl_add_u64 v[78:79], v[78:79], 0, v[242:243]
	global_load_lds_dwordx4 v[78:79], off
	s_mov_b32 s100, 0
	s_mov_b32 s101, 0x4000
	s_waitcnt vmcnt(4)
	s_barrier
	s_branch .LBB0_923

.Ldqx_9:
	s_cmpk_lg_i32 s10, 0x400
	s_mov_b32 s7, s12
	s_waitcnt lgkmcnt(0)
	s_barrier
	s_cbranch_scc0 .LBB0_929

.LBB0_925:
	v_add_u32_e32 v112, s100, v115
	v_add3_u32 v113, v112, v118, s101
	ds_read_b128 v[124:127], v113
	v_add_u32_e32 v112, v112, v117
	ds_read_b128 v[128:131], v113 offset:2048
	ds_read_b128 v[132:135], v112
	ds_read_b128 v[136:139], v112 offset:2048
	ds_read_b128 v[140:143], v113 offset:4096
	ds_read_b128 v[144:147], v113 offset:6144
	s_waitcnt lgkmcnt(3)
	v_mfma_f32_16x16x32_bf16 v[58:61], v[128:131], v[132:135], v[58:61]
	s_andn2_b64 vcc, exec, s[12:13]
	v_mfma_f32_16x16x32_bf16 v[46:49], v[124:127], v[132:135], v[46:49]
	s_waitcnt lgkmcnt(1)
	v_mfma_f32_16x16x32_bf16 v[62:65], v[140:143], v[132:135], v[62:65]
	s_cbranch_vccz .Ldq_9_0
	s_add_u32 s99, s100, 0xc000
	s_cmp_lt_u32 s99, 0x14000
	s_cbranch_scc1 .Ldqw_9_0
	s_sub_u32 s99, s99, 0x14000

.Ldq_9_3:
	v_add_u32_e32 v112, v112, v117
	s_mov_b64 s[14:15], -1
	v_mfma_f32_16x16x32_bf16 v[30:33], v[128:131], v[132:135], v[30:33]
	v_mfma_f32_16x16x32_bf16 v[34:37], v[140:143], v[132:135], v[34:37]
	s_cmp_gt_u32 s9, 5
	s_cbranch_scc1 .Ldq_9_4
	s_add_u32 s99, s100, 0x10000
	s_cmp_lt_u32 s99, 0x14000
	s_cbranch_scc1 .Ldqw_9_4
	s_sub_u32 s99, s99, 0x14000

.Ldq_9_4:
	v_mfma_f32_16x16x32_bf16 v[38:41], v[144:147], v[132:135], v[38:41]
	s_waitcnt lgkmcnt(0)
	v_mfma_f32_16x16x32_bf16 v[26:29], v[124:127], v[136:139], v[26:29]
	s_cmp_gt_u32 s9, 5
	s_cbranch_scc1 .Ldq_9_5
	s_add_u32 m0, s99, 0x1000
	v_lshl_add_u64 v[66:67], v[66:67], 0, v[242:243]
	global_load_lds_dwordx4 v[66:67], off
.Ldq_9_5:
	ds_read_b128 v[124:127], v113
	v_mfma_f32_16x16x32_bf16 v[22:25], v[128:131], v[136:139], v[22:25]
	v_mfma_f32_16x16x32_bf16 v[18:21], v[140:143], v[136:139], v[18:21]
	s_cmp_gt_u32 s9, 5
	s_cbranch_scc1 .Ldq_9_6
	s_add_u32 m0, s99, 0x2000
	v_lshl_add_u64 v[74:75], v[74:75], 0, v[242:243]
	global_load_lds_dwordx4 v[74:75], off
.Ldq_9_6:
	v_mfma_f32_16x16x32_bf16 v[2:5], v[144:147], v[136:139], v[2:5]
	ds_read_b128 v[128:131], v113 offset:2048
	ds_read_b128 v[132:135], v112
	ds_read_b128 v[136:139], v112 offset:2048
	ds_read_b128 v[140:143], v113 offset:4096
	ds_read_b128 v[144:147], v113 offset:6144
	s_waitcnt lgkmcnt(3)
	v_mfma_f32_16x16x32_bf16 v[46:49], v[124:127], v[132:135], v[46:49]
	s_cmp_gt_u32 s9, 5
	s_cbranch_scc1 .Ldq_9_7
	s_add_u32 m0, s99, 0x3000
	v_lshl_add_u64 v[78:79], v[78:79], 0, v[242:243]
	global_load_lds_dwordx4 v[78:79], off
.Ldq_9_7:
	v_mfma_f32_16x16x32_bf16 v[58:61], v[128:131], v[132:135], v[58:61]
	s_waitcnt lgkmcnt(1)
	v_mfma_f32_16x16x32_bf16 v[62:65], v[140:143], v[132:135], v[62:65]
	s_waitcnt lgkmcnt(0)
	v_mfma_f32_16x16x32_bf16 v[54:57], v[144:147], v[132:135], v[54:57]
	v_mfma_f32_16x16x32_bf16 v[14:17], v[124:127], v[136:139], v[14:17]
	v_mfma_f32_16x16x32_bf16 v[6:9], v[128:131], v[136:139], v[6:9]
	v_mfma_f32_16x16x32_bf16 v[10:13], v[140:143], v[136:139], v[10:13]
	v_mfma_f32_16x16x32_bf16 v[50:53], v[144:147], v[136:139], v[50:53]
	ds_read_b128 v[132:135], v112 offset:4096
	ds_read_b128 v[136:139], v112 offset:6144
	s_waitcnt lgkmcnt(1)
	v_mfma_f32_16x16x32_bf16 v[42:45], v[124:127], v[132:135], v[42:45]
	v_mfma_f32_16x16x32_bf16 v[30:33], v[128:131], v[132:135], v[30:33]
	v_mfma_f32_16x16x32_bf16 v[34:37], v[140:143], v[132:135], v[34:37]
	v_mfma_f32_16x16x32_bf16 v[38:41], v[144:147], v[132:135], v[38:41]
	s_waitcnt lgkmcnt(0)
	v_mfma_f32_16x16x32_bf16 v[26:29], v[124:127], v[136:139], v[26:29]
	v_mfma_f32_16x16x32_bf16 v[22:25], v[128:131], v[136:139], v[22:25]
	v_mfma_f32_16x16x32_bf16 v[18:21], v[140:143], v[136:139], v[18:21]
	v_mfma_f32_16x16x32_bf16 v[2:5], v[144:147], v[136:139], v[2:5]
	s_cbranch_vccnz .LBB0_927
	s_add_i32 s12, s7, 0x8000
	s_mov_b64 s[14:15], 0

.LBB0_942:
	s_lshl_b32 s6, s20, 9
	s_and_b32 s6, s6, 0x70000
	v_lshl_add_u64 v[106:107], v[104:105], 0, s[6:7]
	s_lshl_b32 s6, s16, 4
	s_lshl_b32 s9, s16, 7
	s_and_b32 s8, s6, 0xffffff80
	s_and_b32 s25, s9, 0x380
	s_ashr_i32 s9, s8, 31
	s_lshl_b64 s[10:11], s[8:9], 9
	v_lshl_add_u64 v[2:3], v[100:101], 0, s[10:11]
	v_add_co_u32_e32 v6, vcc, s22, v2
	s_lshl_b32 s6, s25, 9
	s_nop 0
	v_addc_co_u32_e32 v7, vcc, 0, v3, vcc
	v_add_co_u32_e32 v8, vcc, s23, v2
	s_nop 1
	v_addc_co_u32_e32 v9, vcc, 0, v3, vcc
	s_barrier
	s_add_u32 m0, s98, 0x1000
	v_lshl_add_u64 v[10:11], v[6:7], 0, v[238:239]
	global_load_lds_dwordx4 v[10:11], off
	s_add_u32 m0, s98, 0x2000
	v_lshl_add_u64 v[26:27], v[8:9], 0, v[238:239]
	global_load_lds_dwordx4 v[26:27], off
	v_add_co_u32_e32 v6, vcc, s24, v2
	v_lshl_add_u64 v[4:5], v[102:103], 0, s[6:7]
	s_nop 0
	v_addc_co_u32_e32 v7, vcc, 0, v3, vcc
	s_mov_b32 m0, s98
	v_lshl_add_u64 v[18:19], v[2:3], 0, v[238:239]
	global_load_lds_dwordx4 v[18:19], off
	s_add_u32 m0, s98, 0x4000
	v_lshl_add_u64 v[42:43], v[4:5], 0, v[238:239]
	global_load_lds_dwordx4 v[42:43], off
	v_add_co_u32_e32 v2, vcc, s22, v4
	s_and_b32 s12, s18, 0xffffff80
	s_nop 0
	v_addc_co_u32_e32 v3, vcc, 0, v5, vcc
	s_add_u32 m0, s98, 0x3000
	v_lshl_add_u64 v[38:39], v[6:7], 0, v[238:239]
	global_load_lds_dwordx4 v[38:39], off
	s_add_u32 m0, s98, 0x5000
	v_lshl_add_u64 v[46:47], v[2:3], 0, v[238:239]
	global_load_lds_dwordx4 v[46:47], off
	v_add_co_u32_e32 v2, vcc, s23, v4
	s_ashr_i32 s13, s12, 31
	s_nop 0
	v_addc_co_u32_e32 v3, vcc, 0, v5, vcc
	v_add_co_u32_e32 v4, vcc, 0xc000, v4
	s_lshl_b64 s[12:13], s[12:13], 9
	s_nop 0
	v_addc_co_u32_e32 v5, vcc, 0, v5, vcc
	s_add_u32 m0, s98, 0x6000
	v_lshl_add_u64 v[58:59], v[2:3], 0, v[238:239]
	global_load_lds_dwordx4 v[58:59], off
	s_add_u32 m0, s98, 0x7000
	v_lshl_add_u64 v[62:63], v[4:5], 0, v[238:239]
	global_load_lds_dwordx4 v[62:63], off
	s_mov_b64 s[10:11], 0
	s_mov_b32 s9, 0
	s_mov_b32 s6, 0
	v_mov_b32_e32 v2, 0
	v_mov_b32_e32 v3, v99
	v_mov_b32_e32 v4, v99
	v_mov_b32_e32 v5, v99
	v_mov_b32_e32 v6, 0
	v_mov_b32_e32 v7, v99
	v_mov_b32_e32 v8, v99
	v_mov_b32_e32 v9, v99
	v_mov_b32_e32 v14, 0
	v_mov_b32_e32 v15, v99
	v_mov_b32_e32 v16, v99
	v_mov_b32_e32 v17, v99
	v_mov_b32_e32 v22, 0
	v_mov_b32_e32 v23, v99
	v_mov_b32_e32 v24, v99
	v_mov_b32_e32 v25, v99
	v_mov_b32_e32 v30, 0
	v_mov_b32_e32 v31, v99
	v_mov_b32_e32 v32, v99
	v_mov_b32_e32 v33, v99
	v_mov_b32_e32 v34, 0
	v_mov_b32_e32 v35, v99
	v_lshl_add_u64 v[108:109], v[104:105], 0, s[12:13]
	v_mov_b32_e32 v36, v99
	v_mov_b32_e32 v37, v99
	v_mov_b32_e32 v50, 0
	v_mov_b32_e32 v51, v99
	v_mov_b32_e32 v52, v99
	v_mov_b32_e32 v53, v99
	v_mov_b32_e32 v54, 0
	v_mov_b32_e32 v55, v99
	v_mov_b32_e32 v56, v99
	v_mov_b32_e32 v57, v99
	v_mov_b32_e32 v66, 0
	v_mov_b32_e32 v67, v99
	v_mov_b32_e32 v68, v99
	v_mov_b32_e32 v69, v99
	v_mov_b32_e32 v70, 0
	v_mov_b32_e32 v71, v99
	v_mov_b32_e32 v72, v99
	v_mov_b32_e32 v73, v99
	v_mov_b32_e32 v74, 0
	v_mov_b32_e32 v75, v99
	v_mov_b32_e32 v76, v99
	v_mov_b32_e32 v77, v99
	v_mov_b32_e32 v78, 0
	v_mov_b32_e32 v79, v99
	v_mov_b32_e32 v80, v99
	v_mov_b32_e32 v81, v99
	v_mov_b32_e32 v82, 0
	v_mov_b32_e32 v83, v99
	v_mov_b32_e32 v84, v99
	v_mov_b32_e32 v85, v99
	v_mov_b32_e32 v86, 0
	v_mov_b32_e32 v87, v99
	v_mov_b32_e32 v88, v99
	v_mov_b32_e32 v89, v99
	v_mov_b32_e32 v90, 0
	v_mov_b32_e32 v91, v99
	v_mov_b32_e32 v92, v99
	v_mov_b32_e32 v93, v99
	v_mov_b32_e32 v94, 0
	v_mov_b32_e32 v95, v99
	v_mov_b32_e32 v96, v99
	v_mov_b32_e32 v97, v99
	s_waitcnt lgkmcnt(0)
	s_add_u32 m0, s98, 0x8000
	v_lshl_add_u64 v[18:19], v[18:19], 0, v[242:243]
	global_load_lds_dwordx4 v[18:19], off
	s_add_u32 m0, s98, 0x9000
	v_lshl_add_u64 v[10:11], v[10:11], 0, v[242:243]
	global_load_lds_dwordx4 v[10:11], off
	s_add_u32 m0, s98, 0xa000
	v_lshl_add_u64 v[26:27], v[26:27], 0, v[242:243]
	global_load_lds_dwordx4 v[26:27], off
	s_add_u32 m0, s98, 0xb000
	v_lshl_add_u64 v[38:39], v[38:39], 0, v[242:243]
	global_load_lds_dwordx4 v[38:39], off
	s_mov_b32 s100, 0
	s_mov_b32 s101, 0x4000
	s_waitcnt vmcnt(4)
	s_barrier
	s_branch .LBB0_944
.LBB0_943:
	s_add_u32 s10, s10, 0x80
	s_addc_u32 s11, s11, 0
	s_add_i32 s6, s6, 1
	s_add_u32 s100, s100, 0x8000
	s_cmp_lt_u32 s100, 0x14000
	s_cbranch_scc1 .Ldqr_10
	s_sub_u32 s100, s100, 0x14000

.Ldqs_10:
	s_cmp_gt_u32 s6, 2
	s_cbranch_scc1 .Ldqv_10
	s_waitcnt vmcnt(4)
	s_branch .Ldqx_10

.Ldqx_10:
	s_cmpk_lg_i32 s10, 0x200
	s_mov_b32 s9, s12
	s_waitcnt lgkmcnt(0)
	s_barrier
	s_cbranch_scc0 .LBB0_941

.LBB0_946:
	v_add_u32_e32 v98, s100, v111
	v_add3_u32 v117, v98, v114, s101
	ds_read_b128 v[118:121], v117
	v_add_u32_e32 v98, v98, v113
	ds_read_b128 v[122:125], v117 offset:2048
	ds_read_b128 v[126:129], v98
	ds_read_b128 v[130:133], v98 offset:2048
	ds_read_b128 v[134:137], v117 offset:4096
	ds_read_b128 v[138:141], v117 offset:6144
	s_waitcnt lgkmcnt(3)
	v_mfma_f32_16x16x32_bf16 v[90:93], v[122:125], v[126:129], v[90:93]
	s_andn2_b64 vcc, exec, s[12:13]
	v_mfma_f32_16x16x32_bf16 v[94:97], v[118:121], v[126:129], v[94:97]
	s_waitcnt lgkmcnt(1)
	v_mfma_f32_16x16x32_bf16 v[86:89], v[134:137], v[126:129], v[86:89]
	s_cbranch_vccz .Ldq_10_0
	s_add_u32 s99, s100, 0xc000
	s_cmp_lt_u32 s99, 0x14000
	s_cbranch_scc1 .Ldqw_10_0
	s_sub_u32 s99, s99, 0x14000

.Ldq_10_0:
	s_waitcnt lgkmcnt(0)
	v_mfma_f32_16x16x32_bf16 v[82:85], v[138:141], v[126:129], v[82:85]
	v_mfma_f32_16x16x32_bf16 v[78:81], v[118:121], v[130:133], v[78:81]
	s_cbranch_vccz .Ldq_10_1
	s_add_u32 m0, s99, 0x1000
	v_lshl_add_u64 v[46:47], v[46:47], 0, v[242:243]
	global_load_lds_dwordx4 v[46:47], off
.Ldq_10_1:
	v_mfma_f32_16x16x32_bf16 v[74:77], v[122:125], v[130:133], v[74:77]
	v_mfma_f32_16x16x32_bf16 v[70:73], v[134:137], v[130:133], v[70:73]
	s_cbranch_vccz .Ldq_10_2
	s_add_u32 m0, s99, 0x2000
	v_lshl_add_u64 v[58:59], v[58:59], 0, v[242:243]
	global_load_lds_dwordx4 v[58:59], off
.Ldq_10_2:
	v_mfma_f32_16x16x32_bf16 v[66:69], v[138:141], v[130:133], v[66:69]
	ds_read_b128 v[126:129], v98 offset:4096
	ds_read_b128 v[130:133], v98 offset:6144
	v_add_u32_e32 v98, s100, v115
	v_add3_u32 v117, v98, v114, s101
	s_waitcnt lgkmcnt(1)
	v_mfma_f32_16x16x32_bf16 v[54:57], v[118:121], v[126:129], v[54:57]
	s_cbranch_vccz .Ldq_10_3
	s_add_u32 m0, s99, 0x3000
	v_lshl_add_u64 v[62:63], v[62:63], 0, v[242:243]
	global_load_lds_dwordx4 v[62:63], off
.Ldq_10_3:
	v_add_u32_e32 v98, v98, v113
	s_mov_b64 s[14:15], -1
	v_mfma_f32_16x16x32_bf16 v[50:53], v[122:125], v[126:129], v[50:53]
	v_mfma_f32_16x16x32_bf16 v[34:37], v[134:137], v[126:129], v[34:37]
	s_cmp_gt_u32 s6, 1
	s_cbranch_scc1 .Ldq_10_4
	s_add_u32 s99, s100, 0x10000
	s_cmp_lt_u32 s99, 0x14000
	s_cbranch_scc1 .Ldqw_10_4
	s_sub_u32 s99, s99, 0x14000
.Ldqw_10_4:
	s_add_u32 s99, s99, s98
	s_mov_b32 m0, s99
	v_lshl_add_u64 v[18:19], v[18:19], 0, v[242:243]
	global_load_lds_dwordx4 v[18:19], off
.Ldq_10_4:
	v_mfma_f32_16x16x32_bf16 v[30:33], v[138:141], v[126:129], v[30:33]
	s_waitcnt lgkmcnt(0)
	v_mfma_f32_16x16x32_bf16 v[22:25], v[118:121], v[130:133], v[22:25]
	s_cmp_gt_u32 s6, 1
	s_cbranch_scc1 .Ldq_10_5
	s_add_u32 m0, s99, 0x1000
	v_lshl_add_u64 v[10:11], v[10:11], 0, v[242:243]
	global_load_lds_dwordx4 v[10:11], off
.Ldq_10_5:
	ds_read_b128 v[118:121], v117
	v_mfma_f32_16x16x32_bf16 v[14:17], v[122:125], v[130:133], v[14:17]
	v_mfma_f32_16x16x32_bf16 v[6:9], v[134:137], v[130:133], v[6:9]
	s_cmp_gt_u32 s6, 1
	s_cbranch_scc1 .Ldq_10_6
	s_add_u32 m0, s99, 0x2000
	v_lshl_add_u64 v[26:27], v[26:27], 0, v[242:243]
	global_load_lds_dwordx4 v[26:27], off
.Ldq_10_6:
	v_mfma_f32_16x16x32_bf16 v[2:5], v[138:141], v[130:133], v[2:5]
	ds_read_b128 v[122:125], v117 offset:2048
	ds_read_b128 v[126:129], v98
	ds_read_b128 v[130:133], v98 offset:2048
	ds_read_b128 v[134:137], v117 offset:4096
	ds_read_b128 v[138:141], v117 offset:6144
	s_waitcnt lgkmcnt(3)
	v_mfma_f32_16x16x32_bf16 v[94:97], v[118:121], v[126:129], v[94:97]
	s_cmp_gt_u32 s6, 1
	s_cbranch_scc1 .Ldq_10_7
	s_add_u32 m0, s99, 0x3000
	v_lshl_add_u64 v[38:39], v[38:39], 0, v[242:243]
	global_load_lds_dwordx4 v[38:39], off
.Ldq_10_7:
	v_mfma_f32_16x16x32_bf16 v[90:93], v[122:125], v[126:129], v[90:93]
	s_waitcnt lgkmcnt(1)
	v_mfma_f32_16x16x32_bf16 v[86:89], v[134:137], v[126:129], v[86:89]
	s_waitcnt lgkmcnt(0)
	v_mfma_f32_16x16x32_bf16 v[82:85], v[138:141], v[126:129], v[82:85]
	v_mfma_f32_16x16x32_bf16 v[78:81], v[118:121], v[130:133], v[78:81]
	v_mfma_f32_16x16x32_bf16 v[74:77], v[122:125], v[130:133], v[74:77]
	v_mfma_f32_16x16x32_bf16 v[70:73], v[134:137], v[130:133], v[70:73]
	v_mfma_f32_16x16x32_bf16 v[66:69], v[138:141], v[130:133], v[66:69]
	ds_read_b128 v[126:129], v98 offset:4096
	ds_read_b128 v[130:133], v98 offset:6144
	s_waitcnt lgkmcnt(1)
	v_mfma_f32_16x16x32_bf16 v[54:57], v[118:121], v[126:129], v[54:57]
	v_mfma_f32_16x16x32_bf16 v[50:53], v[122:125], v[126:129], v[50:53]
	v_mfma_f32_16x16x32_bf16 v[34:37], v[134:137], v[126:129], v[34:37]
	v_mfma_f32_16x16x32_bf16 v[30:33], v[138:141], v[126:129], v[30:33]
	s_waitcnt lgkmcnt(0)
	v_mfma_f32_16x16x32_bf16 v[22:25], v[118:121], v[130:133], v[22:25]
	v_mfma_f32_16x16x32_bf16 v[14:17], v[122:125], v[130:133], v[14:17]
	v_mfma_f32_16x16x32_bf16 v[6:9], v[134:137], v[130:133], v[6:9]
	v_mfma_f32_16x16x32_bf16 v[2:5], v[138:141], v[130:133], v[2:5]
	s_cbranch_vccnz .LBB0_948
	s_add_i32 s12, s9, 0x8000
	s_mov_b64 s[14:15], 0

.LBB0_1014:
	s_lshl_b32 s8, s11, 7
	s_ashr_i32 s9, s8, 31
	s_lshl_b64 s[12:13], s[8:9], 11
	v_lshl_add_u64 v[98:99], v[114:115], 0, s[12:13]
	v_add_co_u32_e32 v4, vcc, s19, v98
	s_lshl_b32 s10, s10, 7
	s_nop 0
	v_addc_co_u32_e32 v5, vcc, 0, v99, vcc
	v_add_co_u32_e32 v6, vcc, s20, v98
	s_ashr_i32 s11, s10, 31
	s_nop 0
	v_addc_co_u32_e32 v7, vcc, 0, v99, vcc
	s_lshl_b64 s[14:15], s[10:11], 11
	s_barrier
	s_add_u32 m0, s98, 0x1000
	v_lshl_add_u64 v[46:47], v[4:5], 0, v[238:239]
	global_load_lds_dwordx4 v[46:47], off
	s_add_u32 m0, s98, 0x2000
	v_lshl_add_u64 v[62:63], v[6:7], 0, v[238:239]
	global_load_lds_dwordx4 v[62:63], off
	v_add_co_u32_e32 v4, vcc, s21, v98
	s_waitcnt lgkmcnt(0)
	v_lshl_add_u64 v[2:3], v[116:117], 0, s[14:15]
	v_addc_co_u32_e32 v5, vcc, 0, v99, vcc
	v_add_co_u32_e32 v6, vcc, s19, v2
	s_mov_b32 m0, s98
	v_lshl_add_u64 v[50:51], v[98:99], 0, v[238:239]
	global_load_lds_dwordx4 v[50:51], off
	s_add_u32 m0, s98, 0x4000
	v_lshl_add_u64 v[82:83], v[2:3], 0, v[238:239]
	global_load_lds_dwordx4 v[82:83], off
	v_addc_co_u32_e32 v7, vcc, 0, v3, vcc
	s_add_u32 m0, s98, 0x3000
	v_lshl_add_u64 v[66:67], v[4:5], 0, v[238:239]
	global_load_lds_dwordx4 v[66:67], off
	s_add_u32 m0, s98, 0x5000
	v_lshl_add_u64 v[86:87], v[6:7], 0, v[238:239]
	global_load_lds_dwordx4 v[86:87], off
	v_add_co_u32_e32 v4, vcc, s20, v2
	v_mov_b32_e32 v78, 0
	v_addc_co_u32_e32 v5, vcc, 0, v3, vcc
	v_add_co_u32_e32 v2, vcc, s21, v2
	s_mov_b32 s11, 0
	s_nop 0
	v_addc_co_u32_e32 v3, vcc, 0, v3, vcc
	s_add_u32 m0, s98, 0x6000
	v_lshl_add_u64 v[90:91], v[4:5], 0, v[238:239]
	global_load_lds_dwordx4 v[90:91], off
	s_add_u32 m0, s98, 0x7000
	v_lshl_add_u64 v[94:95], v[2:3], 0, v[238:239]
	global_load_lds_dwordx4 v[94:95], off
	s_mov_b64 s[12:13], 0
	s_mov_b32 s9, 0
	v_mov_b32_e32 v79, v78
	v_mov_b32_e32 v80, v78
	v_mov_b32_e32 v81, v78
	v_mov_b32_e32 v74, v78
	v_mov_b32_e32 v75, v78
	v_mov_b32_e32 v76, v78
	v_mov_b32_e32 v77, v78
	v_mov_b32_e32 v70, v78
	v_mov_b32_e32 v71, v78
	v_mov_b32_e32 v72, v78
	v_mov_b32_e32 v73, v78
	v_mov_b32_e32 v58, v78
	v_mov_b32_e32 v59, v78
	v_mov_b32_e32 v60, v78
	v_mov_b32_e32 v61, v78
	v_mov_b32_e32 v54, v78
	v_mov_b32_e32 v55, v78
	v_mov_b32_e32 v56, v78
	v_mov_b32_e32 v57, v78
	v_mov_b32_e32 v42, v78
	v_mov_b32_e32 v43, v78
	v_mov_b32_e32 v44, v78
	v_mov_b32_e32 v45, v78
	v_mov_b32_e32 v38, v78
	v_mov_b32_e32 v39, v78
	v_mov_b32_e32 v40, v78
	v_mov_b32_e32 v41, v78
	v_lshl_add_u64 v[100:101], v[118:119], 0, s[14:15]
	v_mov_b32_e32 v34, v78
	v_mov_b32_e32 v35, v78
	v_mov_b32_e32 v36, v78
	v_mov_b32_e32 v37, v78
	v_mov_b32_e32 v30, v78
	v_mov_b32_e32 v31, v78
	v_mov_b32_e32 v32, v78
	v_mov_b32_e32 v33, v78
	v_mov_b32_e32 v26, v78
	v_mov_b32_e32 v27, v78
	v_mov_b32_e32 v28, v78
	v_mov_b32_e32 v29, v78
	v_mov_b32_e32 v22, v78
	v_mov_b32_e32 v23, v78
	v_mov_b32_e32 v24, v78
	v_mov_b32_e32 v25, v78
	v_mov_b32_e32 v18, v78
	v_mov_b32_e32 v19, v78
	v_mov_b32_e32 v20, v78
	v_mov_b32_e32 v21, v78
	v_mov_b32_e32 v14, v78
	v_mov_b32_e32 v15, v78
	v_mov_b32_e32 v16, v78
	v_mov_b32_e32 v17, v78
	v_mov_b32_e32 v10, v78
	v_mov_b32_e32 v11, v78
	v_mov_b32_e32 v12, v78
	v_mov_b32_e32 v13, v78
	v_mov_b32_e32 v6, v78
	v_mov_b32_e32 v7, v78
	v_mov_b32_e32 v8, v78
	v_mov_b32_e32 v9, v78
	v_mov_b32_e32 v2, v78
	v_mov_b32_e32 v3, v78
	v_mov_b32_e32 v4, v78
	v_mov_b32_e32 v5, v78
	s_waitcnt lgkmcnt(0)
	s_add_u32 m0, s98, 0x8000
	v_lshl_add_u64 v[50:51], v[50:51], 0, v[242:243]
	global_load_lds_dwordx4 v[50:51], off
	s_add_u32 m0, s98, 0x9000
	v_lshl_add_u64 v[46:47], v[46:47], 0, v[242:243]
	global_load_lds_dwordx4 v[46:47], off
	s_add_u32 m0, s98, 0xa000
	v_lshl_add_u64 v[62:63], v[62:63], 0, v[242:243]
	global_load_lds_dwordx4 v[62:63], off
	s_add_u32 m0, s98, 0xb000
	v_lshl_add_u64 v[66:67], v[66:67], 0, v[242:243]
	global_load_lds_dwordx4 v[66:67], off
	s_mov_b32 s100, 0
	s_mov_b32 s101, 0x4000
	s_waitcnt vmcnt(4)
	s_barrier
	s_branch .LBB0_1016
.LBB0_1015:
	s_add_u32 s12, s12, 0x80
	s_addc_u32 s13, s13, 0
	s_add_i32 s9, s9, 1
	s_add_u32 s100, s100, 0x8000
	s_cmp_lt_u32 s100, 0x14000
	s_cbranch_scc1 .Ldqr_11
	s_sub_u32 s100, s100, 0x14000

.Ldqs_11:
	s_cmp_gt_u32 s9, 14
	s_cbranch_scc1 .Ldqv_11
	s_waitcnt vmcnt(4)
	s_branch .Ldqx_11

.Ldqx_11:
	s_cmpk_lg_i32 s12, 0x800
	s_mov_b32 s11, s14
	s_waitcnt lgkmcnt(0)
	s_barrier
	s_cbranch_scc0 .LBB0_1022

.LBB0_1018:
	v_add_u32_e32 v106, s100, v129
	v_add3_u32 v139, v106, v132, s101
	ds_read_b128 v[102:105], v139
	v_add_u32_e32 v144, v106, v131
	ds_read_b128 v[106:109], v139 offset:2048
	ds_read_b128 v[110:113], v144
	ds_read_b128 v[120:123], v144 offset:2048
	ds_read_b128 v[124:127], v139 offset:4096
	ds_read_b128 v[140:143], v139 offset:6144
	s_waitcnt lgkmcnt(3)
	v_mfma_f32_16x16x32_bf16 v[74:77], v[106:109], v[110:113], v[74:77]
	s_andn2_b64 vcc, exec, s[14:15]
	v_mfma_f32_16x16x32_bf16 v[78:81], v[102:105], v[110:113], v[78:81]
	s_waitcnt lgkmcnt(1)
	v_mfma_f32_16x16x32_bf16 v[70:73], v[124:127], v[110:113], v[70:73]
	s_cbranch_vccz .Ldq_11_0
	s_add_u32 s99, s100, 0xc000
	s_cmp_lt_u32 s99, 0x14000
	s_cbranch_scc1 .Ldqw_11_0
	s_sub_u32 s99, s99, 0x14000

.Ldq_11_0:
	s_waitcnt lgkmcnt(0)
	v_mfma_f32_16x16x32_bf16 v[58:61], v[140:143], v[110:113], v[58:61]
	v_mfma_f32_16x16x32_bf16 v[54:57], v[102:105], v[120:123], v[54:57]
	s_cbranch_vccz .Ldq_11_1
	s_add_u32 m0, s99, 0x1000
	v_lshl_add_u64 v[86:87], v[86:87], 0, v[242:243]
	global_load_lds_dwordx4 v[86:87], off
.Ldq_11_1:
	v_mfma_f32_16x16x32_bf16 v[42:45], v[106:109], v[120:123], v[42:45]
	v_mfma_f32_16x16x32_bf16 v[38:41], v[124:127], v[120:123], v[38:41]
	s_cbranch_vccz .Ldq_11_2
	s_add_u32 m0, s99, 0x2000
	v_lshl_add_u64 v[90:91], v[90:91], 0, v[242:243]
	global_load_lds_dwordx4 v[90:91], off
.Ldq_11_2:
	v_mfma_f32_16x16x32_bf16 v[34:37], v[140:143], v[120:123], v[34:37]
	ds_read_b128 v[110:113], v144 offset:4096
	ds_read_b128 v[120:123], v144 offset:6144
	s_waitcnt lgkmcnt(1)
	v_mfma_f32_16x16x32_bf16 v[26:29], v[106:109], v[110:113], v[26:29]
	s_cbranch_vccz .Ldq_11_3
	s_add_u32 m0, s99, 0x3000
	v_lshl_add_u64 v[94:95], v[94:95], 0, v[242:243]
	global_load_lds_dwordx4 v[94:95], off
.Ldq_11_3:
	s_waitcnt lgkmcnt(0)
	v_mfma_f32_16x16x32_bf16 v[10:13], v[106:109], v[120:123], v[10:13]
	v_add_u32_e32 v106, s100, v133
	v_add3_u32 v139, v106, v132, s101
	v_add_u32_e32 v144, v106, v131
	v_mfma_f32_16x16x32_bf16 v[30:33], v[102:105], v[110:113], v[30:33]
	s_cmp_gt_u32 s9, 13
	s_cbranch_scc1 .Ldq_11_4
	s_add_u32 s99, s100, 0x10000
	s_cmp_lt_u32 s99, 0x14000
	s_cbranch_scc1 .Ldqw_11_4
	s_sub_u32 s99, s99, 0x14000
.Ldqw_11_4:
	s_add_u32 s99, s99, s98
	s_mov_b32 m0, s99
	v_lshl_add_u64 v[50:51], v[50:51], 0, v[242:243]
	global_load_lds_dwordx4 v[50:51], off
.Ldq_11_4:
	s_mov_b64 s[16:17], -1
	v_mfma_f32_16x16x32_bf16 v[22:25], v[124:127], v[110:113], v[22:25]
	v_mfma_f32_16x16x32_bf16 v[18:21], v[140:143], v[110:113], v[18:21]
	s_cmp_gt_u32 s9, 13
	s_cbranch_scc1 .Ldq_11_5
	s_add_u32 m0, s99, 0x1000
	v_lshl_add_u64 v[46:47], v[46:47], 0, v[242:243]
	global_load_lds_dwordx4 v[46:47], off
.Ldq_11_5:
	v_mfma_f32_16x16x32_bf16 v[14:17], v[102:105], v[120:123], v[14:17]
	ds_read_b128 v[102:105], v139
	v_mfma_f32_16x16x32_bf16 v[6:9], v[124:127], v[120:123], v[6:9]
	s_cmp_gt_u32 s9, 13
	s_cbranch_scc1 .Ldq_11_6
	s_add_u32 m0, s99, 0x2000
	v_lshl_add_u64 v[62:63], v[62:63], 0, v[242:243]
	global_load_lds_dwordx4 v[62:63], off
.Ldq_11_6:
	v_mfma_f32_16x16x32_bf16 v[2:5], v[140:143], v[120:123], v[2:5]
	ds_read_b128 v[106:109], v139 offset:2048
	ds_read_b128 v[110:113], v144
	ds_read_b128 v[120:123], v144 offset:2048
	ds_read_b128 v[124:127], v139 offset:4096
	ds_read_b128 v[140:143], v139 offset:6144
	s_waitcnt lgkmcnt(3)
	v_mfma_f32_16x16x32_bf16 v[78:81], v[102:105], v[110:113], v[78:81]
	s_cmp_gt_u32 s9, 13
	s_cbranch_scc1 .Ldq_11_7
	s_add_u32 m0, s99, 0x3000
	v_lshl_add_u64 v[66:67], v[66:67], 0, v[242:243]
	global_load_lds_dwordx4 v[66:67], off
.Ldq_11_7:
	v_mfma_f32_16x16x32_bf16 v[74:77], v[106:109], v[110:113], v[74:77]
	s_waitcnt lgkmcnt(1)
	v_mfma_f32_16x16x32_bf16 v[70:73], v[124:127], v[110:113], v[70:73]
	s_waitcnt lgkmcnt(0)
	v_mfma_f32_16x16x32_bf16 v[58:61], v[140:143], v[110:113], v[58:61]
	v_mfma_f32_16x16x32_bf16 v[54:57], v[102:105], v[120:123], v[54:57]
	v_mfma_f32_16x16x32_bf16 v[42:45], v[106:109], v[120:123], v[42:45]
	v_mfma_f32_16x16x32_bf16 v[38:41], v[124:127], v[120:123], v[38:41]
	v_mfma_f32_16x16x32_bf16 v[34:37], v[140:143], v[120:123], v[34:37]
	ds_read_b128 v[110:113], v144 offset:4096
	ds_read_b128 v[120:123], v144 offset:6144
	s_waitcnt lgkmcnt(1)
	v_mfma_f32_16x16x32_bf16 v[30:33], v[102:105], v[110:113], v[30:33]
	v_mfma_f32_16x16x32_bf16 v[26:29], v[106:109], v[110:113], v[26:29]
	v_mfma_f32_16x16x32_bf16 v[22:25], v[124:127], v[110:113], v[22:25]
	v_mfma_f32_16x16x32_bf16 v[18:21], v[140:143], v[110:113], v[18:21]
	s_waitcnt lgkmcnt(0)
	v_mfma_f32_16x16x32_bf16 v[14:17], v[102:105], v[120:123], v[14:17]
	v_mfma_f32_16x16x32_bf16 v[10:13], v[106:109], v[120:123], v[10:13]
	v_mfma_f32_16x16x32_bf16 v[6:9], v[124:127], v[120:123], v[6:9]
	v_mfma_f32_16x16x32_bf16 v[2:5], v[140:143], v[120:123], v[2:5]
	s_cbranch_vccnz .LBB0_1020
	s_add_i32 s14, s11, 0x8000
	s_mov_b64 s[16:17], 0

.LBB0_1039:
	s_lshl_b32 s8, s11, 7
	s_ashr_i32 s9, s8, 31
	s_lshl_b64 s[12:13], s[8:9], 11
	v_lshl_add_u64 v[98:99], v[114:115], 0, s[12:13]
	v_add_co_u32_e32 v4, vcc, s21, v98
	s_lshl_b32 s10, s10, 7
	s_nop 0
	v_addc_co_u32_e32 v5, vcc, 0, v99, vcc
	v_add_co_u32_e32 v6, vcc, s22, v98
	s_ashr_i32 s11, s10, 31
	s_nop 0
	v_addc_co_u32_e32 v7, vcc, 0, v99, vcc
	s_lshl_b64 s[14:15], s[10:11], 11
	s_barrier
	s_add_u32 m0, s98, 0x1000
	v_lshl_add_u64 v[46:47], v[4:5], 0, v[238:239]
	global_load_lds_dwordx4 v[46:47], off
	s_add_u32 m0, s98, 0x2000
	v_lshl_add_u64 v[62:63], v[6:7], 0, v[238:239]
	global_load_lds_dwordx4 v[62:63], off
	v_add_co_u32_e32 v4, vcc, s23, v98
	s_waitcnt lgkmcnt(0)
	v_lshl_add_u64 v[2:3], v[116:117], 0, s[14:15]
	v_addc_co_u32_e32 v5, vcc, 0, v99, vcc
	v_add_co_u32_e32 v6, vcc, s21, v2
	s_mov_b32 m0, s98
	v_lshl_add_u64 v[50:51], v[98:99], 0, v[238:239]
	global_load_lds_dwordx4 v[50:51], off
	s_add_u32 m0, s98, 0x4000
	v_lshl_add_u64 v[82:83], v[2:3], 0, v[238:239]
	global_load_lds_dwordx4 v[82:83], off
	v_addc_co_u32_e32 v7, vcc, 0, v3, vcc
	s_add_u32 m0, s98, 0x3000
	v_lshl_add_u64 v[66:67], v[4:5], 0, v[238:239]
	global_load_lds_dwordx4 v[66:67], off
	s_add_u32 m0, s98, 0x5000
	v_lshl_add_u64 v[86:87], v[6:7], 0, v[238:239]
	global_load_lds_dwordx4 v[86:87], off
	v_add_co_u32_e32 v4, vcc, s22, v2
	v_mov_b32_e32 v78, 0
	v_addc_co_u32_e32 v5, vcc, 0, v3, vcc
	v_add_co_u32_e32 v2, vcc, s23, v2
	s_mov_b32 s11, 0
	s_nop 0
	v_addc_co_u32_e32 v3, vcc, 0, v3, vcc
	s_add_u32 m0, s98, 0x6000
	v_lshl_add_u64 v[90:91], v[4:5], 0, v[238:239]
	global_load_lds_dwordx4 v[90:91], off
	s_add_u32 m0, s98, 0x7000
	v_lshl_add_u64 v[94:95], v[2:3], 0, v[238:239]
	global_load_lds_dwordx4 v[94:95], off
	s_mov_b64 s[12:13], 0
	s_mov_b32 s9, 0
	v_mov_b32_e32 v79, v78
	v_mov_b32_e32 v80, v78
	v_mov_b32_e32 v81, v78
	v_mov_b32_e32 v74, v78
	v_mov_b32_e32 v75, v78
	v_mov_b32_e32 v76, v78
	v_mov_b32_e32 v77, v78
	v_mov_b32_e32 v70, v78
	v_mov_b32_e32 v71, v78
	v_mov_b32_e32 v72, v78
	v_mov_b32_e32 v73, v78
	v_mov_b32_e32 v58, v78
	v_mov_b32_e32 v59, v78
	v_mov_b32_e32 v60, v78
	v_mov_b32_e32 v61, v78
	v_mov_b32_e32 v54, v78
	v_mov_b32_e32 v55, v78
	v_mov_b32_e32 v56, v78
	v_mov_b32_e32 v57, v78
	v_mov_b32_e32 v42, v78
	v_mov_b32_e32 v43, v78
	v_mov_b32_e32 v44, v78
	v_mov_b32_e32 v45, v78
	v_mov_b32_e32 v38, v78
	v_mov_b32_e32 v39, v78
	v_mov_b32_e32 v40, v78
	v_mov_b32_e32 v41, v78
	v_lshl_add_u64 v[100:101], v[118:119], 0, s[14:15]
	v_mov_b32_e32 v34, v78
	v_mov_b32_e32 v35, v78
	v_mov_b32_e32 v36, v78
	v_mov_b32_e32 v37, v78
	v_mov_b32_e32 v30, v78
	v_mov_b32_e32 v31, v78
	v_mov_b32_e32 v32, v78
	v_mov_b32_e32 v33, v78
	v_mov_b32_e32 v26, v78
	v_mov_b32_e32 v27, v78
	v_mov_b32_e32 v28, v78
	v_mov_b32_e32 v29, v78
	v_mov_b32_e32 v22, v78
	v_mov_b32_e32 v23, v78
	v_mov_b32_e32 v24, v78
	v_mov_b32_e32 v25, v78
	v_mov_b32_e32 v18, v78
	v_mov_b32_e32 v19, v78
	v_mov_b32_e32 v20, v78
	v_mov_b32_e32 v21, v78
	v_mov_b32_e32 v14, v78
	v_mov_b32_e32 v15, v78
	v_mov_b32_e32 v16, v78
	v_mov_b32_e32 v17, v78
	v_mov_b32_e32 v10, v78
	v_mov_b32_e32 v11, v78
	v_mov_b32_e32 v12, v78
	v_mov_b32_e32 v13, v78
	v_mov_b32_e32 v6, v78
	v_mov_b32_e32 v7, v78
	v_mov_b32_e32 v8, v78
	v_mov_b32_e32 v9, v78
	v_mov_b32_e32 v2, v78
	v_mov_b32_e32 v3, v78
	v_mov_b32_e32 v4, v78
	v_mov_b32_e32 v5, v78
	s_waitcnt lgkmcnt(0)
	s_add_u32 m0, s98, 0x8000
	v_lshl_add_u64 v[50:51], v[50:51], 0, v[242:243]
	global_load_lds_dwordx4 v[50:51], off
	s_add_u32 m0, s98, 0x9000
	v_lshl_add_u64 v[46:47], v[46:47], 0, v[242:243]
	global_load_lds_dwordx4 v[46:47], off
	s_add_u32 m0, s98, 0xa000
	v_lshl_add_u64 v[62:63], v[62:63], 0, v[242:243]
	global_load_lds_dwordx4 v[62:63], off
	s_add_u32 m0, s98, 0xb000
	v_lshl_add_u64 v[66:67], v[66:67], 0, v[242:243]
	global_load_lds_dwordx4 v[66:67], off
	s_mov_b32 s100, 0
	s_mov_b32 s101, 0x4000
	s_waitcnt vmcnt(4)
	s_barrier
	s_branch .LBB0_1041

.LBB0_1061:
	s_lshl_b32 s5, s59, 6
	s_lshl_b32 s4, s8, 7
	s_and_b32 s5, s5, 64
	s_or_b32 s4, s4, s5
	s_ashr_i32 s5, s4, 31
	s_lshl_b32 s6, s7, 7
	s_lshl_b64 s[8:9], s[4:5], 11
	s_add_u32 s8, s54, s8
	s_addc_u32 s9, s55, s9
	s_ashr_i32 s7, s6, 31
	s_lshl_b64 s[10:11], s[6:7], 11
	v_lshrrev_b32_e32 v8, 3, v0
	s_add_u32 s12, s54, s10
	v_lshlrev_b32_e32 v22, 11, v8
	v_mov_b32_e32 v23, 0
	v_lshlrev_b32_e32 v4, 4, v0
	s_addc_u32 s13, s55, s11
	s_waitcnt lgkmcnt(0)
	v_lshl_add_u64 v[2:3], s[8:9], 0, v[22:23]
	v_and_b32_e32 v4, 0x70, v4
	v_mov_b32_e32 v5, v23
	s_waitcnt vmcnt(9)
	v_lshl_add_u64 v[58:59], v[2:3], 0, v[4:5]
	v_lshl_add_u64 v[2:3], s[12:13], 0, v[22:23]
	s_mov_b32 s5, 0x10000
	v_lshl_add_u64 v[2:3], v[2:3], 0, v[4:5]
	v_add_co_u32_e32 v4, vcc, s5, v58
	s_mov_b32 s5, 0xf000000
	s_nop 0
	v_addc_co_u32_e32 v5, vcc, 0, v59, vcc
	s_barrier
	s_mov_b32 m0, s98
	v_lshl_add_u64 v[34:35], v[58:59], 0, v[238:239]
	global_load_lds_dwordx4 v[34:35], off
	s_add_u32 m0, s98, 0x1000
	v_lshl_add_u64 v[38:39], v[4:5], 0, v[238:239]
	global_load_lds_dwordx4 v[38:39], off
	v_add_co_u32_e32 v4, vcc, s5, v2
	s_mov_b32 s5, 0xf010000
	s_nop 0
	v_addc_co_u32_e32 v5, vcc, 0, v3, vcc
	v_add_co_u32_e32 v6, vcc, s5, v2
	s_mov_b32 s5, 0xf020000
	s_nop 0
	v_addc_co_u32_e32 v7, vcc, 0, v3, vcc
	s_add_u32 m0, s98, 0x4000
	v_lshl_add_u64 v[42:43], v[4:5], 0, v[238:239]
	global_load_lds_dwordx4 v[42:43], off
	s_add_u32 m0, s98, 0x5000
	v_lshl_add_u64 v[46:47], v[6:7], 0, v[238:239]
	global_load_lds_dwordx4 v[46:47], off
	v_add_co_u32_e32 v4, vcc, s5, v2
	s_mov_b32 s5, 0xf030000
	s_nop 0
	v_addc_co_u32_e32 v5, vcc, 0, v3, vcc
	v_add_co_u32_e32 v2, vcc, s5, v2
	v_lshlrev_b32_e32 v7, 8, v0
	s_nop 0
	v_addc_co_u32_e32 v3, vcc, 0, v3, vcc
	s_add_u32 m0, s98, 0x6000
	v_lshl_add_u64 v[50:51], v[4:5], 0, v[238:239]
	global_load_lds_dwordx4 v[50:51], off
	s_add_u32 m0, s98, 0x7000
	v_lshl_add_u64 v[54:55], v[2:3], 0, v[238:239]
	global_load_lds_dwordx4 v[54:55], off
	v_lshrrev_b32_e32 v2, 4, v0
	v_bfe_u32 v3, v0, 4, 2
	v_and_b32_e32 v4, 7, v0
	v_lshrrev_b32_e32 v5, 2, v0
	v_lshlrev_b32_e32 v6, 7, v0
	v_lshlrev_b32_e32 v9, 7, v8
	v_xor_b32_e32 v8, v8, v0
	v_and_b32_e32 v62, 32, v5
	v_bitop3_b32 v2, v2, v4, 3 bitop3:0x6c
	v_bitop3_b32 v3, v3, v4, 4 bitop3:0x36
	v_and_b32_e32 v5, 0xf800, v7
	v_lshlrev_b32_e32 v4, 4, v4
	s_movk_i32 s12, 0x70
	v_and_b32_e32 v64, 0x2780, v6
	v_lshlrev_b32_e32 v6, 4, v8
	v_and_or_b32 v63, v0, 15, v62
	v_lshlrev_b32_e32 v65, 4, v2
	v_lshlrev_b32_e32 v66, 4, v3
	v_or3_b32 v2, s10, v5, v4
	v_mov_b32_e32 v3, s11
	s_mov_b32 s7, 0
	s_mov_b64 s[8:9], 0
	s_mov_b32 s5, 0
	v_and_or_b32 v67, v6, s12, v9
	v_lshlrev_b32_e32 v68, 7, v63
	v_lshl_add_u64 v[60:61], s[54:55], 0, v[2:3]
	v_mov_b32_e32 v22, v23
	v_mov_b32_e32 v24, v23
	v_mov_b32_e32 v25, v23
	v_mov_b32_e32 v30, v23
	v_mov_b32_e32 v31, v23
	v_mov_b32_e32 v32, v23
	v_mov_b32_e32 v33, v23
	v_mov_b32_e32 v26, v23
	v_mov_b32_e32 v27, v23
	v_mov_b32_e32 v28, v23
	v_mov_b32_e32 v29, v23
	v_mov_b32_e32 v18, v23
	v_mov_b32_e32 v19, v23
	v_mov_b32_e32 v20, v23
	v_mov_b32_e32 v21, v23
	v_mov_b32_e32 v14, v23
	v_mov_b32_e32 v15, v23
	v_mov_b32_e32 v16, v23
	v_mov_b32_e32 v17, v23
	v_mov_b32_e32 v10, v23
	v_mov_b32_e32 v11, v23
	v_mov_b32_e32 v12, v23
	v_mov_b32_e32 v13, v23
	v_mov_b32_e32 v6, v23
	v_mov_b32_e32 v7, v23
	v_mov_b32_e32 v8, v23
	v_mov_b32_e32 v9, v23
	v_mov_b32_e32 v2, v23
	v_mov_b32_e32 v3, v23
	v_mov_b32_e32 v4, v23
	v_mov_b32_e32 v5, v23
	s_waitcnt lgkmcnt(0)
	s_add_u32 m0, s98, 0x8000
	v_lshl_add_u64 v[34:35], v[34:35], 0, v[242:243]
	global_load_lds_dwordx4 v[34:35], off
	s_add_u32 m0, s98, 0x9000
	v_lshl_add_u64 v[38:39], v[38:39], 0, v[242:243]
	global_load_lds_dwordx4 v[38:39], off
	s_mov_b32 s100, 0
	s_mov_b32 s101, 0x4000
	s_waitcnt vmcnt(2)
	s_barrier
	s_branch .LBB0_1063
.LBB0_1062:
	s_add_u32 s8, s8, 0x80
	s_addc_u32 s9, s9, 0
	s_add_i32 s5, s5, 1
	s_add_u32 s100, s100, 0x8000
	s_cmp_lt_u32 s100, 0x14000
	s_cbranch_scc1 .Ldqr_13
	s_sub_u32 s100, s100, 0x14000

.Ldqs_13:
	s_cmp_gt_u32 s5, 14
	s_cbranch_scc1 .Ldqv_13
	s_waitcnt vmcnt(2)
	s_branch .Ldqx_13

.Ldqx_13:
	s_cmpk_lg_i32 s8, 0x800
	s_mov_b32 s7, s10
	s_waitcnt lgkmcnt(0)
	s_barrier
	s_cbranch_scc0 .LBB0_1069

.LBB0_1065:
	v_add_u32_e32 v69, s100, v65
	v_add3_u32 v90, v69, v64, s101
	ds_read_b128 v[70:73], v90
	v_add_u32_e32 v69, v69, v68
	ds_read_b128 v[74:77], v90 offset:2048
	ds_read_b128 v[78:81], v69
	ds_read_b128 v[82:85], v69 offset:2048
	v_add_u32_e32 v69, s100, v66
	v_add3_u32 v94, v69, v64, s101
	ds_read_b128 v[86:89], v90 offset:4096
	s_waitcnt lgkmcnt(2)
	v_mfma_f32_16x16x32_bf16 v[30:33], v[74:77], v[78:81], v[30:33]
	v_add_u32_e32 v69, v69, v68
	s_mov_b64 s[12:13], -1
	s_andn2_b64 vcc, exec, s[10:11]
	v_mfma_f32_16x16x32_bf16 v[22:25], v[70:73], v[78:81], v[22:25]
	s_waitcnt lgkmcnt(1)
	v_mfma_f32_16x16x32_bf16 v[14:17], v[70:73], v[82:85], v[14:17]
	s_cbranch_vccz .Ldq_13_0
	s_add_u32 s99, s100, 0xc000
	s_cmp_lt_u32 s99, 0x14000
	s_cbranch_scc1 .Ldqw_13_0
	s_sub_u32 s99, s99, 0x14000

.Ldq_13_0:
	ds_read_b128 v[70:73], v94
	ds_read_b128 v[90:93], v90 offset:6144
	s_waitcnt lgkmcnt(2)
	v_mfma_f32_16x16x32_bf16 v[26:29], v[86:89], v[78:81], v[26:29]
	s_waitcnt lgkmcnt(0)
	v_mfma_f32_16x16x32_bf16 v[18:21], v[90:93], v[78:81], v[18:21]
	s_cbranch_vccz .Ldq_13_1
	s_add_u32 m0, s99, 0x1000
	v_lshl_add_u64 v[46:47], v[46:47], 0, v[242:243]
	global_load_lds_dwordx4 v[46:47], off
.Ldq_13_1:
	v_mfma_f32_16x16x32_bf16 v[10:13], v[74:77], v[82:85], v[10:13]
	v_mfma_f32_16x16x32_bf16 v[6:9], v[86:89], v[82:85], v[6:9]
	s_cbranch_vccz .Ldq_13_2
	s_add_u32 m0, s99, 0x2000
	v_lshl_add_u64 v[50:51], v[50:51], 0, v[242:243]
	global_load_lds_dwordx4 v[50:51], off
.Ldq_13_2:
	v_mfma_f32_16x16x32_bf16 v[2:5], v[90:93], v[82:85], v[2:5]
	ds_read_b128 v[74:77], v94 offset:2048
	ds_read_b128 v[78:81], v69
	ds_read_b128 v[82:85], v69 offset:2048
	ds_read_b128 v[86:89], v94 offset:4096
	ds_read_b128 v[90:93], v94 offset:6144
	s_waitcnt lgkmcnt(3)
	v_mfma_f32_16x16x32_bf16 v[22:25], v[70:73], v[78:81], v[22:25]
	s_cbranch_vccz .Ldq_13_3
	s_add_u32 m0, s99, 0x3000
	v_lshl_add_u64 v[54:55], v[54:55], 0, v[242:243]
	global_load_lds_dwordx4 v[54:55], off
.Ldq_13_3:
	v_mfma_f32_16x16x32_bf16 v[30:33], v[74:77], v[78:81], v[30:33]
	s_waitcnt lgkmcnt(1)
	v_mfma_f32_16x16x32_bf16 v[26:29], v[86:89], v[78:81], v[26:29]
	s_cmp_gt_u32 s5, 13
	s_cbranch_scc1 .Ldq_13_4
	s_add_u32 s99, s100, 0x10000
	s_cmp_lt_u32 s99, 0x14000
	s_cbranch_scc1 .Ldqw_13_4
	s_sub_u32 s99, s99, 0x14000

.Ldq_13_4:
	s_waitcnt lgkmcnt(0)
	v_mfma_f32_16x16x32_bf16 v[18:21], v[90:93], v[78:81], v[18:21]
	v_mfma_f32_16x16x32_bf16 v[14:17], v[70:73], v[82:85], v[14:17]
	s_cmp_gt_u32 s5, 13
	s_cbranch_scc1 .Ldq_13_5
	s_add_u32 m0, s99, 0x1000
	v_lshl_add_u64 v[38:39], v[38:39], 0, v[242:243]
	global_load_lds_dwordx4 v[38:39], off
.Ldq_13_5:
	v_mfma_f32_16x16x32_bf16 v[10:13], v[74:77], v[82:85], v[10:13]
	v_mfma_f32_16x16x32_bf16 v[6:9], v[86:89], v[82:85], v[6:9]
	v_mfma_f32_16x16x32_bf16 v[2:5], v[90:93], v[82:85], v[2:5]
	s_cbranch_vccnz .LBB0_1067
	s_add_i32 s10, s7, 0x8000
	s_mov_b64 s[12:13], 0

.LBB0_1083:
	s_lshl_b32 s8, s11, 7
	s_ashr_i32 s9, s8, 31
	s_lshl_b64 s[12:13], s[8:9], 11
	v_lshl_add_u64 v[98:99], v[114:115], 0, s[12:13]
	v_add_co_u32_e32 v4, vcc, s20, v98
	s_lshl_b32 s10, s10, 7
	s_nop 0
	v_addc_co_u32_e32 v5, vcc, 0, v99, vcc
	v_add_co_u32_e32 v6, vcc, s21, v98
	s_ashr_i32 s11, s10, 31
	s_nop 0
	v_addc_co_u32_e32 v7, vcc, 0, v99, vcc
	s_lshl_b64 s[14:15], s[10:11], 11
	s_barrier
	s_add_u32 m0, s98, 0x1000
	v_lshl_add_u64 v[46:47], v[4:5], 0, v[238:239]
	global_load_lds_dwordx4 v[46:47], off
	s_add_u32 m0, s98, 0x2000
	v_lshl_add_u64 v[62:63], v[6:7], 0, v[238:239]
	global_load_lds_dwordx4 v[62:63], off
	v_add_co_u32_e32 v4, vcc, s22, v98
	s_waitcnt lgkmcnt(0)
	v_lshl_add_u64 v[2:3], v[116:117], 0, s[14:15]
	v_addc_co_u32_e32 v5, vcc, 0, v99, vcc
	v_add_co_u32_e32 v6, vcc, s20, v2
	s_mov_b32 m0, s98
	v_lshl_add_u64 v[50:51], v[98:99], 0, v[238:239]
	global_load_lds_dwordx4 v[50:51], off
	s_add_u32 m0, s98, 0x4000
	v_lshl_add_u64 v[82:83], v[2:3], 0, v[238:239]
	global_load_lds_dwordx4 v[82:83], off
	v_addc_co_u32_e32 v7, vcc, 0, v3, vcc
	s_add_u32 m0, s98, 0x3000
	v_lshl_add_u64 v[66:67], v[4:5], 0, v[238:239]
	global_load_lds_dwordx4 v[66:67], off
	s_add_u32 m0, s98, 0x5000
	v_lshl_add_u64 v[86:87], v[6:7], 0, v[238:239]
	global_load_lds_dwordx4 v[86:87], off
	v_add_co_u32_e32 v4, vcc, s21, v2
	v_mov_b32_e32 v78, 0
	v_addc_co_u32_e32 v5, vcc, 0, v3, vcc
	v_add_co_u32_e32 v2, vcc, s22, v2
	s_mov_b32 s11, 0
	s_nop 0
	v_addc_co_u32_e32 v3, vcc, 0, v3, vcc
	s_add_u32 m0, s98, 0x6000
	v_lshl_add_u64 v[90:91], v[4:5], 0, v[238:239]
	global_load_lds_dwordx4 v[90:91], off
	s_add_u32 m0, s98, 0x7000
	v_lshl_add_u64 v[94:95], v[2:3], 0, v[238:239]
	global_load_lds_dwordx4 v[94:95], off
	s_mov_b64 s[12:13], 0
	s_mov_b32 s9, 0
	v_mov_b32_e32 v79, v78
	v_mov_b32_e32 v80, v78
	v_mov_b32_e32 v81, v78
	v_mov_b32_e32 v74, v78
	v_mov_b32_e32 v75, v78
	v_mov_b32_e32 v76, v78
	v_mov_b32_e32 v77, v78
	v_mov_b32_e32 v70, v78
	v_mov_b32_e32 v71, v78
	v_mov_b32_e32 v72, v78
	v_mov_b32_e32 v73, v78
	v_mov_b32_e32 v58, v78
	v_mov_b32_e32 v59, v78
	v_mov_b32_e32 v60, v78
	v_mov_b32_e32 v61, v78
	v_mov_b32_e32 v54, v78
	v_mov_b32_e32 v55, v78
	v_mov_b32_e32 v56, v78
	v_mov_b32_e32 v57, v78
	v_mov_b32_e32 v42, v78
	v_mov_b32_e32 v43, v78
	v_mov_b32_e32 v44, v78
	v_mov_b32_e32 v45, v78
	v_mov_b32_e32 v38, v78
	v_mov_b32_e32 v39, v78
	v_mov_b32_e32 v40, v78
	v_mov_b32_e32 v41, v78
	v_lshl_add_u64 v[100:101], v[118:119], 0, s[14:15]
	v_mov_b32_e32 v34, v78
	v_mov_b32_e32 v35, v78
	v_mov_b32_e32 v36, v78
	v_mov_b32_e32 v37, v78
	v_mov_b32_e32 v30, v78
	v_mov_b32_e32 v31, v78
	v_mov_b32_e32 v32, v78
	v_mov_b32_e32 v33, v78
	v_mov_b32_e32 v26, v78
	v_mov_b32_e32 v27, v78
	v_mov_b32_e32 v28, v78
	v_mov_b32_e32 v29, v78
	v_mov_b32_e32 v22, v78
	v_mov_b32_e32 v23, v78
	v_mov_b32_e32 v24, v78
	v_mov_b32_e32 v25, v78
	v_mov_b32_e32 v18, v78
	v_mov_b32_e32 v19, v78
	v_mov_b32_e32 v20, v78
	v_mov_b32_e32 v21, v78
	v_mov_b32_e32 v14, v78
	v_mov_b32_e32 v15, v78
	v_mov_b32_e32 v16, v78
	v_mov_b32_e32 v17, v78
	v_mov_b32_e32 v10, v78
	v_mov_b32_e32 v11, v78
	v_mov_b32_e32 v12, v78
	v_mov_b32_e32 v13, v78
	v_mov_b32_e32 v6, v78
	v_mov_b32_e32 v7, v78
	v_mov_b32_e32 v8, v78
	v_mov_b32_e32 v9, v78
	v_mov_b32_e32 v2, v78
	v_mov_b32_e32 v3, v78
	v_mov_b32_e32 v4, v78
	v_mov_b32_e32 v5, v78
	s_waitcnt lgkmcnt(0)
	s_add_u32 m0, s98, 0x8000
	v_lshl_add_u64 v[50:51], v[50:51], 0, v[242:243]
	global_load_lds_dwordx4 v[50:51], off
	s_add_u32 m0, s98, 0x9000
	v_lshl_add_u64 v[46:47], v[46:47], 0, v[242:243]
	global_load_lds_dwordx4 v[46:47], off
	s_add_u32 m0, s98, 0xa000
	v_lshl_add_u64 v[62:63], v[62:63], 0, v[242:243]
	global_load_lds_dwordx4 v[62:63], off
	s_add_u32 m0, s98, 0xb000
	v_lshl_add_u64 v[66:67], v[66:67], 0, v[242:243]
	global_load_lds_dwordx4 v[66:67], off
	s_mov_b32 s100, 0
	s_mov_b32 s101, 0x4000
	s_waitcnt vmcnt(4)
	s_barrier
	s_branch .LBB0_1085

.LBB0_1087:
	v_add_u32_e32 v106, s100, v129
	v_add3_u32 v138, v106, v132, s101
	ds_read_b128 v[102:105], v138
	v_add_u32_e32 v142, v106, v131
	ds_read_b128 v[106:109], v138 offset:2048
	ds_read_b128 v[110:113], v142
	ds_read_b128 v[120:123], v142 offset:2048
	ds_read_b128 v[124:127], v138 offset:4096
	ds_read_b128 v[138:141], v138 offset:6144
	s_waitcnt lgkmcnt(3)
	v_mfma_f32_16x16x32_bf16 v[74:77], v[106:109], v[110:113], v[74:77]
	s_andn2_b64 vcc, exec, s[14:15]
	v_mfma_f32_16x16x32_bf16 v[78:81], v[102:105], v[110:113], v[78:81]
	s_waitcnt lgkmcnt(1)
	v_mfma_f32_16x16x32_bf16 v[70:73], v[124:127], v[110:113], v[70:73]
	s_cbranch_vccz .Ldq_14_0
	s_add_u32 s99, s100, 0xc000
	s_cmp_lt_u32 s99, 0x14000
	s_cbranch_scc1 .Ldqw_14_0
	s_sub_u32 s99, s99, 0x14000

.Ldq_14_0:
	s_waitcnt lgkmcnt(0)
	v_mfma_f32_16x16x32_bf16 v[58:61], v[138:141], v[110:113], v[58:61]
	v_mfma_f32_16x16x32_bf16 v[54:57], v[102:105], v[120:123], v[54:57]
	s_cbranch_vccz .Ldq_14_1
	s_add_u32 m0, s99, 0x1000
	v_lshl_add_u64 v[86:87], v[86:87], 0, v[242:243]
	global_load_lds_dwordx4 v[86:87], off

.Ldq_14_2:
	v_mfma_f32_16x16x32_bf16 v[34:37], v[138:141], v[120:123], v[34:37]
	ds_read_b128 v[110:113], v142 offset:4096
	ds_read_b128 v[120:123], v142 offset:6144
	s_waitcnt lgkmcnt(1)
	v_mfma_f32_16x16x32_bf16 v[26:29], v[106:109], v[110:113], v[26:29]
	s_cbranch_vccz .Ldq_14_3
	s_add_u32 m0, s99, 0x3000
	v_lshl_add_u64 v[94:95], v[94:95], 0, v[242:243]
	global_load_lds_dwordx4 v[94:95], off
.Ldq_14_3:
	s_waitcnt lgkmcnt(0)
	v_mfma_f32_16x16x32_bf16 v[10:13], v[106:109], v[120:123], v[10:13]
	v_add_u32_e32 v106, s100, v133
	v_add3_u32 v142, v106, v132, s101
	v_add_u32_e32 v143, v106, v131
	v_mfma_f32_16x16x32_bf16 v[30:33], v[102:105], v[110:113], v[30:33]
	s_cmp_gt_u32 s9, 13
	s_cbranch_scc1 .Ldq_14_4
	s_add_u32 s99, s100, 0x10000
	s_cmp_lt_u32 s99, 0x14000
	s_cbranch_scc1 .Ldqw_14_4
	s_sub_u32 s99, s99, 0x14000

.Ldq_14_4:
	s_mov_b64 s[16:17], -1
	v_mfma_f32_16x16x32_bf16 v[22:25], v[124:127], v[110:113], v[22:25]
	v_mfma_f32_16x16x32_bf16 v[18:21], v[138:141], v[110:113], v[18:21]
	s_cmp_gt_u32 s9, 13
	s_cbranch_scc1 .Ldq_14_5
	s_add_u32 m0, s99, 0x1000
	v_lshl_add_u64 v[46:47], v[46:47], 0, v[242:243]
	global_load_lds_dwordx4 v[46:47], off
.Ldq_14_5:
	v_mfma_f32_16x16x32_bf16 v[14:17], v[102:105], v[120:123], v[14:17]
	ds_read_b128 v[102:105], v142
	v_mfma_f32_16x16x32_bf16 v[6:9], v[124:127], v[120:123], v[6:9]
	s_cmp_gt_u32 s9, 13
	s_cbranch_scc1 .Ldq_14_6
	s_add_u32 m0, s99, 0x2000
	v_lshl_add_u64 v[62:63], v[62:63], 0, v[242:243]
	global_load_lds_dwordx4 v[62:63], off
.Ldq_14_6:
	v_mfma_f32_16x16x32_bf16 v[2:5], v[138:141], v[120:123], v[2:5]
	ds_read_b128 v[106:109], v142 offset:2048
	ds_read_b128 v[110:113], v143
	ds_read_b128 v[120:123], v143 offset:2048
	ds_read_b128 v[124:127], v142 offset:4096
	ds_read_b128 v[138:141], v142 offset:6144
	s_waitcnt lgkmcnt(3)
	v_mfma_f32_16x16x32_bf16 v[78:81], v[102:105], v[110:113], v[78:81]
	s_cmp_gt_u32 s9, 13
	s_cbranch_scc1 .Ldq_14_7
	s_add_u32 m0, s99, 0x3000
	v_lshl_add_u64 v[66:67], v[66:67], 0, v[242:243]
	global_load_lds_dwordx4 v[66:67], off
.Ldq_14_7:
	v_mfma_f32_16x16x32_bf16 v[74:77], v[106:109], v[110:113], v[74:77]
	s_waitcnt lgkmcnt(1)
	v_mfma_f32_16x16x32_bf16 v[70:73], v[124:127], v[110:113], v[70:73]
	s_waitcnt lgkmcnt(0)
	v_mfma_f32_16x16x32_bf16 v[58:61], v[138:141], v[110:113], v[58:61]
	v_mfma_f32_16x16x32_bf16 v[54:57], v[102:105], v[120:123], v[54:57]
	v_mfma_f32_16x16x32_bf16 v[42:45], v[106:109], v[120:123], v[42:45]
	v_mfma_f32_16x16x32_bf16 v[38:41], v[124:127], v[120:123], v[38:41]
	v_mfma_f32_16x16x32_bf16 v[34:37], v[138:141], v[120:123], v[34:37]
	ds_read_b128 v[110:113], v143 offset:4096
	ds_read_b128 v[120:123], v143 offset:6144
	s_waitcnt lgkmcnt(1)
	v_mfma_f32_16x16x32_bf16 v[30:33], v[102:105], v[110:113], v[30:33]
	v_mfma_f32_16x16x32_bf16 v[26:29], v[106:109], v[110:113], v[26:29]
	v_mfma_f32_16x16x32_bf16 v[22:25], v[124:127], v[110:113], v[22:25]
	v_mfma_f32_16x16x32_bf16 v[18:21], v[138:141], v[110:113], v[18:21]
	s_waitcnt lgkmcnt(0)
	v_mfma_f32_16x16x32_bf16 v[14:17], v[102:105], v[120:123], v[14:17]
	v_mfma_f32_16x16x32_bf16 v[10:13], v[106:109], v[120:123], v[10:13]
	v_mfma_f32_16x16x32_bf16 v[6:9], v[124:127], v[120:123], v[6:9]
	v_mfma_f32_16x16x32_bf16 v[2:5], v[138:141], v[120:123], v[2:5]
	s_cbranch_vccnz .LBB0_1089
	s_add_i32 s14, s11, 0x8000
	s_mov_b64 s[16:17], 0
